# E25: bf16 GEMM epilogue stores widened to 16 bytes via v_permlane16_swap (MLP-up, MLA-up, G1-odd) on top of E22
# speedup vs baseline: 1.0161x; 1.0117x over previous
; #define PG8_STAGE(bufoff, gbase, voff) do { _Pragma("unroll") for (int _i = 0; _i < 2; ++_i) \
;     __builtin_amdgcn_global_load_lds((const unsigned*)((const char*)(gbase) + (voff)[_i]), (LAS unsigned*)(lds + (bufoff) + ldsw + _i * 8192), 16, 0, 0); } while (0)
; #define PG8_LDA(dst, b, h) do { _Pragma("unroll") for (int m = 0; m < 4; ++m) _Pragma("unroll") for (int k = 0; k < 2; ++k) dst[m][k] = *(const LAS bf16x8*)(lds + PG8_SA(b, h) + aoff + m * 2048 + k * 1024); } while (0)
; #define PG8_LDB(dst, b, h) do { _Pragma("unroll") for (int n = 0; n < 2; ++n) _Pragma("unroll") for (int k = 0; k < 2; ++k) dst[n][k] = *(const LAS bf16x8*)(lds + PG8_SB(b, h) + boff + n * 2048 + k * 1024); } while (0)
; #define PG8_MMA(ai, bj, At, Bt) do { __builtin_amdgcn_s_setprio(1); _Pragma("unroll") for (int m = 0; m < 4; ++m) _Pragma("unroll") for (int n = 0; n < 2; ++n) _Pragma("unroll") for (int k = 0; k < 2; ++k) \
;     acc[ai][bj][m][n] = __builtin_amdgcn_mfma_f32_16x16x32_bf16(Bt[n][k], At[m][k], acc[ai][bj][m][n], 0, 0, 0); __builtin_amdgcn_s_setprio(0); } while (0)
; #define PG8_WAIT_V(n) asm volatile("s_waitcnt vmcnt(" #n ")" ::: "memory")
; #define PG8_WAIT_L(n) asm volatile("s_waitcnt lgkmcnt(" #n ")" ::: "memory")
; #define PG8_BAR __builtin_amdgcn_s_barrier()
; #define PG8_SCHED __builtin_amdgcn_sched_barrier(0)
; template <class Epi, class Sched>
; __device__ __forceinline__ void gemm_phase(LAS unsigned char* lds, const Gemm g, const Sched& S, const Epi& E) {
;     ...
;       PG8_LDB(B0, 0, 0); PG8_SCHED; PG8_LDA(At, 0, 0); PG8_STAGE(PG8_SA(1, 1), a1 + hstepA, voffA);
;       PG8_WAIT_L(8); PG8_BAR; PG8_WAIT_L(0); PG8_MMA(0, 0, At, B0); PG8_BAR; PG8_SCHED;
;       PG8_LDB(B1, 0, 1); PG8_STAGE(PG8_SB(0, 0), b2, voffB);
;       PG8_BAR; PG8_WAIT_L(0); PG8_MMA(0, 1, At, B1); PG8_BAR;
;       PG8_LDA(At, 0, 1); PG8_STAGE(PG8_SA(0, 0), a2, voffA);
;       PG8_BAR; PG8_WAIT_L(0); PG8_MMA(1, 0, At, B0); PG8_BAR; PG8_SCHED;
;       PG8_STAGE(PG8_SB(0, 1), b2 + hstepB, voffB);
;       PG8_WAIT_V(6); PG8_BAR; PG8_MMA(1, 1, At, B1); PG8_BAR;
.LBB0_621:
	s_add_u32 s4, s10, 0xfffc0080
	s_addc_u32 s5, s11, -1
	s_add_i32 s76, 16, 0x10000
	v_add_u32_e32 v136, s76, v160
	ds_read_b128 v[128:131], v136
	ds_read_b128 v[132:135], v136 offset:1024
	ds_read_b128 v[152:155], v136 offset:2048
	ds_read_b128 v[156:159], v136 offset:3072
	s_cmp_eq_u32 s84, 12
	s_cselect_b32 s79, s18, s5
	s_cselect_b32 s78, s19, s4
	s_cselect_b32 s13, s17, s23
	s_cselect_b32 s12, s20, s21
	v_lshl_add_u64 v[136:137], s[10:11], 0, v[148:149]
	s_add_i32 m0, s39, 0xc000
	ds_read_b128 v[166:169], v164
	ds_read_b128 v[170:173], v164 offset:1024
	ds_read_b128 v[174:177], v164 offset:2048
	ds_read_b128 v[178:181], v164 offset:3072
	ds_read_b128 v[182:185], v164 offset:4096
	ds_read_b128 v[198:201], v164 offset:5120
	ds_read_b128 v[214:217], v164 offset:6144
	ds_read_b128 v[218:221], v164 offset:7168
	global_load_lds_dwordx4 v[136:137], off
	v_lshl_add_u64 v[136:137], s[10:11], 0, v[150:151]
	s_add_i32 m0, s39, 0xe000
	s_nop 0
	global_load_lds_dwordx4 v[136:137], off
	s_waitcnt lgkmcnt(8)
	s_barrier
	s_waitcnt lgkmcnt(0)
	s_setprio 1
	s_waitcnt lgkmcnt(0)
	v_mfma_f32_16x16x32_bf16 v[124:127], v[128:131], v[166:169], v[124:127]
	v_mfma_f32_16x16x32_bf16 v[120:123], v[152:155], v[166:169], v[120:123]
	v_mfma_f32_16x16x32_bf16 v[108:111], v[128:131], v[174:177], v[108:111]
	v_mfma_f32_16x16x32_bf16 v[104:107], v[152:155], v[174:177], v[104:107]
	v_mfma_f32_16x16x32_bf16 v[92:95], v[128:131], v[182:185], v[92:95]
	v_mfma_f32_16x16x32_bf16 v[88:91], v[152:155], v[182:185], v[88:91]
	v_mfma_f32_16x16x32_bf16 v[76:79], v[128:131], v[214:217], v[76:79]
	v_mfma_f32_16x16x32_bf16 v[72:75], v[152:155], v[214:217], v[72:75]
	v_mfma_f32_16x16x32_bf16 v[124:127], v[132:135], v[170:173], v[124:127]
	v_mfma_f32_16x16x32_bf16 v[120:123], v[156:159], v[170:173], v[120:123]
	v_mfma_f32_16x16x32_bf16 v[108:111], v[132:135], v[178:181], v[108:111]
	v_mfma_f32_16x16x32_bf16 v[104:107], v[156:159], v[178:181], v[104:107]
	v_mfma_f32_16x16x32_bf16 v[92:95], v[132:135], v[198:201], v[92:95]
	v_mfma_f32_16x16x32_bf16 v[88:91], v[156:159], v[198:201], v[88:91]
	v_mfma_f32_16x16x32_bf16 v[76:79], v[132:135], v[218:221], v[76:79]
	v_mfma_f32_16x16x32_bf16 v[72:75], v[156:159], v[218:221], v[72:75]
	s_setprio 0
	s_barrier
	s_add_i32 s77, 16, 0x14000
	v_add_u32_e32 v136, s77, v160
	s_add_i32 s4, s76, s58
	ds_read_b128 v[222:225], v136
	ds_read_b128 v[226:229], v136 offset:1024
	ds_read_b128 v[230:233], v136 offset:2048
	ds_read_b128 v[234:237], v136 offset:3072
	v_lshl_add_u64 v[136:137], s[12:13], 0, v[138:139]
	s_mov_b32 m0, s4
	v_lshl_add_u64 v[238:239], s[12:13], 0, v[140:141]
	global_load_lds_dwordx4 v[136:137], off
	s_add_i32 m0, s4, 0x2000
	s_nop 0
	global_load_lds_dwordx4 v[238:239], off
	s_barrier
	s_waitcnt lgkmcnt(0)
	s_setprio 1
	s_waitcnt lgkmcnt(0)
	v_mfma_f32_16x16x32_bf16 v[116:119], v[222:225], v[166:169], v[116:119]
	v_mfma_f32_16x16x32_bf16 v[112:115], v[230:233], v[166:169], v[112:115]
	v_mfma_f32_16x16x32_bf16 v[100:103], v[222:225], v[174:177], v[100:103]
	v_mfma_f32_16x16x32_bf16 v[96:99], v[230:233], v[174:177], v[96:99]
	v_mfma_f32_16x16x32_bf16 v[84:87], v[222:225], v[182:185], v[84:87]
	v_mfma_f32_16x16x32_bf16 v[80:83], v[230:233], v[182:185], v[80:83]
	v_mfma_f32_16x16x32_bf16 v[68:71], v[222:225], v[214:217], v[68:71]
	v_mfma_f32_16x16x32_bf16 v[64:67], v[230:233], v[214:217], v[64:67]
	v_mfma_f32_16x16x32_bf16 v[116:119], v[226:229], v[170:173], v[116:119]
	v_mfma_f32_16x16x32_bf16 v[112:115], v[234:237], v[170:173], v[112:115]
	v_mfma_f32_16x16x32_bf16 v[100:103], v[226:229], v[178:181], v[100:103]
	v_mfma_f32_16x16x32_bf16 v[96:99], v[234:237], v[178:181], v[96:99]
	v_mfma_f32_16x16x32_bf16 v[84:87], v[226:229], v[198:201], v[84:87]
	v_mfma_f32_16x16x32_bf16 v[80:83], v[234:237], v[198:201], v[80:83]
	v_mfma_f32_16x16x32_bf16 v[68:71], v[226:229], v[218:221], v[68:71]
	v_mfma_f32_16x16x32_bf16 v[64:67], v[234:237], v[218:221], v[64:67]
	s_setprio 0
	s_mov_b32 m0, s39
	v_lshl_add_u64 v[240:241], s[78:79], 0, v[138:139]
	s_barrier
	ds_read_b128 v[166:169], v164 offset:16384
	ds_read_b128 v[170:173], v164 offset:17408
	ds_read_b128 v[174:177], v164 offset:18432
	ds_read_b128 v[178:181], v164 offset:19456
	ds_read_b128 v[182:185], v164 offset:20480
	ds_read_b128 v[198:201], v164 offset:21504
	ds_read_b128 v[214:217], v164 offset:22528
	ds_read_b128 v[218:221], v164 offset:23552
	global_load_lds_dwordx4 v[240:241], off
	v_lshl_add_u64 v[242:243], s[78:79], 0, v[140:141]
	s_mov_b32 m0, s59
	s_nop 0
	global_load_lds_dwordx4 v[242:243], off
	s_barrier
	s_waitcnt lgkmcnt(0)
	s_setprio 1
	s_waitcnt lgkmcnt(0)
	v_mfma_f32_16x16x32_bf16 v[60:63], v[128:131], v[166:169], v[60:63]
	v_mfma_f32_16x16x32_bf16 v[56:59], v[152:155], v[166:169], v[56:59]
	v_mfma_f32_16x16x32_bf16 v[44:47], v[128:131], v[174:177], v[44:47]
	v_mfma_f32_16x16x32_bf16 v[40:43], v[152:155], v[174:177], v[40:43]
	v_mfma_f32_16x16x32_bf16 v[28:31], v[128:131], v[182:185], v[28:31]
	v_mfma_f32_16x16x32_bf16 v[24:27], v[152:155], v[182:185], v[24:27]
	v_mfma_f32_16x16x32_bf16 v[12:15], v[128:131], v[214:217], v[12:15]
	v_mfma_f32_16x16x32_bf16 v[8:11], v[152:155], v[214:217], v[8:11]
	v_mfma_f32_16x16x32_bf16 v[60:63], v[132:135], v[170:173], v[60:63]
	v_mfma_f32_16x16x32_bf16 v[56:59], v[156:159], v[170:173], v[56:59]
	v_mfma_f32_16x16x32_bf16 v[44:47], v[132:135], v[178:181], v[44:47]
	v_mfma_f32_16x16x32_bf16 v[40:43], v[156:159], v[178:181], v[40:43]
	v_mfma_f32_16x16x32_bf16 v[28:31], v[132:135], v[198:201], v[28:31]
	v_mfma_f32_16x16x32_bf16 v[24:27], v[156:159], v[198:201], v[24:27]
	v_mfma_f32_16x16x32_bf16 v[12:15], v[132:135], v[218:221], v[12:15]
	v_mfma_f32_16x16x32_bf16 v[8:11], v[156:159], v[218:221], v[8:11]
	s_setprio 0
	s_barrier
; #define PG8_STAGE(bufoff, gbase, voff) do { _Pragma("unroll") for (int _i = 0; _i < 2; ++_i) \
;     __builtin_amdgcn_global_load_lds((const unsigned*)((const char*)(gbase) + (voff)[_i]), (LAS unsigned*)(lds + (bufoff) + ldsw + _i * 8192), 16, 0, 0); } while (0)
; #define PG8_LDA(dst, b, h) do { _Pragma("unroll") for (int m = 0; m < 4; ++m) _Pragma("unroll") for (int k = 0; k < 2; ++k) dst[m][k] = *(const LAS bf16x8*)(lds + PG8_SA(b, h) + aoff + m * 2048 + k * 1024); } while (0)
; #define PG8_LDB(dst, b, h) do { _Pragma("unroll") for (int n = 0; n < 2; ++n) _Pragma("unroll") for (int k = 0; k < 2; ++k) dst[n][k] = *(const LAS bf16x8*)(lds + PG8_SB(b, h) + boff + n * 2048 + k * 1024); } while (0)
; #define PG8_MMA(ai, bj, At, Bt) do { __builtin_amdgcn_s_setprio(1); _Pragma("unroll") for (int m = 0; m < 4; ++m) _Pragma("unroll") for (int n = 0; n < 2; ++n) _Pragma("unroll") for (int k = 0; k < 2; ++k) \
;     acc[ai][bj][m][n] = __builtin_amdgcn_mfma_f32_16x16x32_bf16(Bt[n][k], At[m][k], acc[ai][bj][m][n], 0, 0, 0); __builtin_amdgcn_s_setprio(0); } while (0)
; #define PG8_WAIT_V(n) asm volatile("s_waitcnt vmcnt(" #n ")" ::: "memory")
; #define PG8_WAIT_L(n) asm volatile("s_waitcnt lgkmcnt(" #n ")" ::: "memory")
; #define PG8_BAR __builtin_amdgcn_s_barrier()
; #define PG8_SCHED __builtin_amdgcn_sched_barrier(0)
; template <class Epi, class Sched>
; __device__ __forceinline__ void gemm_phase(LAS unsigned char* lds, const Gemm g, const Sched& S, const Epi& E) {
;     ...
;       PG8_STAGE(PG8_SB(0, 1), b2 + hstepB, voffB);
;       PG8_WAIT_V(6); PG8_BAR; PG8_MMA(1, 1, At, B1); PG8_BAR;
;       PG8_LDB(B0, 1, 0); PG8_SCHED; PG8_LDA(At, 1, 0); PG8_STAGE(PG8_SA(0, 1), a2 + hstepA, voffA);
;       PG8_WAIT_L(8); PG8_BAR; PG8_WAIT_L(0); PG8_MMA(0, 0, At, B0); PG8_BAR; PG8_SCHED;
;       PG8_LDB(B1, 1, 1); PG8_STAGE(PG8_SB(1, 0), b3, voffB);
;       PG8_BAR; PG8_WAIT_L(0); PG8_MMA(0, 1, At, B1); PG8_BAR;
;       PG8_LDA(At, 1, 1); PG8_STAGE(PG8_SA(1, 0), a3, voffA);
;       PG8_BAR; PG8_WAIT_L(0); PG8_MMA(1, 0, At, B0); PG8_BAR; PG8_SCHED;
	s_add_u32 s4, s12, 0x40000
	s_addc_u32 s5, s13, 0
	s_add_i32 s76, s77, s58
	v_lshl_add_u64 v[128:129], s[4:5], 0, v[138:139]
	s_mov_b32 m0, s76
	s_nop 0
	global_load_lds_dwordx4 v[128:129], off
	v_lshl_add_u64 v[128:129], s[4:5], 0, v[140:141]
	s_add_i32 m0, s76, 0x2000
	s_nop 0
	global_load_lds_dwordx4 v[128:129], off
	s_waitcnt vmcnt(6)
	s_barrier
	s_setprio 1
	v_mfma_f32_16x16x32_bf16 v[52:55], v[222:225], v[166:169], v[52:55]
	v_mfma_f32_16x16x32_bf16 v[48:51], v[230:233], v[166:169], v[48:51]
	v_mfma_f32_16x16x32_bf16 v[36:39], v[222:225], v[174:177], v[36:39]
	v_mfma_f32_16x16x32_bf16 v[32:35], v[230:233], v[174:177], v[32:35]
	v_mfma_f32_16x16x32_bf16 v[20:23], v[222:225], v[182:185], v[20:23]
	v_mfma_f32_16x16x32_bf16 v[16:19], v[230:233], v[182:185], v[16:19]
	v_mfma_f32_16x16x32_bf16 v[4:7], v[222:225], v[214:217], v[4:7]
	v_mfma_f32_16x16x32_bf16 v[0:3], v[230:233], v[214:217], v[0:3]
	v_mfma_f32_16x16x32_bf16 v[52:55], v[226:229], v[170:173], v[52:55]
	v_mfma_f32_16x16x32_bf16 v[48:51], v[234:237], v[170:173], v[48:51]
	v_mfma_f32_16x16x32_bf16 v[36:39], v[226:229], v[178:181], v[36:39]
	v_mfma_f32_16x16x32_bf16 v[32:35], v[234:237], v[178:181], v[32:35]
	v_mfma_f32_16x16x32_bf16 v[20:23], v[226:229], v[198:201], v[20:23]
	v_mfma_f32_16x16x32_bf16 v[16:19], v[234:237], v[198:201], v[16:19]
	v_mfma_f32_16x16x32_bf16 v[4:7], v[226:229], v[218:221], v[4:7]
	v_mfma_f32_16x16x32_bf16 v[0:3], v[234:237], v[218:221], v[0:3]
	s_setprio 0
	s_add_i32 s76, 16, 0x18000
	v_add_u32_e32 v156, s76, v160
	s_barrier
	ds_read_b128 v[128:131], v156
	ds_read_b128 v[132:135], v156 offset:1024
	ds_read_b128 v[152:155], v156 offset:2048
	ds_read_b128 v[156:159], v156 offset:3072
	s_add_u32 s4, s78, 0x40000
	s_addc_u32 s5, s79, 0
	s_mov_b32 m0, s67
	v_lshl_add_u64 v[222:223], s[4:5], 0, v[138:139]
	ds_read_b128 v[166:169], v164 offset:32768
	ds_read_b128 v[170:173], v164 offset:33792
	ds_read_b128 v[174:177], v164 offset:34816
	ds_read_b128 v[178:181], v164 offset:35840
	ds_read_b128 v[182:185], v164 offset:36864
	ds_read_b128 v[198:201], v164 offset:37888
	ds_read_b128 v[214:217], v164 offset:38912
	ds_read_b128 v[218:221], v164 offset:39936
	global_load_lds_dwordx4 v[222:223], off
	v_lshl_add_u64 v[222:223], s[4:5], 0, v[140:141]
	s_mov_b32 m0, s68
	s_nop 0
	global_load_lds_dwordx4 v[222:223], off
	s_waitcnt lgkmcnt(8)
	s_barrier
	s_waitcnt lgkmcnt(0)
	s_setprio 1
	s_waitcnt lgkmcnt(0)
	v_mfma_f32_16x16x32_bf16 v[124:127], v[128:131], v[166:169], v[124:127]
	v_mfma_f32_16x16x32_bf16 v[120:123], v[152:155], v[166:169], v[120:123]
	v_mfma_f32_16x16x32_bf16 v[108:111], v[128:131], v[174:177], v[108:111]
	v_mfma_f32_16x16x32_bf16 v[104:107], v[152:155], v[174:177], v[104:107]
	v_mfma_f32_16x16x32_bf16 v[92:95], v[128:131], v[182:185], v[92:95]
	v_mfma_f32_16x16x32_bf16 v[88:91], v[152:155], v[182:185], v[88:91]
	v_mfma_f32_16x16x32_bf16 v[76:79], v[128:131], v[214:217], v[76:79]
	v_mfma_f32_16x16x32_bf16 v[72:75], v[152:155], v[214:217], v[72:75]
	v_mfma_f32_16x16x32_bf16 v[124:127], v[132:135], v[170:173], v[124:127]
	v_mfma_f32_16x16x32_bf16 v[120:123], v[156:159], v[170:173], v[120:123]
	v_mfma_f32_16x16x32_bf16 v[108:111], v[132:135], v[178:181], v[108:111]
	v_mfma_f32_16x16x32_bf16 v[104:107], v[156:159], v[178:181], v[104:107]
	v_mfma_f32_16x16x32_bf16 v[92:95], v[132:135], v[198:201], v[92:95]
	v_mfma_f32_16x16x32_bf16 v[88:91], v[156:159], v[198:201], v[88:91]
	v_mfma_f32_16x16x32_bf16 v[76:79], v[132:135], v[218:221], v[76:79]
	v_mfma_f32_16x16x32_bf16 v[72:75], v[156:159], v[218:221], v[72:75]
	s_setprio 0
	s_barrier
	s_add_i32 s77, 16, 0x1c000
	s_add_i32 s4, s76, s58
	v_add_u32_e32 v165, s77, v160
	v_lshl_add_u64 v[136:137], v[136:137], 0, s[62:63]
	s_mov_b32 m0, s4
	ds_read_b128 v[222:225], v165
	ds_read_b128 v[226:229], v165 offset:1024
	ds_read_b128 v[230:233], v165 offset:2048
	ds_read_b128 v[234:237], v165 offset:3072
	global_load_lds_dwordx4 v[136:137], off
	v_lshl_add_u64 v[136:137], v[238:239], 0, s[62:63]
	s_add_i32 m0, s4, 0x2000
	s_nop 0
	global_load_lds_dwordx4 v[136:137], off
	s_barrier
	s_waitcnt lgkmcnt(0)
	s_setprio 1
	s_waitcnt lgkmcnt(0)
	v_mfma_f32_16x16x32_bf16 v[116:119], v[222:225], v[166:169], v[116:119]
	v_mfma_f32_16x16x32_bf16 v[112:115], v[230:233], v[166:169], v[112:115]
	v_mfma_f32_16x16x32_bf16 v[100:103], v[222:225], v[174:177], v[100:103]
	v_mfma_f32_16x16x32_bf16 v[96:99], v[230:233], v[174:177], v[96:99]
	v_mfma_f32_16x16x32_bf16 v[84:87], v[222:225], v[182:185], v[84:87]
	v_mfma_f32_16x16x32_bf16 v[80:83], v[230:233], v[182:185], v[80:83]
	v_mfma_f32_16x16x32_bf16 v[68:71], v[222:225], v[214:217], v[68:71]
	v_mfma_f32_16x16x32_bf16 v[64:67], v[230:233], v[214:217], v[64:67]
	v_mfma_f32_16x16x32_bf16 v[116:119], v[226:229], v[170:173], v[116:119]
	v_mfma_f32_16x16x32_bf16 v[112:115], v[234:237], v[170:173], v[112:115]
	v_mfma_f32_16x16x32_bf16 v[100:103], v[226:229], v[178:181], v[100:103]
	v_mfma_f32_16x16x32_bf16 v[96:99], v[234:237], v[178:181], v[96:99]
	v_mfma_f32_16x16x32_bf16 v[84:87], v[226:229], v[198:201], v[84:87]
	v_mfma_f32_16x16x32_bf16 v[80:83], v[234:237], v[198:201], v[80:83]
	v_mfma_f32_16x16x32_bf16 v[68:71], v[226:229], v[218:221], v[68:71]
	v_mfma_f32_16x16x32_bf16 v[64:67], v[234:237], v[218:221], v[64:67]
	s_setprio 0
	s_mov_b32 m0, s74
	v_lshl_add_u64 v[136:137], v[240:241], 0, s[62:63]
	s_barrier
; __device__ __forceinline__ float siluf_(float v) { return v * sigmoidf_(v); }
; __device__ __forceinline__ void store_bf16x4(bf16_t* p, f32x4 v) { u32x2 w; w.x = cvt_pk_bf16(v[0], v[1]); w.y = cvt_pk_bf16(v[2], v[3]); *(u32x2*)p = w; }
; #define PG8_STAGE(bufoff, gbase, voff) do { _Pragma("unroll") for (int _i = 0; _i < 2; ++_i) \
;     __builtin_amdgcn_global_load_lds((const unsigned*)((const char*)(gbase) + (voff)[_i]), (LAS unsigned*)(lds + (bufoff) + ldsw + _i * 8192), 16, 0, 0); } while (0)
; #define PG8_LDA(dst, b, h) do { _Pragma("unroll") for (int m = 0; m < 4; ++m) _Pragma("unroll") for (int k = 0; k < 2; ++k) dst[m][k] = *(const LAS bf16x8*)(lds + PG8_SA(b, h) + aoff + m * 2048 + k * 1024); } while (0)
; #define PG8_MMA(ai, bj, At, Bt) do { __builtin_amdgcn_s_setprio(1); _Pragma("unroll") for (int m = 0; m < 4; ++m) _Pragma("unroll") for (int n = 0; n < 2; ++n) _Pragma("unroll") for (int k = 0; k < 2; ++k) \
;     acc[ai][bj][m][n] = __builtin_amdgcn_mfma_f32_16x16x32_bf16(Bt[n][k], At[m][k], acc[ai][bj][m][n], 0, 0, 0); __builtin_amdgcn_s_setprio(0); } while (0)
; #define PG8_WAIT_V(n) asm volatile("s_waitcnt vmcnt(" #n ")" ::: "memory")
; #define PG8_WAIT_L(n) asm volatile("s_waitcnt lgkmcnt(" #n ")" ::: "memory")
; #define PG8_BAR __builtin_amdgcn_s_barrier()
; #define PG8_SCHED __builtin_amdgcn_sched_barrier(0)
; template <class Epi, class Sched>
; __device__ __forceinline__ void gemm_phase(LAS unsigned char* lds, const Gemm g, const Sched& S, const Epi& E) {
;     ...
;       PG8_LDA(At, 1, 1); PG8_STAGE(PG8_SA(1, 0), a3, voffA);
;       PG8_BAR; PG8_WAIT_L(0); PG8_MMA(1, 0, At, B0); PG8_BAR; PG8_SCHED;
;       PG8_STAGE(PG8_SB(1, 1), b3 + hstepB, voffB);
;       PG8_WAIT_V(6); PG8_BAR; PG8_MMA(1, 1, At, B1); PG8_BAR;
;   __device__ __forceinline__ void operator()(const f32x4 (&acc)[2][2][4][2], const pg8::Unit& u, int wr, int wc, int fr, int fq) const {
;     ...
;     EPI_LOOP(
;       if (pn < 4) { store_bf16x4(DQK + (size_t)row * 1024 + col, v); }
;       else if (pn < 6) { store_bf16x4(DV + (size_t)row * 512 + (col - 1024), v); }
;       else if (pn < 10) { store_bf16x4(RV + (size_t)row * 512 + (col - 2048), v); }
;       else { f32x4 o; for (int j = 0; j < 4; ++j) o[j] = siluf_(v[j]); store_bf16x4(RG + (size_t)row * 512 + (col - 2560), o); }
	ds_read_b128 v[166:169], v164 offset:49152
	ds_read_b128 v[170:173], v164 offset:50176
	ds_read_b128 v[174:177], v164 offset:51200
	ds_read_b128 v[178:181], v164 offset:52224
	ds_read_b128 v[182:185], v164 offset:53248
	ds_read_b128 v[198:201], v164 offset:54272
	ds_read_b128 v[214:217], v164 offset:55296
	ds_read_b128 v[218:221], v164 offset:56320
	global_load_lds_dwordx4 v[136:137], off
	v_lshl_add_u64 v[136:137], v[242:243], 0, s[62:63]
	s_mov_b32 m0, s75
	s_nop 0
	global_load_lds_dwordx4 v[136:137], off
	s_barrier
	s_waitcnt lgkmcnt(0)
	s_setprio 1
	s_waitcnt lgkmcnt(0)
	v_mfma_f32_16x16x32_bf16 v[60:63], v[128:131], v[166:169], v[60:63]
	v_mfma_f32_16x16x32_bf16 v[56:59], v[152:155], v[166:169], v[56:59]
	v_mfma_f32_16x16x32_bf16 v[44:47], v[128:131], v[174:177], v[44:47]
	v_mfma_f32_16x16x32_bf16 v[40:43], v[152:155], v[174:177], v[40:43]
	v_mfma_f32_16x16x32_bf16 v[28:31], v[128:131], v[182:185], v[28:31]
	v_mfma_f32_16x16x32_bf16 v[24:27], v[152:155], v[182:185], v[24:27]
	v_mfma_f32_16x16x32_bf16 v[12:15], v[128:131], v[214:217], v[12:15]
	v_mfma_f32_16x16x32_bf16 v[8:11], v[152:155], v[214:217], v[8:11]
	v_mfma_f32_16x16x32_bf16 v[60:63], v[132:135], v[170:173], v[60:63]
	v_mfma_f32_16x16x32_bf16 v[56:59], v[156:159], v[170:173], v[56:59]
	v_mfma_f32_16x16x32_bf16 v[44:47], v[132:135], v[178:181], v[44:47]
	v_mfma_f32_16x16x32_bf16 v[40:43], v[156:159], v[178:181], v[40:43]
	v_mfma_f32_16x16x32_bf16 v[28:31], v[132:135], v[198:201], v[28:31]
	v_mfma_f32_16x16x32_bf16 v[24:27], v[156:159], v[198:201], v[24:27]
	v_mfma_f32_16x16x32_bf16 v[12:15], v[132:135], v[218:221], v[12:15]
	v_mfma_f32_16x16x32_bf16 v[8:11], v[156:159], v[218:221], v[8:11]
	s_setprio 0
	s_barrier
	s_add_u32 s4, s12, 0x40080
	s_addc_u32 s5, s13, 0
	s_add_i32 s12, s77, s58
	v_lshl_add_u64 v[128:129], s[4:5], 0, v[138:139]
	s_mov_b32 m0, s12
	s_nop 0
	global_load_lds_dwordx4 v[128:129], off
	v_lshl_add_u64 v[128:129], s[4:5], 0, v[140:141]
	s_add_i32 m0, s12, 0x2000
	s_nop 0
	global_load_lds_dwordx4 v[128:129], off
	s_waitcnt vmcnt(6)
	s_barrier
	s_setprio 1
	v_mfma_f32_16x16x32_bf16 v[52:55], v[222:225], v[166:169], v[52:55]
	v_mfma_f32_16x16x32_bf16 v[48:51], v[230:233], v[166:169], v[48:51]
	v_mfma_f32_16x16x32_bf16 v[36:39], v[222:225], v[174:177], v[36:39]
	v_mfma_f32_16x16x32_bf16 v[32:35], v[230:233], v[174:177], v[32:35]
	v_mfma_f32_16x16x32_bf16 v[20:23], v[222:225], v[182:185], v[20:23]
	v_mfma_f32_16x16x32_bf16 v[16:19], v[230:233], v[182:185], v[16:19]
	v_mfma_f32_16x16x32_bf16 v[4:7], v[222:225], v[214:217], v[4:7]
	v_mfma_f32_16x16x32_bf16 v[0:3], v[230:233], v[214:217], v[0:3]
	v_mfma_f32_16x16x32_bf16 v[52:55], v[226:229], v[170:173], v[52:55]
	v_mfma_f32_16x16x32_bf16 v[48:51], v[234:237], v[170:173], v[48:51]
	v_mfma_f32_16x16x32_bf16 v[36:39], v[226:229], v[178:181], v[36:39]
	v_mfma_f32_16x16x32_bf16 v[32:35], v[234:237], v[178:181], v[32:35]
	v_mfma_f32_16x16x32_bf16 v[20:23], v[226:229], v[198:201], v[20:23]
	v_mfma_f32_16x16x32_bf16 v[16:19], v[234:237], v[198:201], v[16:19]
	v_mfma_f32_16x16x32_bf16 v[4:7], v[226:229], v[218:221], v[4:7]
	v_mfma_f32_16x16x32_bf16 v[0:3], v[234:237], v[218:221], v[0:3]
	s_setprio 0
	s_add_i32 s84, s84, 2
	s_add_u32 s10, s10, 0x100
	s_addc_u32 s11, s11, 0
	s_add_u32 s21, s21, 0x100
	s_addc_u32 s23, s23, 0
	s_cmp_gt_u32 s84, 13
	s_barrier
	s_cbranch_scc0 .LBB0_621
	s_and_b32 s4, s38, -2
	s_cmp_lg_u32 s4, 6
	s_mov_b64 s[10:11], -1
	s_cbranch_scc0 .LBB0_1008
	s_cmp_gt_i32 s38, 3
	v_lshl_add_u32 v130, s66, 8, v145
	s_cselect_b64 s[10:11], -1, 0
	s_cmp_gt_u32 s38, 5
	s_cselect_b64 s[84:85], -1, 0
	s_cmp_gt_u32 s38, 9
	v_ashrrev_i32_e32 v131, 31, v130
	v_lshl_or_b32 v128, s38, 8, v142
	v_and_b32_e32 v252, 16, v187
	v_lshrrev_b32_e32 v253, 1, v252
	v_add_u32_e32 v252, v252, v253
	v_mov_b32_e32 v253, v144
	s_cselect_b64 s[78:79], -1, 0
	v_lshlrev_b64 v[132:133], 10, v[130:131]
	s_mov_b64 s[12:13], -1
	s_and_b64 vcc, exec, s[10:11]
	s_cbranch_vccz .LBB0_633
	s_and_b64 vcc, exec, s[84:85]
	s_cbranch_vccz .LBB0_630
	s_andn2_b64 vcc, exec, s[78:79]
	s_cbranch_vccnz .LBB0_627
	v_mul_f32_e32 v129, 0xbfb8aa3b, v124
	v_mul_f32_e32 v134, 0xbfb8aa3b, v125
	v_mul_f32_e32 v135, 0xbfb8aa3b, v126
	v_exp_f32_e32 v129, v129
	v_exp_f32_e32 v134, v134
	v_exp_f32_e32 v135, v135
	v_mul_f32_e32 v136, 0xbfb8aa3b, v127
	v_add_f32_e32 v129, 1.0, v129
	v_add_f32_e32 v134, 1.0, v134
	v_exp_f32_e32 v136, v136
	v_add_f32_e32 v135, 1.0, v135
	v_rcp_f32_e32 v129, v129
	v_rcp_f32_e32 v134, v134
	v_rcp_f32_e32 v135, v135
	v_add_f32_e32 v136, 1.0, v136
	v_rcp_f32_e32 v136, v136
	v_mul_f32_e32 v137, v124, v129
	v_mul_f32_e32 v152, v125, v134
	v_mul_f32_e32 v153, v126, v135
	v_lshl_add_u64 v[134:135], s[46:47], 0, v[132:133]
	v_mov_b32_e32 v129, v144
	v_lshl_add_u64 v[134:135], v[128:129], 1, v[134:135]
	v_add_co_u32_e32 v134, vcc, 0xfffff000, v134
	s_mov_b64 s[12:13], 0
	s_nop 0
	v_addc_co_u32_e32 v135, vcc, -1, v135, vcc
	v_mul_f32_e32 v154, v127, v136
	v_cvt_pk_bf16_f32 v244, v137, v152
	v_cvt_pk_bf16_f32 v245, v153, v154
.LBB0_627:
	s_andn2_b64 vcc, exec, s[12:13]
	s_cbranch_vccnz .LBB0_629
	v_lshl_add_u64 v[134:135], s[48:49], 0, v[132:133]
	v_mov_b32_e32 v129, v144
	v_lshl_add_u64 v[134:135], v[128:129], 1, v[134:135]
	v_cvt_pk_bf16_f32 v244, v124, v125
	v_cvt_pk_bf16_f32 v245, v126, v127

; __device__ __forceinline__ unsigned cvt_pk_bf16(float lo, float hi) { unsigned r; asm volatile("v_cvt_pk_bf16_f32 %0, %1, %2" : "=v"(r) : "v"(lo), "v"(hi)); return r; }
; __device__ __forceinline__ void store_bf16x4(bf16_t* p, f32x4 v) { u32x2 w; w.x = cvt_pk_bf16(v[0], v[1]); w.y = cvt_pk_bf16(v[2], v[3]); *(u32x2*)p = w; }
;   __device__ __forceinline__ void operator()(const f32x4 (&acc)[2][2][4][2], const pg8::Unit& u, int wr, int wc, int fr, int fq) const {
;     ...
;     EPI_LOOP(
;       if (pn < 4) { store_bf16x4(DQK + (size_t)row * 1024 + col, v); }
;       else if (pn < 6) { store_bf16x4(DV + (size_t)row * 512 + (col - 1024), v); }
.LBB0_630:
	s_andn2_b64 vcc, exec, s[12:13]
	s_cbranch_vccnz .LBB0_632
	v_lshl_add_u64 v[134:135], s[90:91], 0, v[132:133]
	v_mov_b32_e32 v129, v144
	v_lshl_add_u64 v[134:135], v[128:129], 1, v[134:135]
	v_cvt_pk_bf16_f32 v244, v124, v125
	v_cvt_pk_bf16_f32 v245, v126, v127

; __device__ __forceinline__ unsigned cvt_pk_bf16(float lo, float hi) { unsigned r; asm volatile("v_cvt_pk_bf16_f32 %0, %1, %2" : "=v"(r) : "v"(lo), "v"(hi)); return r; }
; __device__ __forceinline__ float siluf_(float v) { return v * sigmoidf_(v); }
; __device__ __forceinline__ void store_bf16x4(bf16_t* p, f32x4 v) { u32x2 w; w.x = cvt_pk_bf16(v[0], v[1]); w.y = cvt_pk_bf16(v[2], v[3]); *(u32x2*)p = w; }
;   __device__ __forceinline__ void operator()(const f32x4 (&acc)[2][2][4][2], const pg8::Unit& u, int wr, int wc, int fr, int fq) const {
;     ...
;     EPI_LOOP(
;       if (pn < 4) { store_bf16x4(DQK + (size_t)row * 1024 + col, v); }
;       else if (pn < 6) { store_bf16x4(DV + (size_t)row * 512 + (col - 1024), v); }
;       else if (pn < 10) { store_bf16x4(RV + (size_t)row * 512 + (col - 2048), v); }
;       else { f32x4 o; for (int j = 0; j < 4; ++j) o[j] = siluf_(v[j]); store_bf16x4(RG + (size_t)row * 512 + (col - 2560), o); }
.LBB0_633:
	v_lshlrev_b64 v[134:135], 11, v[130:131]
	s_andn2_b64 vcc, exec, s[12:13]
	v_lshl_add_u64 v[134:135], s[88:89], 0, v[134:135]
	v_ashrrev_i32_e32 v129, 31, v128
	s_cbranch_vccnz .LBB0_635
	v_lshl_add_u64 v[136:137], v[128:129], 1, v[134:135]
	v_cvt_pk_bf16_f32 v244, v124, v125
	v_cvt_pk_bf16_f32 v245, v126, v127
.LBB0_635:
	v_cndmask_b32_e64 v131, 0, 1, s[10:11]
	v_cmp_ne_u32_e64 s[12:13], 1, v131
	v_cndmask_b32_e64 v131, 0, 1, s[84:85]
	s_mov_b64 s[18:19], -1
	s_andn2_b64 vcc, exec, s[10:11]
	v_cmp_ne_u32_e64 s[10:11], 1, v131
	s_cbranch_vccnz .LBB0_665
	s_and_b64 vcc, exec, s[10:11]
	s_cbranch_vccnz .LBB0_642
	s_andn2_b64 vcc, exec, s[78:79]
	s_cbranch_vccnz .LBB0_639
	v_mul_f32_e32 v136, 0xbfb8aa3b, v121
	v_mul_f32_e32 v137, 0xbfb8aa3b, v122
	v_mul_f32_e32 v152, 0xbfb8aa3b, v123
	v_exp_f32_e32 v136, v136
	v_exp_f32_e32 v137, v137
	v_exp_f32_e32 v152, v152
	v_mul_f32_e32 v131, 0xbfb8aa3b, v120
	v_exp_f32_e32 v131, v131
	v_add_f32_e32 v136, 1.0, v136
	v_add_f32_e32 v137, 1.0, v137
	v_add_f32_e32 v152, 1.0, v152
	v_rcp_f32_e32 v136, v136
	v_rcp_f32_e32 v137, v137
	v_rcp_f32_e32 v152, v152
	v_add_f32_e32 v131, 1.0, v131
	v_rcp_f32_e32 v131, v131
	v_mul_f32_e32 v154, v121, v136
	v_mul_f32_e32 v155, v122, v137
	v_mul_f32_e32 v156, v123, v152
	v_lshl_add_u64 v[136:137], s[46:47], 0, v[132:133]
	v_mov_b32_e32 v152, v128
	v_mov_b32_e32 v153, v144
	v_lshl_add_u64 v[136:137], v[152:153], 1, v[136:137]
	v_add_co_u32_e32 v136, vcc, 0xfffff000, v136
	s_mov_b64 s[18:19], 0
	s_nop 0
	v_addc_co_u32_e32 v137, vcc, -1, v137, vcc
	v_mul_f32_e32 v131, v120, v131
	v_cvt_pk_bf16_f32 v246, v131, v154
	v_cvt_pk_bf16_f32 v247, v155, v156
	s_nop 1
	v_permlane16_swap_b32_e32 v244, v246
	v_permlane16_swap_b32_e32 v245, v247
	v_lshl_add_u64 v[248:249], v[136:137], 0, v[252:253]
	global_store_dwordx4 v[248:249], v[244:247], off offset:-1024
.LBB0_639:
	s_andn2_b64 vcc, exec, s[18:19]
	s_cbranch_vccnz .LBB0_641
	v_lshl_add_u64 v[136:137], s[48:49], 0, v[132:133]
	v_mov_b32_e32 v152, v128
	v_mov_b32_e32 v153, v144
	v_lshl_add_u64 v[136:137], v[152:153], 1, v[136:137]
	v_cvt_pk_bf16_f32 v246, v120, v121
	v_cvt_pk_bf16_f32 v247, v122, v123
	s_nop 1
	v_permlane16_swap_b32_e32 v244, v246
	v_permlane16_swap_b32_e32 v245, v247
	v_lshl_add_u64 v[248:249], v[136:137], 0, v[252:253]
	global_store_dwordx4 v[248:249], v[244:247], off offset:-4096

; __device__ __forceinline__ unsigned cvt_pk_bf16(float lo, float hi) { unsigned r; asm volatile("v_cvt_pk_bf16_f32 %0, %1, %2" : "=v"(r) : "v"(lo), "v"(hi)); return r; }
; __device__ __forceinline__ void store_bf16x4(bf16_t* p, f32x4 v) { u32x2 w; w.x = cvt_pk_bf16(v[0], v[1]); w.y = cvt_pk_bf16(v[2], v[3]); *(u32x2*)p = w; }
;   __device__ __forceinline__ void operator()(const f32x4 (&acc)[2][2][4][2], const pg8::Unit& u, int wr, int wc, int fr, int fq) const {
;     ...
;     EPI_LOOP(
;       if (pn < 4) { store_bf16x4(DQK + (size_t)row * 1024 + col, v); }
;       else if (pn < 6) { store_bf16x4(DV + (size_t)row * 512 + (col - 1024), v); }
.LBB0_642:
	s_andn2_b64 vcc, exec, s[18:19]
	s_cbranch_vccnz .LBB0_644
	v_lshl_add_u64 v[136:137], s[90:91], 0, v[132:133]
	v_mov_b32_e32 v152, v128
	v_mov_b32_e32 v153, v144
	v_lshl_add_u64 v[136:137], v[152:153], 1, v[136:137]
	v_cvt_pk_bf16_f32 v246, v120, v121
	v_cvt_pk_bf16_f32 v247, v122, v123
	s_nop 1
	v_permlane16_swap_b32_e32 v244, v246
	v_permlane16_swap_b32_e32 v245, v247
	v_lshl_add_u64 v[248:249], v[136:137], 0, v[252:253]
	global_store_dwordx4 v[248:249], v[244:247], off offset:-2048

; __device__ __forceinline__ unsigned cvt_pk_bf16(float lo, float hi) { unsigned r; asm volatile("v_cvt_pk_bf16_f32 %0, %1, %2" : "=v"(r) : "v"(lo), "v"(hi)); return r; }
; __device__ __forceinline__ float siluf_(float v) { return v * sigmoidf_(v); }
; __device__ __forceinline__ void store_bf16x4(bf16_t* p, f32x4 v) { u32x2 w; w.x = cvt_pk_bf16(v[0], v[1]); w.y = cvt_pk_bf16(v[2], v[3]); *(u32x2*)p = w; }
;   __device__ __forceinline__ void operator()(const f32x4 (&acc)[2][2][4][2], const pg8::Unit& u, int wr, int wc, int fr, int fq) const {
;     ...
;     EPI_LOOP(
;       if (pn < 4) { store_bf16x4(DQK + (size_t)row * 1024 + col, v); }
;       else if (pn < 6) { store_bf16x4(DV + (size_t)row * 512 + (col - 1024), v); }
;       else if (pn < 10) { store_bf16x4(RV + (size_t)row * 512 + (col - 2048), v); }
;       else { f32x4 o; for (int j = 0; j < 4; ++j) o[j] = siluf_(v[j]); store_bf16x4(RG + (size_t)row * 512 + (col - 2560), o); }
.LBB0_646:
	s_and_b64 vcc, exec, s[10:11]
	s_cbranch_vccnz .LBB0_652
	s_andn2_b64 vcc, exec, s[78:79]
	s_cbranch_vccnz .LBB0_649
	v_mul_f32_e32 v136, 0xbfb8aa3b, v117
	v_mul_f32_e32 v137, 0xbfb8aa3b, v118
	v_mul_f32_e32 v152, 0xbfb8aa3b, v119
	v_exp_f32_e32 v136, v136
	v_exp_f32_e32 v137, v137
	v_exp_f32_e32 v152, v152
	v_mul_f32_e32 v131, 0xbfb8aa3b, v116
	v_exp_f32_e32 v131, v131
	v_add_f32_e32 v136, 1.0, v136
	v_add_f32_e32 v137, 1.0, v137
	v_add_f32_e32 v152, 1.0, v152
	v_rcp_f32_e32 v136, v136
	v_rcp_f32_e32 v137, v137
	v_rcp_f32_e32 v152, v152
	v_add_f32_e32 v131, 1.0, v131
	v_rcp_f32_e32 v131, v131
	v_mul_f32_e32 v154, v117, v136
	v_mul_f32_e32 v155, v118, v137
	v_mul_f32_e32 v156, v119, v152
	v_lshl_add_u64 v[136:137], s[46:47], 0, v[132:133]
	v_mov_b32_e32 v152, v128
	v_mov_b32_e32 v153, v144
	v_lshl_add_u64 v[136:137], v[152:153], 1, v[136:137]
	v_add_co_u32_e32 v136, vcc, 0xfffff000, v136
	s_mov_b64 s[18:19], 0
	s_nop 0
	v_addc_co_u32_e32 v137, vcc, -1, v137, vcc
	v_mul_f32_e32 v131, v116, v131
	v_cvt_pk_bf16_f32 v244, v131, v154
	v_cvt_pk_bf16_f32 v245, v155, v156
.LBB0_649:
	s_andn2_b64 vcc, exec, s[18:19]
	s_cbranch_vccnz .LBB0_651
	v_lshl_add_u64 v[136:137], s[48:49], 0, v[132:133]
	v_mov_b32_e32 v152, v128
	v_mov_b32_e32 v153, v144
	v_lshl_add_u64 v[136:137], v[152:153], 1, v[136:137]
	v_cvt_pk_bf16_f32 v244, v116, v117
	v_cvt_pk_bf16_f32 v245, v118, v119

; __device__ __forceinline__ unsigned cvt_pk_bf16(float lo, float hi) { unsigned r; asm volatile("v_cvt_pk_bf16_f32 %0, %1, %2" : "=v"(r) : "v"(lo), "v"(hi)); return r; }
; __device__ __forceinline__ void store_bf16x4(bf16_t* p, f32x4 v) { u32x2 w; w.x = cvt_pk_bf16(v[0], v[1]); w.y = cvt_pk_bf16(v[2], v[3]); *(u32x2*)p = w; }
;   __device__ __forceinline__ void operator()(const f32x4 (&acc)[2][2][4][2], const pg8::Unit& u, int wr, int wc, int fr, int fq) const {
;     ...
;     EPI_LOOP(
;       if (pn < 4) { store_bf16x4(DQK + (size_t)row * 1024 + col, v); }
;       else if (pn < 6) { store_bf16x4(DV + (size_t)row * 512 + (col - 1024), v); }
.LBB0_652:
	s_andn2_b64 vcc, exec, s[18:19]
	s_cbranch_vccnz .LBB0_654
	v_lshl_add_u64 v[136:137], s[90:91], 0, v[132:133]
	v_mov_b32_e32 v152, v128
	v_mov_b32_e32 v153, v144
	v_lshl_add_u64 v[136:137], v[152:153], 1, v[136:137]
	v_cvt_pk_bf16_f32 v244, v116, v117
	v_cvt_pk_bf16_f32 v245, v118, v119

; __device__ __forceinline__ unsigned cvt_pk_bf16(float lo, float hi) { unsigned r; asm volatile("v_cvt_pk_bf16_f32 %0, %1, %2" : "=v"(r) : "v"(lo), "v"(hi)); return r; }
; __device__ __forceinline__ float siluf_(float v) { return v * sigmoidf_(v); }
; __device__ __forceinline__ void store_bf16x4(bf16_t* p, f32x4 v) { u32x2 w; w.x = cvt_pk_bf16(v[0], v[1]); w.y = cvt_pk_bf16(v[2], v[3]); *(u32x2*)p = w; }
;   __device__ __forceinline__ void operator()(const f32x4 (&acc)[2][2][4][2], const pg8::Unit& u, int wr, int wc, int fr, int fq) const {
;     ...
;     EPI_LOOP(
;       if (pn < 4) { store_bf16x4(DQK + (size_t)row * 1024 + col, v); }
;       else if (pn < 6) { store_bf16x4(DV + (size_t)row * 512 + (col - 1024), v); }
;       else if (pn < 10) { store_bf16x4(RV + (size_t)row * 512 + (col - 2048), v); }
;       else { f32x4 o; for (int j = 0; j < 4; ++j) o[j] = siluf_(v[j]); store_bf16x4(RG + (size_t)row * 512 + (col - 2560), o); }
.LBB0_656:
	s_and_b64 vcc, exec, s[10:11]
	s_cbranch_vccnz .LBB0_662
	s_andn2_b64 vcc, exec, s[78:79]
	s_cbranch_vccnz .LBB0_659
	v_mul_f32_e32 v136, 0xbfb8aa3b, v113
	v_mul_f32_e32 v137, 0xbfb8aa3b, v114
	v_mul_f32_e32 v152, 0xbfb8aa3b, v115
	v_exp_f32_e32 v136, v136
	v_exp_f32_e32 v137, v137
	v_exp_f32_e32 v152, v152
	v_mul_f32_e32 v131, 0xbfb8aa3b, v112
	v_exp_f32_e32 v131, v131
	v_add_f32_e32 v136, 1.0, v136
	v_add_f32_e32 v137, 1.0, v137
	v_add_f32_e32 v152, 1.0, v152
	v_rcp_f32_e32 v136, v136
	v_rcp_f32_e32 v137, v137
	v_rcp_f32_e32 v152, v152
	v_add_f32_e32 v131, 1.0, v131
	v_rcp_f32_e32 v131, v131
	v_mul_f32_e32 v154, v113, v136
	v_mul_f32_e32 v155, v114, v137
	v_mul_f32_e32 v156, v115, v152
	v_lshl_add_u64 v[136:137], s[46:47], 0, v[132:133]
	v_mov_b32_e32 v152, v128
	v_mov_b32_e32 v153, v144
	v_lshl_add_u64 v[136:137], v[152:153], 1, v[136:137]
	v_add_co_u32_e32 v136, vcc, 0xfffff000, v136
	s_mov_b64 s[18:19], 0
	s_nop 0
	v_addc_co_u32_e32 v137, vcc, -1, v137, vcc
	v_mul_f32_e32 v131, v112, v131
	v_cvt_pk_bf16_f32 v246, v131, v154
	v_cvt_pk_bf16_f32 v247, v155, v156
	s_nop 1
	v_permlane16_swap_b32_e32 v244, v246
	v_permlane16_swap_b32_e32 v245, v247
	v_lshl_add_u64 v[248:249], v[136:137], 0, v[252:253]
	global_store_dwordx4 v[248:249], v[244:247], off offset:-768
.LBB0_659:
	s_andn2_b64 vcc, exec, s[18:19]
	s_cbranch_vccnz .LBB0_661
	v_lshl_add_u64 v[136:137], s[48:49], 0, v[132:133]
	v_mov_b32_e32 v152, v128
	v_mov_b32_e32 v153, v144
	v_lshl_add_u64 v[136:137], v[152:153], 1, v[136:137]
	v_cvt_pk_bf16_f32 v246, v112, v113
	v_cvt_pk_bf16_f32 v247, v114, v115
	s_nop 1
	v_permlane16_swap_b32_e32 v244, v246
	v_permlane16_swap_b32_e32 v245, v247
	v_lshl_add_u64 v[248:249], v[136:137], 0, v[252:253]
	global_store_dwordx4 v[248:249], v[244:247], off offset:-3840

; __device__ __forceinline__ unsigned cvt_pk_bf16(float lo, float hi) { unsigned r; asm volatile("v_cvt_pk_bf16_f32 %0, %1, %2" : "=v"(r) : "v"(lo), "v"(hi)); return r; }
; __device__ __forceinline__ void store_bf16x4(bf16_t* p, f32x4 v) { u32x2 w; w.x = cvt_pk_bf16(v[0], v[1]); w.y = cvt_pk_bf16(v[2], v[3]); *(u32x2*)p = w; }
;   __device__ __forceinline__ void operator()(const f32x4 (&acc)[2][2][4][2], const pg8::Unit& u, int wr, int wc, int fr, int fq) const {
;     ...
;     EPI_LOOP(
;       if (pn < 4) { store_bf16x4(DQK + (size_t)row * 1024 + col, v); }
;       else if (pn < 6) { store_bf16x4(DV + (size_t)row * 512 + (col - 1024), v); }
.LBB0_662:
	s_andn2_b64 vcc, exec, s[18:19]
	s_cbranch_vccnz .LBB0_664
	v_lshl_add_u64 v[132:133], s[90:91], 0, v[132:133]
	v_mov_b32_e32 v136, v128
	v_mov_b32_e32 v137, v144
	v_lshl_add_u64 v[132:133], v[136:137], 1, v[132:133]
	v_cvt_pk_bf16_f32 v246, v112, v113
	v_cvt_pk_bf16_f32 v247, v114, v115
	s_nop 1
	v_permlane16_swap_b32_e32 v244, v246
	v_permlane16_swap_b32_e32 v245, v247
	v_lshl_add_u64 v[248:249], v[132:133], 0, v[252:253]
	global_store_dwordx4 v[248:249], v[244:247], off offset:-1792

; __device__ __forceinline__ unsigned cvt_pk_bf16(float lo, float hi) { unsigned r; asm volatile("v_cvt_pk_bf16_f32 %0, %1, %2" : "=v"(r) : "v"(lo), "v"(hi)); return r; }
; __device__ __forceinline__ void store_bf16x4(bf16_t* p, f32x4 v) { u32x2 w; w.x = cvt_pk_bf16(v[0], v[1]); w.y = cvt_pk_bf16(v[2], v[3]); *(u32x2*)p = w; }
;   __device__ __forceinline__ void operator()(const f32x4 (&acc)[2][2][4][2], const pg8::Unit& u, int wr, int wc, int fr, int fq) const {
;     ...
;     EPI_LOOP(
;       if (pn < 4) { store_bf16x4(DQK + (size_t)row * 1024 + col, v); }
.LBB0_666:
	v_lshl_add_u64 v[136:137], v[128:129], 1, v[134:135]
	v_cvt_pk_bf16_f32 v246, v120, v121
	v_cvt_pk_bf16_f32 v247, v122, v123
	s_nop 1
	v_permlane16_swap_b32_e32 v244, v246
	v_permlane16_swap_b32_e32 v245, v247
	v_lshl_add_u64 v[248:249], v[136:137], 0, v[252:253]
	global_store_dwordx4 v[248:249], v[244:247], off
	s_and_b64 vcc, exec, s[12:13]
	s_mov_b64 s[18:19], -1
	s_cbranch_vccz .LBB0_646

; __device__ __forceinline__ unsigned cvt_pk_bf16(float lo, float hi) { unsigned r; asm volatile("v_cvt_pk_bf16_f32 %0, %1, %2" : "=v"(r) : "v"(lo), "v"(hi)); return r; }
; __device__ __forceinline__ void store_bf16x4(bf16_t* p, f32x4 v) { u32x2 w; w.x = cvt_pk_bf16(v[0], v[1]); w.y = cvt_pk_bf16(v[2], v[3]); *(u32x2*)p = w; }
;   __device__ __forceinline__ void operator()(const f32x4 (&acc)[2][2][4][2], const pg8::Unit& u, int wr, int wc, int fr, int fq) const {
;     ...
;     EPI_LOOP(
;       if (pn < 4) { store_bf16x4(DQK + (size_t)row * 1024 + col, v); }
.LBB0_668:
	v_lshl_add_u64 v[136:137], v[128:129], 1, v[134:135]
	v_cvt_pk_bf16_f32 v244, v116, v117
	v_cvt_pk_bf16_f32 v245, v118, v119
	s_and_b64 vcc, exec, s[12:13]
	s_mov_b64 s[18:19], -1
	s_cbranch_vccz .LBB0_656

; __device__ __forceinline__ unsigned cvt_pk_bf16(float lo, float hi) { unsigned r; asm volatile("v_cvt_pk_bf16_f32 %0, %1, %2" : "=v"(r) : "v"(lo), "v"(hi)); return r; }
; __device__ __forceinline__ float siluf_(float v) { return v * sigmoidf_(v); }
; __device__ __forceinline__ void store_bf16x4(bf16_t* p, f32x4 v) { u32x2 w; w.x = cvt_pk_bf16(v[0], v[1]); w.y = cvt_pk_bf16(v[2], v[3]); *(u32x2*)p = w; }
;   __device__ __forceinline__ void operator()(const f32x4 (&acc)[2][2][4][2], const pg8::Unit& u, int wr, int wc, int fr, int fq) const {
;     ...
;     EPI_LOOP(
;       if (pn < 4) { store_bf16x4(DQK + (size_t)row * 1024 + col, v); }
;       else if (pn < 6) { store_bf16x4(DV + (size_t)row * 512 + (col - 1024), v); }
;       else if (pn < 10) { store_bf16x4(RV + (size_t)row * 512 + (col - 2048), v); }
;       else { f32x4 o; for (int j = 0; j < 4; ++j) o[j] = siluf_(v[j]); store_bf16x4(RG + (size_t)row * 512 + (col - 2560), o); }
.LBB0_670:
	v_lshl_add_u64 v[132:133], v[128:129], 1, v[134:135]
	v_cvt_pk_bf16_f32 v246, v112, v113
	v_cvt_pk_bf16_f32 v247, v114, v115
	s_nop 1
	v_permlane16_swap_b32_e32 v244, v246
	v_permlane16_swap_b32_e32 v245, v247
	v_lshl_add_u64 v[248:249], v[132:133], 0, v[252:253]
	global_store_dwordx4 v[248:249], v[244:247], off offset:256
.LBB0_671:
	v_or_b32_e32 v134, 16, v130
	v_ashrrev_i32_e32 v135, 31, v134
	v_lshlrev_b64 v[132:133], 10, v[134:135]
	s_and_b64 vcc, exec, s[12:13]
	s_mov_b64 s[18:19], -1
	s_cbranch_vccnz .LBB0_711
	s_and_b64 vcc, exec, s[10:11]
	s_cbranch_vccnz .LBB0_678
	s_andn2_b64 vcc, exec, s[78:79]
	s_cbranch_vccnz .LBB0_675
	v_mul_f32_e32 v136, 0xbfb8aa3b, v109
	v_mul_f32_e32 v137, 0xbfb8aa3b, v110
	v_mul_f32_e32 v152, 0xbfb8aa3b, v111
	v_exp_f32_e32 v136, v136
	v_exp_f32_e32 v137, v137
	v_exp_f32_e32 v152, v152
	v_mul_f32_e32 v131, 0xbfb8aa3b, v108
	v_exp_f32_e32 v131, v131
	v_add_f32_e32 v136, 1.0, v136
	v_add_f32_e32 v137, 1.0, v137
	v_add_f32_e32 v152, 1.0, v152
	v_rcp_f32_e32 v136, v136
	v_rcp_f32_e32 v137, v137
	v_rcp_f32_e32 v152, v152
	v_add_f32_e32 v131, 1.0, v131
	v_rcp_f32_e32 v131, v131
	v_mul_f32_e32 v154, v109, v136
	v_mul_f32_e32 v155, v110, v137
	v_mul_f32_e32 v156, v111, v152
	v_lshl_add_u64 v[136:137], s[46:47], 0, v[132:133]
	v_mov_b32_e32 v152, v128
	v_mov_b32_e32 v153, v144
	v_lshl_add_u64 v[136:137], v[152:153], 1, v[136:137]
	v_add_co_u32_e32 v136, vcc, 0xfffff000, v136
	s_mov_b64 s[18:19], 0
	s_nop 0
	v_addc_co_u32_e32 v137, vcc, -1, v137, vcc
	v_mul_f32_e32 v131, v108, v131
	v_cvt_pk_bf16_f32 v244, v131, v154
	v_cvt_pk_bf16_f32 v245, v155, v156
.LBB0_675:
	s_andn2_b64 vcc, exec, s[18:19]
	s_cbranch_vccnz .LBB0_677
	v_lshl_add_u64 v[136:137], s[48:49], 0, v[132:133]
	v_mov_b32_e32 v152, v128
	v_mov_b32_e32 v153, v144
	v_lshl_add_u64 v[136:137], v[152:153], 1, v[136:137]
	v_cvt_pk_bf16_f32 v244, v108, v109
	v_cvt_pk_bf16_f32 v245, v110, v111

; __device__ __forceinline__ unsigned cvt_pk_bf16(float lo, float hi) { unsigned r; asm volatile("v_cvt_pk_bf16_f32 %0, %1, %2" : "=v"(r) : "v"(lo), "v"(hi)); return r; }
; __device__ __forceinline__ void store_bf16x4(bf16_t* p, f32x4 v) { u32x2 w; w.x = cvt_pk_bf16(v[0], v[1]); w.y = cvt_pk_bf16(v[2], v[3]); *(u32x2*)p = w; }
;   __device__ __forceinline__ void operator()(const f32x4 (&acc)[2][2][4][2], const pg8::Unit& u, int wr, int wc, int fr, int fq) const {
;     ...
;     EPI_LOOP(
;       if (pn < 4) { store_bf16x4(DQK + (size_t)row * 1024 + col, v); }
;       else if (pn < 6) { store_bf16x4(DV + (size_t)row * 512 + (col - 1024), v); }
.LBB0_678:
	s_andn2_b64 vcc, exec, s[18:19]
	s_cbranch_vccnz .LBB0_680
	v_lshl_add_u64 v[136:137], s[90:91], 0, v[132:133]
	v_mov_b32_e32 v152, v128
	v_mov_b32_e32 v153, v144
	v_lshl_add_u64 v[136:137], v[152:153], 1, v[136:137]
	v_cvt_pk_bf16_f32 v244, v108, v109
	v_cvt_pk_bf16_f32 v245, v110, v111

; __device__ __forceinline__ unsigned cvt_pk_bf16(float lo, float hi) { unsigned r; asm volatile("v_cvt_pk_bf16_f32 %0, %1, %2" : "=v"(r) : "v"(lo), "v"(hi)); return r; }
; __device__ __forceinline__ float siluf_(float v) { return v * sigmoidf_(v); }
; __device__ __forceinline__ void store_bf16x4(bf16_t* p, f32x4 v) { u32x2 w; w.x = cvt_pk_bf16(v[0], v[1]); w.y = cvt_pk_bf16(v[2], v[3]); *(u32x2*)p = w; }
;   __device__ __forceinline__ void operator()(const f32x4 (&acc)[2][2][4][2], const pg8::Unit& u, int wr, int wc, int fr, int fq) const {
;     ...
;     EPI_LOOP(
;       if (pn < 4) { store_bf16x4(DQK + (size_t)row * 1024 + col, v); }
;       else if (pn < 6) { store_bf16x4(DV + (size_t)row * 512 + (col - 1024), v); }
;       else if (pn < 10) { store_bf16x4(RV + (size_t)row * 512 + (col - 2048), v); }
;       else { f32x4 o; for (int j = 0; j < 4; ++j) o[j] = siluf_(v[j]); store_bf16x4(RG + (size_t)row * 512 + (col - 2560), o); }
.LBB0_682:
	s_and_b64 vcc, exec, s[10:11]
	s_cbranch_vccnz .LBB0_688
	s_andn2_b64 vcc, exec, s[78:79]
	s_cbranch_vccnz .LBB0_685
	v_mul_f32_e32 v136, 0xbfb8aa3b, v105
	v_mul_f32_e32 v137, 0xbfb8aa3b, v106
	v_mul_f32_e32 v152, 0xbfb8aa3b, v107
	v_exp_f32_e32 v136, v136
	v_exp_f32_e32 v137, v137
	v_exp_f32_e32 v152, v152
	v_mul_f32_e32 v131, 0xbfb8aa3b, v104
	v_exp_f32_e32 v131, v131
	v_add_f32_e32 v136, 1.0, v136
	v_add_f32_e32 v137, 1.0, v137
	v_add_f32_e32 v152, 1.0, v152
	v_rcp_f32_e32 v136, v136
	v_rcp_f32_e32 v137, v137
	v_rcp_f32_e32 v152, v152
	v_add_f32_e32 v131, 1.0, v131
	v_rcp_f32_e32 v131, v131
	v_mul_f32_e32 v154, v105, v136
	v_mul_f32_e32 v155, v106, v137
	v_mul_f32_e32 v156, v107, v152
	v_lshl_add_u64 v[136:137], s[46:47], 0, v[132:133]
	v_mov_b32_e32 v152, v128
	v_mov_b32_e32 v153, v144
	v_lshl_add_u64 v[136:137], v[152:153], 1, v[136:137]
	v_add_co_u32_e32 v136, vcc, 0xfffff000, v136
	s_mov_b64 s[18:19], 0
	s_nop 0
	v_addc_co_u32_e32 v137, vcc, -1, v137, vcc
	v_mul_f32_e32 v131, v104, v131
	v_cvt_pk_bf16_f32 v246, v131, v154
	v_cvt_pk_bf16_f32 v247, v155, v156
	s_nop 1
	v_permlane16_swap_b32_e32 v244, v246
	v_permlane16_swap_b32_e32 v245, v247
	v_lshl_add_u64 v[248:249], v[136:137], 0, v[252:253]
	global_store_dwordx4 v[248:249], v[244:247], off offset:-1024
.LBB0_685:
	s_andn2_b64 vcc, exec, s[18:19]
	s_cbranch_vccnz .LBB0_687
	v_lshl_add_u64 v[136:137], s[48:49], 0, v[132:133]
	v_mov_b32_e32 v152, v128
	v_mov_b32_e32 v153, v144
	v_lshl_add_u64 v[136:137], v[152:153], 1, v[136:137]
	v_cvt_pk_bf16_f32 v246, v104, v105
	v_cvt_pk_bf16_f32 v247, v106, v107
	s_nop 1
	v_permlane16_swap_b32_e32 v244, v246
	v_permlane16_swap_b32_e32 v245, v247
	v_lshl_add_u64 v[248:249], v[136:137], 0, v[252:253]
	global_store_dwordx4 v[248:249], v[244:247], off offset:-4096

; __device__ __forceinline__ unsigned cvt_pk_bf16(float lo, float hi) { unsigned r; asm volatile("v_cvt_pk_bf16_f32 %0, %1, %2" : "=v"(r) : "v"(lo), "v"(hi)); return r; }
; __device__ __forceinline__ void store_bf16x4(bf16_t* p, f32x4 v) { u32x2 w; w.x = cvt_pk_bf16(v[0], v[1]); w.y = cvt_pk_bf16(v[2], v[3]); *(u32x2*)p = w; }
;   __device__ __forceinline__ void operator()(const f32x4 (&acc)[2][2][4][2], const pg8::Unit& u, int wr, int wc, int fr, int fq) const {
;     ...
;     EPI_LOOP(
;       if (pn < 4) { store_bf16x4(DQK + (size_t)row * 1024 + col, v); }
;       else if (pn < 6) { store_bf16x4(DV + (size_t)row * 512 + (col - 1024), v); }
.LBB0_688:
	s_andn2_b64 vcc, exec, s[18:19]
	s_cbranch_vccnz .LBB0_690
	v_lshl_add_u64 v[136:137], s[90:91], 0, v[132:133]
	v_mov_b32_e32 v152, v128
	v_mov_b32_e32 v153, v144
	v_lshl_add_u64 v[136:137], v[152:153], 1, v[136:137]
	v_cvt_pk_bf16_f32 v246, v104, v105
	v_cvt_pk_bf16_f32 v247, v106, v107
	s_nop 1
	v_permlane16_swap_b32_e32 v244, v246
	v_permlane16_swap_b32_e32 v245, v247
	v_lshl_add_u64 v[248:249], v[136:137], 0, v[252:253]
	global_store_dwordx4 v[248:249], v[244:247], off offset:-2048

; __device__ __forceinline__ unsigned cvt_pk_bf16(float lo, float hi) { unsigned r; asm volatile("v_cvt_pk_bf16_f32 %0, %1, %2" : "=v"(r) : "v"(lo), "v"(hi)); return r; }
; __device__ __forceinline__ float siluf_(float v) { return v * sigmoidf_(v); }
; __device__ __forceinline__ void store_bf16x4(bf16_t* p, f32x4 v) { u32x2 w; w.x = cvt_pk_bf16(v[0], v[1]); w.y = cvt_pk_bf16(v[2], v[3]); *(u32x2*)p = w; }
;   __device__ __forceinline__ void operator()(const f32x4 (&acc)[2][2][4][2], const pg8::Unit& u, int wr, int wc, int fr, int fq) const {
;     ...
;     EPI_LOOP(
;       if (pn < 4) { store_bf16x4(DQK + (size_t)row * 1024 + col, v); }
;       else if (pn < 6) { store_bf16x4(DV + (size_t)row * 512 + (col - 1024), v); }
;       else if (pn < 10) { store_bf16x4(RV + (size_t)row * 512 + (col - 2048), v); }
;       else { f32x4 o; for (int j = 0; j < 4; ++j) o[j] = siluf_(v[j]); store_bf16x4(RG + (size_t)row * 512 + (col - 2560), o); }
.LBB0_692:
	s_and_b64 vcc, exec, s[10:11]
	s_cbranch_vccnz .LBB0_698
	s_andn2_b64 vcc, exec, s[78:79]
	s_cbranch_vccnz .LBB0_695
	v_mul_f32_e32 v136, 0xbfb8aa3b, v101
	v_mul_f32_e32 v137, 0xbfb8aa3b, v102
	v_mul_f32_e32 v152, 0xbfb8aa3b, v103
	v_exp_f32_e32 v136, v136
	v_exp_f32_e32 v137, v137
	v_exp_f32_e32 v152, v152
	v_mul_f32_e32 v131, 0xbfb8aa3b, v100
	v_exp_f32_e32 v131, v131
	v_add_f32_e32 v136, 1.0, v136
	v_add_f32_e32 v137, 1.0, v137
	v_add_f32_e32 v152, 1.0, v152
	v_rcp_f32_e32 v136, v136
	v_rcp_f32_e32 v137, v137
	v_rcp_f32_e32 v152, v152
	v_add_f32_e32 v131, 1.0, v131
	v_rcp_f32_e32 v131, v131
	v_mul_f32_e32 v154, v101, v136
	v_mul_f32_e32 v155, v102, v137
	v_mul_f32_e32 v156, v103, v152
	v_lshl_add_u64 v[136:137], s[46:47], 0, v[132:133]
	v_mov_b32_e32 v152, v128
	v_mov_b32_e32 v153, v144
	v_lshl_add_u64 v[136:137], v[152:153], 1, v[136:137]
	v_add_co_u32_e32 v136, vcc, 0xfffff000, v136
	s_mov_b64 s[18:19], 0
	s_nop 0
	v_addc_co_u32_e32 v137, vcc, -1, v137, vcc
	v_mul_f32_e32 v131, v100, v131
	v_cvt_pk_bf16_f32 v244, v131, v154
	v_cvt_pk_bf16_f32 v245, v155, v156
.LBB0_695:
	s_andn2_b64 vcc, exec, s[18:19]
	s_cbranch_vccnz .LBB0_697
	v_lshl_add_u64 v[136:137], s[48:49], 0, v[132:133]
	v_mov_b32_e32 v152, v128
	v_mov_b32_e32 v153, v144
	v_lshl_add_u64 v[136:137], v[152:153], 1, v[136:137]
	v_cvt_pk_bf16_f32 v244, v100, v101
	v_cvt_pk_bf16_f32 v245, v102, v103

; __device__ __forceinline__ unsigned cvt_pk_bf16(float lo, float hi) { unsigned r; asm volatile("v_cvt_pk_bf16_f32 %0, %1, %2" : "=v"(r) : "v"(lo), "v"(hi)); return r; }
; __device__ __forceinline__ void store_bf16x4(bf16_t* p, f32x4 v) { u32x2 w; w.x = cvt_pk_bf16(v[0], v[1]); w.y = cvt_pk_bf16(v[2], v[3]); *(u32x2*)p = w; }
;   __device__ __forceinline__ void operator()(const f32x4 (&acc)[2][2][4][2], const pg8::Unit& u, int wr, int wc, int fr, int fq) const {
;     ...
;     EPI_LOOP(
;       if (pn < 4) { store_bf16x4(DQK + (size_t)row * 1024 + col, v); }
;       else if (pn < 6) { store_bf16x4(DV + (size_t)row * 512 + (col - 1024), v); }
.LBB0_698:
	s_andn2_b64 vcc, exec, s[18:19]
	s_cbranch_vccnz .LBB0_700
	v_lshl_add_u64 v[136:137], s[90:91], 0, v[132:133]
	v_mov_b32_e32 v152, v128
	v_mov_b32_e32 v153, v144
	v_lshl_add_u64 v[136:137], v[152:153], 1, v[136:137]
	v_cvt_pk_bf16_f32 v244, v100, v101
	v_cvt_pk_bf16_f32 v245, v102, v103

; __device__ __forceinline__ unsigned cvt_pk_bf16(float lo, float hi) { unsigned r; asm volatile("v_cvt_pk_bf16_f32 %0, %1, %2" : "=v"(r) : "v"(lo), "v"(hi)); return r; }
; __device__ __forceinline__ float siluf_(float v) { return v * sigmoidf_(v); }
; __device__ __forceinline__ void store_bf16x4(bf16_t* p, f32x4 v) { u32x2 w; w.x = cvt_pk_bf16(v[0], v[1]); w.y = cvt_pk_bf16(v[2], v[3]); *(u32x2*)p = w; }
;   __device__ __forceinline__ void operator()(const f32x4 (&acc)[2][2][4][2], const pg8::Unit& u, int wr, int wc, int fr, int fq) const {
;     ...
;     EPI_LOOP(
;       if (pn < 4) { store_bf16x4(DQK + (size_t)row * 1024 + col, v); }
;       else if (pn < 6) { store_bf16x4(DV + (size_t)row * 512 + (col - 1024), v); }
;       else if (pn < 10) { store_bf16x4(RV + (size_t)row * 512 + (col - 2048), v); }
;       else { f32x4 o; for (int j = 0; j < 4; ++j) o[j] = siluf_(v[j]); store_bf16x4(RG + (size_t)row * 512 + (col - 2560), o); }
.LBB0_702:
	s_and_b64 vcc, exec, s[10:11]
	s_cbranch_vccnz .LBB0_708
	s_andn2_b64 vcc, exec, s[78:79]
	s_cbranch_vccnz .LBB0_705
	v_mul_f32_e32 v136, 0xbfb8aa3b, v97
	v_mul_f32_e32 v137, 0xbfb8aa3b, v98
	v_mul_f32_e32 v152, 0xbfb8aa3b, v99
	v_exp_f32_e32 v136, v136
	v_exp_f32_e32 v137, v137
	v_exp_f32_e32 v152, v152
	v_mul_f32_e32 v131, 0xbfb8aa3b, v96
	v_exp_f32_e32 v131, v131
	v_add_f32_e32 v136, 1.0, v136
	v_add_f32_e32 v137, 1.0, v137
	v_add_f32_e32 v152, 1.0, v152
	v_rcp_f32_e32 v136, v136
	v_rcp_f32_e32 v137, v137
	v_rcp_f32_e32 v152, v152
	v_add_f32_e32 v131, 1.0, v131
	v_rcp_f32_e32 v131, v131
	v_mul_f32_e32 v154, v97, v136
	v_mul_f32_e32 v155, v98, v137
	v_mul_f32_e32 v156, v99, v152
	v_lshl_add_u64 v[136:137], s[46:47], 0, v[132:133]
	v_mov_b32_e32 v152, v128
	v_mov_b32_e32 v153, v144
	v_lshl_add_u64 v[136:137], v[152:153], 1, v[136:137]
	v_add_co_u32_e32 v136, vcc, 0xfffff000, v136
	s_mov_b64 s[18:19], 0
	s_nop 0
	v_addc_co_u32_e32 v137, vcc, -1, v137, vcc
	v_mul_f32_e32 v131, v96, v131
	v_cvt_pk_bf16_f32 v246, v131, v154
	v_cvt_pk_bf16_f32 v247, v155, v156
	s_nop 1
	v_permlane16_swap_b32_e32 v244, v246
	v_permlane16_swap_b32_e32 v245, v247
	v_lshl_add_u64 v[248:249], v[136:137], 0, v[252:253]
	global_store_dwordx4 v[248:249], v[244:247], off offset:-768
.LBB0_705:
	s_andn2_b64 vcc, exec, s[18:19]
	s_cbranch_vccnz .LBB0_707
	v_lshl_add_u64 v[136:137], s[48:49], 0, v[132:133]
	v_mov_b32_e32 v152, v128
	v_mov_b32_e32 v153, v144
	v_lshl_add_u64 v[136:137], v[152:153], 1, v[136:137]
	v_cvt_pk_bf16_f32 v246, v96, v97
	v_cvt_pk_bf16_f32 v247, v98, v99
	s_nop 1
	v_permlane16_swap_b32_e32 v244, v246
	v_permlane16_swap_b32_e32 v245, v247
	v_lshl_add_u64 v[248:249], v[136:137], 0, v[252:253]
	global_store_dwordx4 v[248:249], v[244:247], off offset:-3840

; __device__ __forceinline__ unsigned cvt_pk_bf16(float lo, float hi) { unsigned r; asm volatile("v_cvt_pk_bf16_f32 %0, %1, %2" : "=v"(r) : "v"(lo), "v"(hi)); return r; }
; __device__ __forceinline__ void store_bf16x4(bf16_t* p, f32x4 v) { u32x2 w; w.x = cvt_pk_bf16(v[0], v[1]); w.y = cvt_pk_bf16(v[2], v[3]); *(u32x2*)p = w; }
;   __device__ __forceinline__ void operator()(const f32x4 (&acc)[2][2][4][2], const pg8::Unit& u, int wr, int wc, int fr, int fq) const {
;     ...
;     EPI_LOOP(
;       if (pn < 4) { store_bf16x4(DQK + (size_t)row * 1024 + col, v); }
;       else if (pn < 6) { store_bf16x4(DV + (size_t)row * 512 + (col - 1024), v); }
.LBB0_708:
	s_andn2_b64 vcc, exec, s[18:19]
	s_cbranch_vccnz .LBB0_710
	v_lshl_add_u64 v[132:133], s[90:91], 0, v[132:133]
	v_mov_b32_e32 v136, v128
	v_mov_b32_e32 v137, v144
	v_lshl_add_u64 v[132:133], v[136:137], 1, v[132:133]
	v_cvt_pk_bf16_f32 v246, v96, v97
	v_cvt_pk_bf16_f32 v247, v98, v99
	s_nop 1
	v_permlane16_swap_b32_e32 v244, v246
	v_permlane16_swap_b32_e32 v245, v247
	v_lshl_add_u64 v[248:249], v[132:133], 0, v[252:253]
	global_store_dwordx4 v[248:249], v[244:247], off offset:-1792

; __device__ __forceinline__ unsigned cvt_pk_bf16(float lo, float hi) { unsigned r; asm volatile("v_cvt_pk_bf16_f32 %0, %1, %2" : "=v"(r) : "v"(lo), "v"(hi)); return r; }
; __device__ __forceinline__ void store_bf16x4(bf16_t* p, f32x4 v) { u32x2 w; w.x = cvt_pk_bf16(v[0], v[1]); w.y = cvt_pk_bf16(v[2], v[3]); *(u32x2*)p = w; }
;   __device__ __forceinline__ void operator()(const f32x4 (&acc)[2][2][4][2], const pg8::Unit& u, int wr, int wc, int fr, int fq) const {
;     ...
;     EPI_LOOP(
;       if (pn < 4) { store_bf16x4(DQK + (size_t)row * 1024 + col, v); }
.LBB0_712:
	v_lshl_add_u64 v[136:137], v[128:129], 1, v[134:135]
	v_cvt_pk_bf16_f32 v244, v108, v109
	v_cvt_pk_bf16_f32 v245, v110, v111
	s_and_b64 vcc, exec, s[12:13]
	s_mov_b64 s[18:19], -1
	s_cbranch_vccz .LBB0_682

; __device__ __forceinline__ unsigned cvt_pk_bf16(float lo, float hi) { unsigned r; asm volatile("v_cvt_pk_bf16_f32 %0, %1, %2" : "=v"(r) : "v"(lo), "v"(hi)); return r; }
; __device__ __forceinline__ void store_bf16x4(bf16_t* p, f32x4 v) { u32x2 w; w.x = cvt_pk_bf16(v[0], v[1]); w.y = cvt_pk_bf16(v[2], v[3]); *(u32x2*)p = w; }
;   __device__ __forceinline__ void operator()(const f32x4 (&acc)[2][2][4][2], const pg8::Unit& u, int wr, int wc, int fr, int fq) const {
;     ...
;     EPI_LOOP(
;       if (pn < 4) { store_bf16x4(DQK + (size_t)row * 1024 + col, v); }
.LBB0_714:
	v_lshl_add_u64 v[136:137], v[128:129], 1, v[134:135]
	v_cvt_pk_bf16_f32 v246, v104, v105
	v_cvt_pk_bf16_f32 v247, v106, v107
	s_nop 1
	v_permlane16_swap_b32_e32 v244, v246
	v_permlane16_swap_b32_e32 v245, v247
	v_lshl_add_u64 v[248:249], v[136:137], 0, v[252:253]
	global_store_dwordx4 v[248:249], v[244:247], off
	s_and_b64 vcc, exec, s[12:13]
	s_mov_b64 s[18:19], -1
	s_cbranch_vccz .LBB0_692

; __device__ __forceinline__ unsigned cvt_pk_bf16(float lo, float hi) { unsigned r; asm volatile("v_cvt_pk_bf16_f32 %0, %1, %2" : "=v"(r) : "v"(lo), "v"(hi)); return r; }
; __device__ __forceinline__ void store_bf16x4(bf16_t* p, f32x4 v) { u32x2 w; w.x = cvt_pk_bf16(v[0], v[1]); w.y = cvt_pk_bf16(v[2], v[3]); *(u32x2*)p = w; }
;   __device__ __forceinline__ void operator()(const f32x4 (&acc)[2][2][4][2], const pg8::Unit& u, int wr, int wc, int fr, int fq) const {
;     ...
;     EPI_LOOP(
;       if (pn < 4) { store_bf16x4(DQK + (size_t)row * 1024 + col, v); }
.LBB0_716:
	v_lshl_add_u64 v[136:137], v[128:129], 1, v[134:135]
	v_cvt_pk_bf16_f32 v244, v100, v101
	v_cvt_pk_bf16_f32 v245, v102, v103
	s_and_b64 vcc, exec, s[12:13]
	s_mov_b64 s[18:19], -1
	s_cbranch_vccz .LBB0_702

; __device__ __forceinline__ unsigned cvt_pk_bf16(float lo, float hi) { unsigned r; asm volatile("v_cvt_pk_bf16_f32 %0, %1, %2" : "=v"(r) : "v"(lo), "v"(hi)); return r; }
; __device__ __forceinline__ float siluf_(float v) { return v * sigmoidf_(v); }
; __device__ __forceinline__ void store_bf16x4(bf16_t* p, f32x4 v) { u32x2 w; w.x = cvt_pk_bf16(v[0], v[1]); w.y = cvt_pk_bf16(v[2], v[3]); *(u32x2*)p = w; }
;   __device__ __forceinline__ void operator()(const f32x4 (&acc)[2][2][4][2], const pg8::Unit& u, int wr, int wc, int fr, int fq) const {
;     ...
;     EPI_LOOP(
;       if (pn < 4) { store_bf16x4(DQK + (size_t)row * 1024 + col, v); }
;       else if (pn < 6) { store_bf16x4(DV + (size_t)row * 512 + (col - 1024), v); }
;       else if (pn < 10) { store_bf16x4(RV + (size_t)row * 512 + (col - 2048), v); }
;       else { f32x4 o; for (int j = 0; j < 4; ++j) o[j] = siluf_(v[j]); store_bf16x4(RG + (size_t)row * 512 + (col - 2560), o); }
.LBB0_718:
	v_lshl_add_u64 v[132:133], v[128:129], 1, v[134:135]
	v_cvt_pk_bf16_f32 v246, v96, v97
	v_cvt_pk_bf16_f32 v247, v98, v99
	s_nop 1
	v_permlane16_swap_b32_e32 v244, v246
	v_permlane16_swap_b32_e32 v245, v247
	v_lshl_add_u64 v[248:249], v[132:133], 0, v[252:253]
	global_store_dwordx4 v[248:249], v[244:247], off offset:256
.LBB0_719:
	v_or_b32_e32 v134, 32, v130
	v_ashrrev_i32_e32 v135, 31, v134
	v_lshlrev_b64 v[132:133], 10, v[134:135]
	s_and_b64 vcc, exec, s[12:13]
	s_mov_b64 s[18:19], -1
	s_cbranch_vccnz .LBB0_759
	s_and_b64 vcc, exec, s[10:11]
	s_cbranch_vccnz .LBB0_726
	s_andn2_b64 vcc, exec, s[78:79]
	s_cbranch_vccnz .LBB0_723
	v_mul_f32_e32 v136, 0xbfb8aa3b, v93
	v_mul_f32_e32 v137, 0xbfb8aa3b, v94
	v_mul_f32_e32 v152, 0xbfb8aa3b, v95
	v_exp_f32_e32 v136, v136
	v_exp_f32_e32 v137, v137
	v_exp_f32_e32 v152, v152
	v_mul_f32_e32 v131, 0xbfb8aa3b, v92
	v_exp_f32_e32 v131, v131
	v_add_f32_e32 v136, 1.0, v136
	v_add_f32_e32 v137, 1.0, v137
	v_add_f32_e32 v152, 1.0, v152
	v_rcp_f32_e32 v136, v136
	v_rcp_f32_e32 v137, v137
	v_rcp_f32_e32 v152, v152
	v_add_f32_e32 v131, 1.0, v131
	v_rcp_f32_e32 v131, v131
	v_mul_f32_e32 v154, v93, v136
	v_mul_f32_e32 v155, v94, v137
	v_mul_f32_e32 v156, v95, v152
	v_lshl_add_u64 v[136:137], s[46:47], 0, v[132:133]
	v_mov_b32_e32 v152, v128
	v_mov_b32_e32 v153, v144
	v_lshl_add_u64 v[136:137], v[152:153], 1, v[136:137]
	v_add_co_u32_e32 v136, vcc, 0xfffff000, v136
	s_mov_b64 s[18:19], 0
	s_nop 0
	v_addc_co_u32_e32 v137, vcc, -1, v137, vcc
	v_mul_f32_e32 v131, v92, v131
	v_cvt_pk_bf16_f32 v244, v131, v154
	v_cvt_pk_bf16_f32 v245, v155, v156
.LBB0_723:
	s_andn2_b64 vcc, exec, s[18:19]
	s_cbranch_vccnz .LBB0_725
	v_lshl_add_u64 v[136:137], s[48:49], 0, v[132:133]
	v_mov_b32_e32 v152, v128
	v_mov_b32_e32 v153, v144
	v_lshl_add_u64 v[136:137], v[152:153], 1, v[136:137]
	v_cvt_pk_bf16_f32 v244, v92, v93
	v_cvt_pk_bf16_f32 v245, v94, v95

; __device__ __forceinline__ unsigned cvt_pk_bf16(float lo, float hi) { unsigned r; asm volatile("v_cvt_pk_bf16_f32 %0, %1, %2" : "=v"(r) : "v"(lo), "v"(hi)); return r; }
; __device__ __forceinline__ void store_bf16x4(bf16_t* p, f32x4 v) { u32x2 w; w.x = cvt_pk_bf16(v[0], v[1]); w.y = cvt_pk_bf16(v[2], v[3]); *(u32x2*)p = w; }
;   __device__ __forceinline__ void operator()(const f32x4 (&acc)[2][2][4][2], const pg8::Unit& u, int wr, int wc, int fr, int fq) const {
;     ...
;     EPI_LOOP(
;       if (pn < 4) { store_bf16x4(DQK + (size_t)row * 1024 + col, v); }
;       else if (pn < 6) { store_bf16x4(DV + (size_t)row * 512 + (col - 1024), v); }
.LBB0_726:
	s_andn2_b64 vcc, exec, s[18:19]
	s_cbranch_vccnz .LBB0_728
	v_lshl_add_u64 v[136:137], s[90:91], 0, v[132:133]
	v_mov_b32_e32 v152, v128
	v_mov_b32_e32 v153, v144
	v_lshl_add_u64 v[136:137], v[152:153], 1, v[136:137]
	v_cvt_pk_bf16_f32 v244, v92, v93
	v_cvt_pk_bf16_f32 v245, v94, v95

; __device__ __forceinline__ unsigned cvt_pk_bf16(float lo, float hi) { unsigned r; asm volatile("v_cvt_pk_bf16_f32 %0, %1, %2" : "=v"(r) : "v"(lo), "v"(hi)); return r; }
; __device__ __forceinline__ float siluf_(float v) { return v * sigmoidf_(v); }
; __device__ __forceinline__ void store_bf16x4(bf16_t* p, f32x4 v) { u32x2 w; w.x = cvt_pk_bf16(v[0], v[1]); w.y = cvt_pk_bf16(v[2], v[3]); *(u32x2*)p = w; }
;   __device__ __forceinline__ void operator()(const f32x4 (&acc)[2][2][4][2], const pg8::Unit& u, int wr, int wc, int fr, int fq) const {
;     ...
;     EPI_LOOP(
;       if (pn < 4) { store_bf16x4(DQK + (size_t)row * 1024 + col, v); }
;       else if (pn < 6) { store_bf16x4(DV + (size_t)row * 512 + (col - 1024), v); }
;       else if (pn < 10) { store_bf16x4(RV + (size_t)row * 512 + (col - 2048), v); }
;       else { f32x4 o; for (int j = 0; j < 4; ++j) o[j] = siluf_(v[j]); store_bf16x4(RG + (size_t)row * 512 + (col - 2560), o); }
.LBB0_730:
	s_and_b64 vcc, exec, s[10:11]
	s_cbranch_vccnz .LBB0_736
	s_andn2_b64 vcc, exec, s[78:79]
	s_cbranch_vccnz .LBB0_733
	v_mul_f32_e32 v136, 0xbfb8aa3b, v89
	v_mul_f32_e32 v137, 0xbfb8aa3b, v90
	v_mul_f32_e32 v152, 0xbfb8aa3b, v91
	v_exp_f32_e32 v136, v136
	v_exp_f32_e32 v137, v137
	v_exp_f32_e32 v152, v152
	v_mul_f32_e32 v131, 0xbfb8aa3b, v88
	v_exp_f32_e32 v131, v131
	v_add_f32_e32 v136, 1.0, v136
	v_add_f32_e32 v137, 1.0, v137
	v_add_f32_e32 v152, 1.0, v152
	v_rcp_f32_e32 v136, v136
	v_rcp_f32_e32 v137, v137
	v_rcp_f32_e32 v152, v152
	v_add_f32_e32 v131, 1.0, v131
	v_rcp_f32_e32 v131, v131
	v_mul_f32_e32 v154, v89, v136
	v_mul_f32_e32 v155, v90, v137
	v_mul_f32_e32 v156, v91, v152
	v_lshl_add_u64 v[136:137], s[46:47], 0, v[132:133]
	v_mov_b32_e32 v152, v128
	v_mov_b32_e32 v153, v144
	v_lshl_add_u64 v[136:137], v[152:153], 1, v[136:137]
	v_add_co_u32_e32 v136, vcc, 0xfffff000, v136
	s_mov_b64 s[18:19], 0
	s_nop 0
	v_addc_co_u32_e32 v137, vcc, -1, v137, vcc
	v_mul_f32_e32 v131, v88, v131
	v_cvt_pk_bf16_f32 v246, v131, v154
	v_cvt_pk_bf16_f32 v247, v155, v156
	s_nop 1
	v_permlane16_swap_b32_e32 v244, v246
	v_permlane16_swap_b32_e32 v245, v247
	v_lshl_add_u64 v[248:249], v[136:137], 0, v[252:253]
	global_store_dwordx4 v[248:249], v[244:247], off offset:-1024
.LBB0_733:
	s_andn2_b64 vcc, exec, s[18:19]
	s_cbranch_vccnz .LBB0_735
	v_lshl_add_u64 v[136:137], s[48:49], 0, v[132:133]
	v_mov_b32_e32 v152, v128
	v_mov_b32_e32 v153, v144
	v_lshl_add_u64 v[136:137], v[152:153], 1, v[136:137]
	v_cvt_pk_bf16_f32 v246, v88, v89
	v_cvt_pk_bf16_f32 v247, v90, v91
	s_nop 1
	v_permlane16_swap_b32_e32 v244, v246
	v_permlane16_swap_b32_e32 v245, v247
	v_lshl_add_u64 v[248:249], v[136:137], 0, v[252:253]
	global_store_dwordx4 v[248:249], v[244:247], off offset:-4096

; __device__ __forceinline__ unsigned cvt_pk_bf16(float lo, float hi) { unsigned r; asm volatile("v_cvt_pk_bf16_f32 %0, %1, %2" : "=v"(r) : "v"(lo), "v"(hi)); return r; }
; __device__ __forceinline__ void store_bf16x4(bf16_t* p, f32x4 v) { u32x2 w; w.x = cvt_pk_bf16(v[0], v[1]); w.y = cvt_pk_bf16(v[2], v[3]); *(u32x2*)p = w; }
;   __device__ __forceinline__ void operator()(const f32x4 (&acc)[2][2][4][2], const pg8::Unit& u, int wr, int wc, int fr, int fq) const {
;     ...
;     EPI_LOOP(
;       if (pn < 4) { store_bf16x4(DQK + (size_t)row * 1024 + col, v); }
;       else if (pn < 6) { store_bf16x4(DV + (size_t)row * 512 + (col - 1024), v); }
.LBB0_736:
	s_andn2_b64 vcc, exec, s[18:19]
	s_cbranch_vccnz .LBB0_738
	v_lshl_add_u64 v[136:137], s[90:91], 0, v[132:133]
	v_mov_b32_e32 v152, v128
	v_mov_b32_e32 v153, v144
	v_lshl_add_u64 v[136:137], v[152:153], 1, v[136:137]
	v_cvt_pk_bf16_f32 v246, v88, v89
	v_cvt_pk_bf16_f32 v247, v90, v91
	s_nop 1
	v_permlane16_swap_b32_e32 v244, v246
	v_permlane16_swap_b32_e32 v245, v247
	v_lshl_add_u64 v[248:249], v[136:137], 0, v[252:253]
	global_store_dwordx4 v[248:249], v[244:247], off offset:-2048

; __device__ __forceinline__ unsigned cvt_pk_bf16(float lo, float hi) { unsigned r; asm volatile("v_cvt_pk_bf16_f32 %0, %1, %2" : "=v"(r) : "v"(lo), "v"(hi)); return r; }
; __device__ __forceinline__ float siluf_(float v) { return v * sigmoidf_(v); }
; __device__ __forceinline__ void store_bf16x4(bf16_t* p, f32x4 v) { u32x2 w; w.x = cvt_pk_bf16(v[0], v[1]); w.y = cvt_pk_bf16(v[2], v[3]); *(u32x2*)p = w; }
;   __device__ __forceinline__ void operator()(const f32x4 (&acc)[2][2][4][2], const pg8::Unit& u, int wr, int wc, int fr, int fq) const {
;     ...
;     EPI_LOOP(
;       if (pn < 4) { store_bf16x4(DQK + (size_t)row * 1024 + col, v); }
;       else if (pn < 6) { store_bf16x4(DV + (size_t)row * 512 + (col - 1024), v); }
;       else if (pn < 10) { store_bf16x4(RV + (size_t)row * 512 + (col - 2048), v); }
;       else { f32x4 o; for (int j = 0; j < 4; ++j) o[j] = siluf_(v[j]); store_bf16x4(RG + (size_t)row * 512 + (col - 2560), o); }
.LBB0_740:
	s_and_b64 vcc, exec, s[10:11]
	s_cbranch_vccnz .LBB0_746
	s_andn2_b64 vcc, exec, s[78:79]
	s_cbranch_vccnz .LBB0_743
	v_mul_f32_e32 v136, 0xbfb8aa3b, v85
	v_mul_f32_e32 v137, 0xbfb8aa3b, v86
	v_mul_f32_e32 v152, 0xbfb8aa3b, v87
	v_exp_f32_e32 v136, v136
	v_exp_f32_e32 v137, v137
	v_exp_f32_e32 v152, v152
	v_mul_f32_e32 v131, 0xbfb8aa3b, v84
	v_exp_f32_e32 v131, v131
	v_add_f32_e32 v136, 1.0, v136
	v_add_f32_e32 v137, 1.0, v137
	v_add_f32_e32 v152, 1.0, v152
	v_rcp_f32_e32 v136, v136
	v_rcp_f32_e32 v137, v137
	v_rcp_f32_e32 v152, v152
	v_add_f32_e32 v131, 1.0, v131
	v_rcp_f32_e32 v131, v131
	v_mul_f32_e32 v154, v85, v136
	v_mul_f32_e32 v155, v86, v137
	v_mul_f32_e32 v156, v87, v152
	v_lshl_add_u64 v[136:137], s[46:47], 0, v[132:133]
	v_mov_b32_e32 v152, v128
	v_mov_b32_e32 v153, v144
	v_lshl_add_u64 v[136:137], v[152:153], 1, v[136:137]
	v_add_co_u32_e32 v136, vcc, 0xfffff000, v136
	s_mov_b64 s[18:19], 0
	s_nop 0
	v_addc_co_u32_e32 v137, vcc, -1, v137, vcc
	v_mul_f32_e32 v131, v84, v131
	v_cvt_pk_bf16_f32 v244, v131, v154
	v_cvt_pk_bf16_f32 v245, v155, v156
.LBB0_743:
	s_andn2_b64 vcc, exec, s[18:19]
	s_cbranch_vccnz .LBB0_745
	v_lshl_add_u64 v[136:137], s[48:49], 0, v[132:133]
	v_mov_b32_e32 v152, v128
	v_mov_b32_e32 v153, v144
	v_lshl_add_u64 v[136:137], v[152:153], 1, v[136:137]
	v_cvt_pk_bf16_f32 v244, v84, v85
	v_cvt_pk_bf16_f32 v245, v86, v87

; __device__ __forceinline__ unsigned cvt_pk_bf16(float lo, float hi) { unsigned r; asm volatile("v_cvt_pk_bf16_f32 %0, %1, %2" : "=v"(r) : "v"(lo), "v"(hi)); return r; }
; __device__ __forceinline__ void store_bf16x4(bf16_t* p, f32x4 v) { u32x2 w; w.x = cvt_pk_bf16(v[0], v[1]); w.y = cvt_pk_bf16(v[2], v[3]); *(u32x2*)p = w; }
;   __device__ __forceinline__ void operator()(const f32x4 (&acc)[2][2][4][2], const pg8::Unit& u, int wr, int wc, int fr, int fq) const {
;     ...
;     EPI_LOOP(
;       if (pn < 4) { store_bf16x4(DQK + (size_t)row * 1024 + col, v); }
;       else if (pn < 6) { store_bf16x4(DV + (size_t)row * 512 + (col - 1024), v); }
.LBB0_746:
	s_andn2_b64 vcc, exec, s[18:19]
	s_cbranch_vccnz .LBB0_748
	v_lshl_add_u64 v[136:137], s[90:91], 0, v[132:133]
	v_mov_b32_e32 v152, v128
	v_mov_b32_e32 v153, v144
	v_lshl_add_u64 v[136:137], v[152:153], 1, v[136:137]
	v_cvt_pk_bf16_f32 v244, v84, v85
	v_cvt_pk_bf16_f32 v245, v86, v87

; __device__ __forceinline__ unsigned cvt_pk_bf16(float lo, float hi) { unsigned r; asm volatile("v_cvt_pk_bf16_f32 %0, %1, %2" : "=v"(r) : "v"(lo), "v"(hi)); return r; }
; __device__ __forceinline__ float siluf_(float v) { return v * sigmoidf_(v); }
; __device__ __forceinline__ void store_bf16x4(bf16_t* p, f32x4 v) { u32x2 w; w.x = cvt_pk_bf16(v[0], v[1]); w.y = cvt_pk_bf16(v[2], v[3]); *(u32x2*)p = w; }
;   __device__ __forceinline__ void operator()(const f32x4 (&acc)[2][2][4][2], const pg8::Unit& u, int wr, int wc, int fr, int fq) const {
;     ...
;     EPI_LOOP(
;       if (pn < 4) { store_bf16x4(DQK + (size_t)row * 1024 + col, v); }
;       else if (pn < 6) { store_bf16x4(DV + (size_t)row * 512 + (col - 1024), v); }
;       else if (pn < 10) { store_bf16x4(RV + (size_t)row * 512 + (col - 2048), v); }
;       else { f32x4 o; for (int j = 0; j < 4; ++j) o[j] = siluf_(v[j]); store_bf16x4(RG + (size_t)row * 512 + (col - 2560), o); }
.LBB0_750:
	s_and_b64 vcc, exec, s[10:11]
	s_cbranch_vccnz .LBB0_756
	s_andn2_b64 vcc, exec, s[78:79]
	s_cbranch_vccnz .LBB0_753
	v_mul_f32_e32 v136, 0xbfb8aa3b, v81
	v_mul_f32_e32 v137, 0xbfb8aa3b, v82
	v_mul_f32_e32 v152, 0xbfb8aa3b, v83
	v_exp_f32_e32 v136, v136
	v_exp_f32_e32 v137, v137
	v_exp_f32_e32 v152, v152
	v_mul_f32_e32 v131, 0xbfb8aa3b, v80
	v_exp_f32_e32 v131, v131
	v_add_f32_e32 v136, 1.0, v136
	v_add_f32_e32 v137, 1.0, v137
	v_add_f32_e32 v152, 1.0, v152
	v_rcp_f32_e32 v136, v136
	v_rcp_f32_e32 v137, v137
	v_rcp_f32_e32 v152, v152
	v_add_f32_e32 v131, 1.0, v131
	v_rcp_f32_e32 v131, v131
	v_mul_f32_e32 v154, v81, v136
	v_mul_f32_e32 v155, v82, v137
	v_mul_f32_e32 v156, v83, v152
	v_lshl_add_u64 v[136:137], s[46:47], 0, v[132:133]
	v_mov_b32_e32 v152, v128
	v_mov_b32_e32 v153, v144
	v_lshl_add_u64 v[136:137], v[152:153], 1, v[136:137]
	v_add_co_u32_e32 v136, vcc, 0xfffff000, v136
	s_mov_b64 s[18:19], 0
	s_nop 0
	v_addc_co_u32_e32 v137, vcc, -1, v137, vcc
	v_mul_f32_e32 v131, v80, v131
	v_cvt_pk_bf16_f32 v246, v131, v154
	v_cvt_pk_bf16_f32 v247, v155, v156
	s_nop 1
	v_permlane16_swap_b32_e32 v244, v246
	v_permlane16_swap_b32_e32 v245, v247
	v_lshl_add_u64 v[248:249], v[136:137], 0, v[252:253]
	global_store_dwordx4 v[248:249], v[244:247], off offset:-768
.LBB0_753:
	s_andn2_b64 vcc, exec, s[18:19]
	s_cbranch_vccnz .LBB0_755
	v_lshl_add_u64 v[136:137], s[48:49], 0, v[132:133]
	v_mov_b32_e32 v152, v128
	v_mov_b32_e32 v153, v144
	v_lshl_add_u64 v[136:137], v[152:153], 1, v[136:137]
	v_cvt_pk_bf16_f32 v246, v80, v81
	v_cvt_pk_bf16_f32 v247, v82, v83
	s_nop 1
	v_permlane16_swap_b32_e32 v244, v246
	v_permlane16_swap_b32_e32 v245, v247
	v_lshl_add_u64 v[248:249], v[136:137], 0, v[252:253]
	global_store_dwordx4 v[248:249], v[244:247], off offset:-3840

; __device__ __forceinline__ unsigned cvt_pk_bf16(float lo, float hi) { unsigned r; asm volatile("v_cvt_pk_bf16_f32 %0, %1, %2" : "=v"(r) : "v"(lo), "v"(hi)); return r; }
; __device__ __forceinline__ void store_bf16x4(bf16_t* p, f32x4 v) { u32x2 w; w.x = cvt_pk_bf16(v[0], v[1]); w.y = cvt_pk_bf16(v[2], v[3]); *(u32x2*)p = w; }
;   __device__ __forceinline__ void operator()(const f32x4 (&acc)[2][2][4][2], const pg8::Unit& u, int wr, int wc, int fr, int fq) const {
;     ...
;     EPI_LOOP(
;       if (pn < 4) { store_bf16x4(DQK + (size_t)row * 1024 + col, v); }
;       else if (pn < 6) { store_bf16x4(DV + (size_t)row * 512 + (col - 1024), v); }
.LBB0_756:
	s_andn2_b64 vcc, exec, s[18:19]
	s_cbranch_vccnz .LBB0_758
	v_lshl_add_u64 v[132:133], s[90:91], 0, v[132:133]
	v_mov_b32_e32 v136, v128
	v_mov_b32_e32 v137, v144
	v_lshl_add_u64 v[132:133], v[136:137], 1, v[132:133]
	v_cvt_pk_bf16_f32 v246, v80, v81
	v_cvt_pk_bf16_f32 v247, v82, v83
	s_nop 1
	v_permlane16_swap_b32_e32 v244, v246
	v_permlane16_swap_b32_e32 v245, v247
	v_lshl_add_u64 v[248:249], v[132:133], 0, v[252:253]
	global_store_dwordx4 v[248:249], v[244:247], off offset:-1792

; __device__ __forceinline__ unsigned cvt_pk_bf16(float lo, float hi) { unsigned r; asm volatile("v_cvt_pk_bf16_f32 %0, %1, %2" : "=v"(r) : "v"(lo), "v"(hi)); return r; }
; __device__ __forceinline__ void store_bf16x4(bf16_t* p, f32x4 v) { u32x2 w; w.x = cvt_pk_bf16(v[0], v[1]); w.y = cvt_pk_bf16(v[2], v[3]); *(u32x2*)p = w; }
;   __device__ __forceinline__ void operator()(const f32x4 (&acc)[2][2][4][2], const pg8::Unit& u, int wr, int wc, int fr, int fq) const {
;     ...
;     EPI_LOOP(
;       if (pn < 4) { store_bf16x4(DQK + (size_t)row * 1024 + col, v); }
.LBB0_760:
	v_lshl_add_u64 v[136:137], v[128:129], 1, v[134:135]
	v_cvt_pk_bf16_f32 v244, v92, v93
	v_cvt_pk_bf16_f32 v245, v94, v95
	s_and_b64 vcc, exec, s[12:13]
	s_mov_b64 s[18:19], -1
	s_cbranch_vccz .LBB0_730

; __device__ __forceinline__ unsigned cvt_pk_bf16(float lo, float hi) { unsigned r; asm volatile("v_cvt_pk_bf16_f32 %0, %1, %2" : "=v"(r) : "v"(lo), "v"(hi)); return r; }
; __device__ __forceinline__ void store_bf16x4(bf16_t* p, f32x4 v) { u32x2 w; w.x = cvt_pk_bf16(v[0], v[1]); w.y = cvt_pk_bf16(v[2], v[3]); *(u32x2*)p = w; }
;   __device__ __forceinline__ void operator()(const f32x4 (&acc)[2][2][4][2], const pg8::Unit& u, int wr, int wc, int fr, int fq) const {
;     ...
;     EPI_LOOP(
;       if (pn < 4) { store_bf16x4(DQK + (size_t)row * 1024 + col, v); }
.LBB0_762:
	v_lshl_add_u64 v[136:137], v[128:129], 1, v[134:135]
	v_cvt_pk_bf16_f32 v246, v88, v89
	v_cvt_pk_bf16_f32 v247, v90, v91
	s_nop 1
	v_permlane16_swap_b32_e32 v244, v246
	v_permlane16_swap_b32_e32 v245, v247
	v_lshl_add_u64 v[248:249], v[136:137], 0, v[252:253]
	global_store_dwordx4 v[248:249], v[244:247], off
	s_and_b64 vcc, exec, s[12:13]
	s_mov_b64 s[18:19], -1
	s_cbranch_vccz .LBB0_740

; __device__ __forceinline__ unsigned cvt_pk_bf16(float lo, float hi) { unsigned r; asm volatile("v_cvt_pk_bf16_f32 %0, %1, %2" : "=v"(r) : "v"(lo), "v"(hi)); return r; }
; __device__ __forceinline__ void store_bf16x4(bf16_t* p, f32x4 v) { u32x2 w; w.x = cvt_pk_bf16(v[0], v[1]); w.y = cvt_pk_bf16(v[2], v[3]); *(u32x2*)p = w; }
;   __device__ __forceinline__ void operator()(const f32x4 (&acc)[2][2][4][2], const pg8::Unit& u, int wr, int wc, int fr, int fq) const {
;     ...
;     EPI_LOOP(
;       if (pn < 4) { store_bf16x4(DQK + (size_t)row * 1024 + col, v); }
.LBB0_764:
	v_lshl_add_u64 v[136:137], v[128:129], 1, v[134:135]
	v_cvt_pk_bf16_f32 v244, v84, v85
	v_cvt_pk_bf16_f32 v245, v86, v87
	s_and_b64 vcc, exec, s[12:13]
	s_mov_b64 s[18:19], -1
	s_cbranch_vccz .LBB0_750

; __device__ __forceinline__ unsigned cvt_pk_bf16(float lo, float hi) { unsigned r; asm volatile("v_cvt_pk_bf16_f32 %0, %1, %2" : "=v"(r) : "v"(lo), "v"(hi)); return r; }
; __device__ __forceinline__ float siluf_(float v) { return v * sigmoidf_(v); }
; __device__ __forceinline__ void store_bf16x4(bf16_t* p, f32x4 v) { u32x2 w; w.x = cvt_pk_bf16(v[0], v[1]); w.y = cvt_pk_bf16(v[2], v[3]); *(u32x2*)p = w; }
;   __device__ __forceinline__ void operator()(const f32x4 (&acc)[2][2][4][2], const pg8::Unit& u, int wr, int wc, int fr, int fq) const {
;     ...
;     EPI_LOOP(
;       if (pn < 4) { store_bf16x4(DQK + (size_t)row * 1024 + col, v); }
;       else if (pn < 6) { store_bf16x4(DV + (size_t)row * 512 + (col - 1024), v); }
;       else if (pn < 10) { store_bf16x4(RV + (size_t)row * 512 + (col - 2048), v); }
;       else { f32x4 o; for (int j = 0; j < 4; ++j) o[j] = siluf_(v[j]); store_bf16x4(RG + (size_t)row * 512 + (col - 2560), o); }
.LBB0_766:
	v_lshl_add_u64 v[132:133], v[128:129], 1, v[134:135]
	v_cvt_pk_bf16_f32 v246, v80, v81
	v_cvt_pk_bf16_f32 v247, v82, v83
	s_nop 1
	v_permlane16_swap_b32_e32 v244, v246
	v_permlane16_swap_b32_e32 v245, v247
	v_lshl_add_u64 v[248:249], v[132:133], 0, v[252:253]
	global_store_dwordx4 v[248:249], v[244:247], off offset:256
.LBB0_767:
	v_or_b32_e32 v134, 48, v130
	v_ashrrev_i32_e32 v135, 31, v134
	v_lshlrev_b64 v[132:133], 10, v[134:135]
	s_and_b64 vcc, exec, s[12:13]
	s_mov_b64 s[18:19], -1
	s_cbranch_vccnz .LBB0_807
	s_and_b64 vcc, exec, s[10:11]
	s_cbranch_vccnz .LBB0_774
	s_andn2_b64 vcc, exec, s[78:79]
	s_cbranch_vccnz .LBB0_771
	v_mul_f32_e32 v136, 0xbfb8aa3b, v77
	v_mul_f32_e32 v137, 0xbfb8aa3b, v78
	v_mul_f32_e32 v152, 0xbfb8aa3b, v79
	v_exp_f32_e32 v136, v136
	v_exp_f32_e32 v137, v137
	v_exp_f32_e32 v152, v152
	v_mul_f32_e32 v131, 0xbfb8aa3b, v76
	v_exp_f32_e32 v131, v131
	v_add_f32_e32 v136, 1.0, v136
	v_add_f32_e32 v137, 1.0, v137
	v_add_f32_e32 v152, 1.0, v152
	v_rcp_f32_e32 v136, v136
	v_rcp_f32_e32 v137, v137
	v_rcp_f32_e32 v152, v152
	v_add_f32_e32 v131, 1.0, v131
	v_rcp_f32_e32 v131, v131
	v_mul_f32_e32 v154, v77, v136
	v_mul_f32_e32 v155, v78, v137
	v_mul_f32_e32 v156, v79, v152
	v_lshl_add_u64 v[136:137], s[46:47], 0, v[132:133]
	v_mov_b32_e32 v152, v128
	v_mov_b32_e32 v153, v144
	v_lshl_add_u64 v[136:137], v[152:153], 1, v[136:137]
	v_add_co_u32_e32 v136, vcc, 0xfffff000, v136
	s_mov_b64 s[18:19], 0
	s_nop 0
	v_addc_co_u32_e32 v137, vcc, -1, v137, vcc
	v_mul_f32_e32 v131, v76, v131
	v_cvt_pk_bf16_f32 v244, v131, v154
	v_cvt_pk_bf16_f32 v245, v155, v156
.LBB0_771:
	s_andn2_b64 vcc, exec, s[18:19]
	s_cbranch_vccnz .LBB0_773
	v_lshl_add_u64 v[136:137], s[48:49], 0, v[132:133]
	v_mov_b32_e32 v152, v128
	v_mov_b32_e32 v153, v144
	v_lshl_add_u64 v[136:137], v[152:153], 1, v[136:137]
	v_cvt_pk_bf16_f32 v244, v76, v77
	v_cvt_pk_bf16_f32 v245, v78, v79

; __device__ __forceinline__ unsigned cvt_pk_bf16(float lo, float hi) { unsigned r; asm volatile("v_cvt_pk_bf16_f32 %0, %1, %2" : "=v"(r) : "v"(lo), "v"(hi)); return r; }
; __device__ __forceinline__ void store_bf16x4(bf16_t* p, f32x4 v) { u32x2 w; w.x = cvt_pk_bf16(v[0], v[1]); w.y = cvt_pk_bf16(v[2], v[3]); *(u32x2*)p = w; }
;   __device__ __forceinline__ void operator()(const f32x4 (&acc)[2][2][4][2], const pg8::Unit& u, int wr, int wc, int fr, int fq) const {
;     ...
;     EPI_LOOP(
;       if (pn < 4) { store_bf16x4(DQK + (size_t)row * 1024 + col, v); }
;       else if (pn < 6) { store_bf16x4(DV + (size_t)row * 512 + (col - 1024), v); }
.LBB0_774:
	s_andn2_b64 vcc, exec, s[18:19]
	s_cbranch_vccnz .LBB0_776
	v_lshl_add_u64 v[136:137], s[90:91], 0, v[132:133]
	v_mov_b32_e32 v152, v128
	v_mov_b32_e32 v153, v144
	v_lshl_add_u64 v[136:137], v[152:153], 1, v[136:137]
	v_cvt_pk_bf16_f32 v244, v76, v77
	v_cvt_pk_bf16_f32 v245, v78, v79

; __device__ __forceinline__ unsigned cvt_pk_bf16(float lo, float hi) { unsigned r; asm volatile("v_cvt_pk_bf16_f32 %0, %1, %2" : "=v"(r) : "v"(lo), "v"(hi)); return r; }
; __device__ __forceinline__ float siluf_(float v) { return v * sigmoidf_(v); }
; __device__ __forceinline__ void store_bf16x4(bf16_t* p, f32x4 v) { u32x2 w; w.x = cvt_pk_bf16(v[0], v[1]); w.y = cvt_pk_bf16(v[2], v[3]); *(u32x2*)p = w; }
;   __device__ __forceinline__ void operator()(const f32x4 (&acc)[2][2][4][2], const pg8::Unit& u, int wr, int wc, int fr, int fq) const {
;     ...
;     EPI_LOOP(
;       if (pn < 4) { store_bf16x4(DQK + (size_t)row * 1024 + col, v); }
;       else if (pn < 6) { store_bf16x4(DV + (size_t)row * 512 + (col - 1024), v); }
;       else if (pn < 10) { store_bf16x4(RV + (size_t)row * 512 + (col - 2048), v); }
;       else { f32x4 o; for (int j = 0; j < 4; ++j) o[j] = siluf_(v[j]); store_bf16x4(RG + (size_t)row * 512 + (col - 2560), o); }
.LBB0_778:
	s_and_b64 vcc, exec, s[10:11]
	s_cbranch_vccnz .LBB0_784
	s_andn2_b64 vcc, exec, s[78:79]
	s_cbranch_vccnz .LBB0_781
	v_mul_f32_e32 v136, 0xbfb8aa3b, v73
	v_mul_f32_e32 v137, 0xbfb8aa3b, v74
	v_mul_f32_e32 v152, 0xbfb8aa3b, v75
	v_exp_f32_e32 v136, v136
	v_exp_f32_e32 v137, v137
	v_exp_f32_e32 v152, v152
	v_mul_f32_e32 v131, 0xbfb8aa3b, v72
	v_exp_f32_e32 v131, v131
	v_add_f32_e32 v136, 1.0, v136
	v_add_f32_e32 v137, 1.0, v137
	v_add_f32_e32 v152, 1.0, v152
	v_rcp_f32_e32 v136, v136
	v_rcp_f32_e32 v137, v137
	v_rcp_f32_e32 v152, v152
	v_add_f32_e32 v131, 1.0, v131
	v_rcp_f32_e32 v131, v131
	v_mul_f32_e32 v154, v73, v136
	v_mul_f32_e32 v155, v74, v137
	v_mul_f32_e32 v156, v75, v152
	v_lshl_add_u64 v[136:137], s[46:47], 0, v[132:133]
	v_mov_b32_e32 v152, v128
	v_mov_b32_e32 v153, v144
	v_lshl_add_u64 v[136:137], v[152:153], 1, v[136:137]
	v_add_co_u32_e32 v136, vcc, 0xfffff000, v136
	s_mov_b64 s[18:19], 0
	s_nop 0
	v_addc_co_u32_e32 v137, vcc, -1, v137, vcc
	v_mul_f32_e32 v131, v72, v131
	v_cvt_pk_bf16_f32 v246, v131, v154
	v_cvt_pk_bf16_f32 v247, v155, v156
	s_nop 1
	v_permlane16_swap_b32_e32 v244, v246
	v_permlane16_swap_b32_e32 v245, v247
	v_lshl_add_u64 v[248:249], v[136:137], 0, v[252:253]
	global_store_dwordx4 v[248:249], v[244:247], off offset:-1024
.LBB0_781:
	s_andn2_b64 vcc, exec, s[18:19]
	s_cbranch_vccnz .LBB0_783
	v_lshl_add_u64 v[136:137], s[48:49], 0, v[132:133]
	v_mov_b32_e32 v152, v128
	v_mov_b32_e32 v153, v144
	v_lshl_add_u64 v[136:137], v[152:153], 1, v[136:137]
	v_cvt_pk_bf16_f32 v246, v72, v73
	v_cvt_pk_bf16_f32 v247, v74, v75
	s_nop 1
	v_permlane16_swap_b32_e32 v244, v246
	v_permlane16_swap_b32_e32 v245, v247
	v_lshl_add_u64 v[248:249], v[136:137], 0, v[252:253]
	global_store_dwordx4 v[248:249], v[244:247], off offset:-4096

; __device__ __forceinline__ unsigned cvt_pk_bf16(float lo, float hi) { unsigned r; asm volatile("v_cvt_pk_bf16_f32 %0, %1, %2" : "=v"(r) : "v"(lo), "v"(hi)); return r; }
; __device__ __forceinline__ void store_bf16x4(bf16_t* p, f32x4 v) { u32x2 w; w.x = cvt_pk_bf16(v[0], v[1]); w.y = cvt_pk_bf16(v[2], v[3]); *(u32x2*)p = w; }
;   __device__ __forceinline__ void operator()(const f32x4 (&acc)[2][2][4][2], const pg8::Unit& u, int wr, int wc, int fr, int fq) const {
;     ...
;     EPI_LOOP(
;       if (pn < 4) { store_bf16x4(DQK + (size_t)row * 1024 + col, v); }
;       else if (pn < 6) { store_bf16x4(DV + (size_t)row * 512 + (col - 1024), v); }
.LBB0_784:
	s_andn2_b64 vcc, exec, s[18:19]
	s_cbranch_vccnz .LBB0_786
	v_lshl_add_u64 v[136:137], s[90:91], 0, v[132:133]
	v_mov_b32_e32 v152, v128
	v_mov_b32_e32 v153, v144
	v_lshl_add_u64 v[136:137], v[152:153], 1, v[136:137]
	v_cvt_pk_bf16_f32 v246, v72, v73
	v_cvt_pk_bf16_f32 v247, v74, v75
	s_nop 1
	v_permlane16_swap_b32_e32 v244, v246
	v_permlane16_swap_b32_e32 v245, v247
	v_lshl_add_u64 v[248:249], v[136:137], 0, v[252:253]
	global_store_dwordx4 v[248:249], v[244:247], off offset:-2048

; __device__ __forceinline__ unsigned cvt_pk_bf16(float lo, float hi) { unsigned r; asm volatile("v_cvt_pk_bf16_f32 %0, %1, %2" : "=v"(r) : "v"(lo), "v"(hi)); return r; }
; __device__ __forceinline__ float siluf_(float v) { return v * sigmoidf_(v); }
; __device__ __forceinline__ void store_bf16x4(bf16_t* p, f32x4 v) { u32x2 w; w.x = cvt_pk_bf16(v[0], v[1]); w.y = cvt_pk_bf16(v[2], v[3]); *(u32x2*)p = w; }
;   __device__ __forceinline__ void operator()(const f32x4 (&acc)[2][2][4][2], const pg8::Unit& u, int wr, int wc, int fr, int fq) const {
;     ...
;     EPI_LOOP(
;       if (pn < 4) { store_bf16x4(DQK + (size_t)row * 1024 + col, v); }
;       else if (pn < 6) { store_bf16x4(DV + (size_t)row * 512 + (col - 1024), v); }
;       else if (pn < 10) { store_bf16x4(RV + (size_t)row * 512 + (col - 2048), v); }
;       else { f32x4 o; for (int j = 0; j < 4; ++j) o[j] = siluf_(v[j]); store_bf16x4(RG + (size_t)row * 512 + (col - 2560), o); }
.LBB0_788:
	s_and_b64 vcc, exec, s[10:11]
	s_cbranch_vccnz .LBB0_794
	s_andn2_b64 vcc, exec, s[78:79]
	s_cbranch_vccnz .LBB0_791
	v_mul_f32_e32 v136, 0xbfb8aa3b, v69
	v_mul_f32_e32 v137, 0xbfb8aa3b, v70
	v_mul_f32_e32 v152, 0xbfb8aa3b, v71
	v_exp_f32_e32 v136, v136
	v_exp_f32_e32 v137, v137
	v_exp_f32_e32 v152, v152
	v_mul_f32_e32 v131, 0xbfb8aa3b, v68
	v_exp_f32_e32 v131, v131
	v_add_f32_e32 v136, 1.0, v136
	v_add_f32_e32 v137, 1.0, v137
	v_add_f32_e32 v152, 1.0, v152
	v_rcp_f32_e32 v136, v136
	v_rcp_f32_e32 v137, v137
	v_rcp_f32_e32 v152, v152
	v_add_f32_e32 v131, 1.0, v131
	v_rcp_f32_e32 v131, v131
	v_mul_f32_e32 v154, v69, v136
	v_mul_f32_e32 v155, v70, v137
	v_mul_f32_e32 v156, v71, v152
	v_lshl_add_u64 v[136:137], s[46:47], 0, v[132:133]
	v_mov_b32_e32 v152, v128
	v_mov_b32_e32 v153, v144
	v_lshl_add_u64 v[136:137], v[152:153], 1, v[136:137]
	v_add_co_u32_e32 v136, vcc, 0xfffff000, v136
	s_mov_b64 s[18:19], 0
	s_nop 0
	v_addc_co_u32_e32 v137, vcc, -1, v137, vcc
	v_mul_f32_e32 v131, v68, v131
	v_cvt_pk_bf16_f32 v244, v131, v154
	v_cvt_pk_bf16_f32 v245, v155, v156
.LBB0_791:
	s_andn2_b64 vcc, exec, s[18:19]
	s_cbranch_vccnz .LBB0_793
	v_lshl_add_u64 v[136:137], s[48:49], 0, v[132:133]
	v_mov_b32_e32 v152, v128
	v_mov_b32_e32 v153, v144
	v_lshl_add_u64 v[136:137], v[152:153], 1, v[136:137]
	v_cvt_pk_bf16_f32 v244, v68, v69
	v_cvt_pk_bf16_f32 v245, v70, v71

; __device__ __forceinline__ unsigned cvt_pk_bf16(float lo, float hi) { unsigned r; asm volatile("v_cvt_pk_bf16_f32 %0, %1, %2" : "=v"(r) : "v"(lo), "v"(hi)); return r; }
; __device__ __forceinline__ void store_bf16x4(bf16_t* p, f32x4 v) { u32x2 w; w.x = cvt_pk_bf16(v[0], v[1]); w.y = cvt_pk_bf16(v[2], v[3]); *(u32x2*)p = w; }
;   __device__ __forceinline__ void operator()(const f32x4 (&acc)[2][2][4][2], const pg8::Unit& u, int wr, int wc, int fr, int fq) const {
;     ...
;     EPI_LOOP(
;       if (pn < 4) { store_bf16x4(DQK + (size_t)row * 1024 + col, v); }
;       else if (pn < 6) { store_bf16x4(DV + (size_t)row * 512 + (col - 1024), v); }
.LBB0_794:
	s_andn2_b64 vcc, exec, s[18:19]
	s_cbranch_vccnz .LBB0_796
	v_lshl_add_u64 v[136:137], s[90:91], 0, v[132:133]
	v_mov_b32_e32 v152, v128
	v_mov_b32_e32 v153, v144
	v_lshl_add_u64 v[136:137], v[152:153], 1, v[136:137]
	v_cvt_pk_bf16_f32 v244, v68, v69
	v_cvt_pk_bf16_f32 v245, v70, v71

; __device__ __forceinline__ unsigned cvt_pk_bf16(float lo, float hi) { unsigned r; asm volatile("v_cvt_pk_bf16_f32 %0, %1, %2" : "=v"(r) : "v"(lo), "v"(hi)); return r; }
; __device__ __forceinline__ float siluf_(float v) { return v * sigmoidf_(v); }
; __device__ __forceinline__ void store_bf16x4(bf16_t* p, f32x4 v) { u32x2 w; w.x = cvt_pk_bf16(v[0], v[1]); w.y = cvt_pk_bf16(v[2], v[3]); *(u32x2*)p = w; }
;   __device__ __forceinline__ void operator()(const f32x4 (&acc)[2][2][4][2], const pg8::Unit& u, int wr, int wc, int fr, int fq) const {
;     ...
;     EPI_LOOP(
;       if (pn < 4) { store_bf16x4(DQK + (size_t)row * 1024 + col, v); }
;       else if (pn < 6) { store_bf16x4(DV + (size_t)row * 512 + (col - 1024), v); }
;       else if (pn < 10) { store_bf16x4(RV + (size_t)row * 512 + (col - 2048), v); }
;       else { f32x4 o; for (int j = 0; j < 4; ++j) o[j] = siluf_(v[j]); store_bf16x4(RG + (size_t)row * 512 + (col - 2560), o); }
.LBB0_798:
	s_and_b64 vcc, exec, s[10:11]
	s_cbranch_vccnz .LBB0_804
	s_andn2_b64 vcc, exec, s[78:79]
	s_cbranch_vccnz .LBB0_801
	v_mul_f32_e32 v136, 0xbfb8aa3b, v65
	v_mul_f32_e32 v137, 0xbfb8aa3b, v66
	v_mul_f32_e32 v152, 0xbfb8aa3b, v67
	v_exp_f32_e32 v136, v136
	v_exp_f32_e32 v137, v137
	v_exp_f32_e32 v152, v152
	v_mul_f32_e32 v131, 0xbfb8aa3b, v64
	v_exp_f32_e32 v131, v131
	v_add_f32_e32 v136, 1.0, v136
	v_add_f32_e32 v137, 1.0, v137
	v_add_f32_e32 v152, 1.0, v152
	v_rcp_f32_e32 v136, v136
	v_rcp_f32_e32 v137, v137
	v_rcp_f32_e32 v152, v152
	v_add_f32_e32 v131, 1.0, v131
	v_rcp_f32_e32 v131, v131
	v_mul_f32_e32 v154, v65, v136
	v_mul_f32_e32 v155, v66, v137
	v_mul_f32_e32 v156, v67, v152
	v_lshl_add_u64 v[136:137], s[46:47], 0, v[132:133]
	v_mov_b32_e32 v152, v128
	v_mov_b32_e32 v153, v144
	v_lshl_add_u64 v[136:137], v[152:153], 1, v[136:137]
	v_add_co_u32_e32 v136, vcc, 0xfffff000, v136
	s_mov_b64 s[18:19], 0
	s_nop 0
	v_addc_co_u32_e32 v137, vcc, -1, v137, vcc
	v_mul_f32_e32 v131, v64, v131
	v_cvt_pk_bf16_f32 v246, v131, v154
	v_cvt_pk_bf16_f32 v247, v155, v156
	s_nop 1
	v_permlane16_swap_b32_e32 v244, v246
	v_permlane16_swap_b32_e32 v245, v247
	v_lshl_add_u64 v[248:249], v[136:137], 0, v[252:253]
	global_store_dwordx4 v[248:249], v[244:247], off offset:-768
.LBB0_801:
	s_andn2_b64 vcc, exec, s[18:19]
	s_cbranch_vccnz .LBB0_803
	v_lshl_add_u64 v[136:137], s[48:49], 0, v[132:133]
	v_mov_b32_e32 v152, v128
	v_mov_b32_e32 v153, v144
	v_lshl_add_u64 v[136:137], v[152:153], 1, v[136:137]
	v_cvt_pk_bf16_f32 v246, v64, v65
	v_cvt_pk_bf16_f32 v247, v66, v67
	s_nop 1
	v_permlane16_swap_b32_e32 v244, v246
	v_permlane16_swap_b32_e32 v245, v247
	v_lshl_add_u64 v[248:249], v[136:137], 0, v[252:253]
	global_store_dwordx4 v[248:249], v[244:247], off offset:-3840

; __device__ __forceinline__ unsigned cvt_pk_bf16(float lo, float hi) { unsigned r; asm volatile("v_cvt_pk_bf16_f32 %0, %1, %2" : "=v"(r) : "v"(lo), "v"(hi)); return r; }
; __device__ __forceinline__ void store_bf16x4(bf16_t* p, f32x4 v) { u32x2 w; w.x = cvt_pk_bf16(v[0], v[1]); w.y = cvt_pk_bf16(v[2], v[3]); *(u32x2*)p = w; }
;   __device__ __forceinline__ void operator()(const f32x4 (&acc)[2][2][4][2], const pg8::Unit& u, int wr, int wc, int fr, int fq) const {
;     ...
;     EPI_LOOP(
;       if (pn < 4) { store_bf16x4(DQK + (size_t)row * 1024 + col, v); }
;       else if (pn < 6) { store_bf16x4(DV + (size_t)row * 512 + (col - 1024), v); }
.LBB0_804:
	s_andn2_b64 vcc, exec, s[18:19]
	s_cbranch_vccnz .LBB0_806
	v_lshl_add_u64 v[132:133], s[90:91], 0, v[132:133]
	v_mov_b32_e32 v136, v128
	v_mov_b32_e32 v137, v144
	v_lshl_add_u64 v[132:133], v[136:137], 1, v[132:133]
	v_cvt_pk_bf16_f32 v246, v64, v65
	v_cvt_pk_bf16_f32 v247, v66, v67
	s_nop 1
	v_permlane16_swap_b32_e32 v244, v246
	v_permlane16_swap_b32_e32 v245, v247
	v_lshl_add_u64 v[248:249], v[132:133], 0, v[252:253]
	global_store_dwordx4 v[248:249], v[244:247], off offset:-1792

; __device__ __forceinline__ unsigned cvt_pk_bf16(float lo, float hi) { unsigned r; asm volatile("v_cvt_pk_bf16_f32 %0, %1, %2" : "=v"(r) : "v"(lo), "v"(hi)); return r; }
; __device__ __forceinline__ void store_bf16x4(bf16_t* p, f32x4 v) { u32x2 w; w.x = cvt_pk_bf16(v[0], v[1]); w.y = cvt_pk_bf16(v[2], v[3]); *(u32x2*)p = w; }
;   __device__ __forceinline__ void operator()(const f32x4 (&acc)[2][2][4][2], const pg8::Unit& u, int wr, int wc, int fr, int fq) const {
;     ...
;     EPI_LOOP(
;       if (pn < 4) { store_bf16x4(DQK + (size_t)row * 1024 + col, v); }
.LBB0_808:
	v_lshl_add_u64 v[136:137], v[128:129], 1, v[134:135]
	v_cvt_pk_bf16_f32 v244, v76, v77
	v_cvt_pk_bf16_f32 v245, v78, v79
	s_and_b64 vcc, exec, s[12:13]
	s_mov_b64 s[18:19], -1
	s_cbranch_vccz .LBB0_778

; __device__ __forceinline__ unsigned cvt_pk_bf16(float lo, float hi) { unsigned r; asm volatile("v_cvt_pk_bf16_f32 %0, %1, %2" : "=v"(r) : "v"(lo), "v"(hi)); return r; }
; __device__ __forceinline__ void store_bf16x4(bf16_t* p, f32x4 v) { u32x2 w; w.x = cvt_pk_bf16(v[0], v[1]); w.y = cvt_pk_bf16(v[2], v[3]); *(u32x2*)p = w; }
;   __device__ __forceinline__ void operator()(const f32x4 (&acc)[2][2][4][2], const pg8::Unit& u, int wr, int wc, int fr, int fq) const {
;     ...
;     EPI_LOOP(
;       if (pn < 4) { store_bf16x4(DQK + (size_t)row * 1024 + col, v); }
.LBB0_810:
	v_lshl_add_u64 v[136:137], v[128:129], 1, v[134:135]
	v_cvt_pk_bf16_f32 v246, v72, v73
	v_cvt_pk_bf16_f32 v247, v74, v75
	s_nop 1
	v_permlane16_swap_b32_e32 v244, v246
	v_permlane16_swap_b32_e32 v245, v247
	v_lshl_add_u64 v[248:249], v[136:137], 0, v[252:253]
	global_store_dwordx4 v[248:249], v[244:247], off
	s_and_b64 vcc, exec, s[12:13]
	s_mov_b64 s[18:19], -1
	s_cbranch_vccz .LBB0_788

; __device__ __forceinline__ unsigned cvt_pk_bf16(float lo, float hi) { unsigned r; asm volatile("v_cvt_pk_bf16_f32 %0, %1, %2" : "=v"(r) : "v"(lo), "v"(hi)); return r; }
; __device__ __forceinline__ void store_bf16x4(bf16_t* p, f32x4 v) { u32x2 w; w.x = cvt_pk_bf16(v[0], v[1]); w.y = cvt_pk_bf16(v[2], v[3]); *(u32x2*)p = w; }
;   __device__ __forceinline__ void operator()(const f32x4 (&acc)[2][2][4][2], const pg8::Unit& u, int wr, int wc, int fr, int fq) const {
;     ...
;     EPI_LOOP(
;       if (pn < 4) { store_bf16x4(DQK + (size_t)row * 1024 + col, v); }
.LBB0_812:
	v_lshl_add_u64 v[136:137], v[128:129], 1, v[134:135]
	v_cvt_pk_bf16_f32 v244, v68, v69
	v_cvt_pk_bf16_f32 v245, v70, v71
	s_and_b64 vcc, exec, s[12:13]
	s_mov_b64 s[18:19], -1
	s_cbranch_vccz .LBB0_798

; __device__ __forceinline__ float siluf_(float v) { return v * sigmoidf_(v); }
; __device__ __forceinline__ void store_bf16x4(bf16_t* p, f32x4 v) { u32x2 w; w.x = cvt_pk_bf16(v[0], v[1]); w.y = cvt_pk_bf16(v[2], v[3]); *(u32x2*)p = w; }
;   __device__ __forceinline__ void operator()(const f32x4 (&acc)[2][2][4][2], const pg8::Unit& u, int wr, int wc, int fr, int fq) const {
;     ...
;     EPI_LOOP(
;       if (pn < 4) { store_bf16x4(DQK + (size_t)row * 1024 + col, v); }
;       else if (pn < 6) { store_bf16x4(DV + (size_t)row * 512 + (col - 1024), v); }
;       else if (pn < 10) { store_bf16x4(RV + (size_t)row * 512 + (col - 2048), v); }
;       else { f32x4 o; for (int j = 0; j < 4; ++j) o[j] = siluf_(v[j]); store_bf16x4(RG + (size_t)row * 512 + (col - 2560), o); }
;     )
.LBB0_814:
	v_lshl_add_u64 v[132:133], v[128:129], 1, v[134:135]
	v_cvt_pk_bf16_f32 v246, v64, v65
	v_cvt_pk_bf16_f32 v247, v66, v67
	s_nop 1
	v_permlane16_swap_b32_e32 v244, v246
	v_permlane16_swap_b32_e32 v245, v247
	v_lshl_add_u64 v[248:249], v[132:133], 0, v[252:253]
	global_store_dwordx4 v[248:249], v[244:247], off offset:256
.LBB0_815:
	v_add_u32_e32 v134, 0x80, v130
	v_ashrrev_i32_e32 v135, 31, v134
	v_lshlrev_b64 v[132:133], 10, v[134:135]
	s_and_b64 vcc, exec, s[12:13]
	s_mov_b64 s[18:19], -1
	s_cbranch_vccnz .LBB0_855
	s_and_b64 vcc, exec, s[10:11]
	s_cbranch_vccnz .LBB0_822
	s_andn2_b64 vcc, exec, s[78:79]
	s_cbranch_vccnz .LBB0_819
	v_mul_f32_e32 v136, 0xbfb8aa3b, v61
	v_mul_f32_e32 v137, 0xbfb8aa3b, v62
	v_mul_f32_e32 v152, 0xbfb8aa3b, v63
	v_exp_f32_e32 v136, v136
	v_exp_f32_e32 v137, v137
	v_exp_f32_e32 v152, v152
	v_mul_f32_e32 v131, 0xbfb8aa3b, v60
	v_exp_f32_e32 v131, v131
	v_add_f32_e32 v136, 1.0, v136
	v_add_f32_e32 v137, 1.0, v137
	v_add_f32_e32 v152, 1.0, v152
	v_rcp_f32_e32 v136, v136
	v_rcp_f32_e32 v137, v137
	v_rcp_f32_e32 v152, v152
	v_add_f32_e32 v131, 1.0, v131
	v_rcp_f32_e32 v131, v131
	v_mul_f32_e32 v154, v61, v136
	v_mul_f32_e32 v155, v62, v137
	v_mul_f32_e32 v156, v63, v152
	v_lshl_add_u64 v[136:137], s[46:47], 0, v[132:133]
	v_mov_b32_e32 v152, v128
	v_mov_b32_e32 v153, v144
	v_lshl_add_u64 v[136:137], v[152:153], 1, v[136:137]
	v_add_co_u32_e32 v136, vcc, 0xfffff000, v136
	s_mov_b64 s[18:19], 0
	s_nop 0
	v_addc_co_u32_e32 v137, vcc, -1, v137, vcc
	v_mul_f32_e32 v131, v60, v131
	v_cvt_pk_bf16_f32 v244, v131, v154
	v_cvt_pk_bf16_f32 v245, v155, v156
.LBB0_819:
	s_andn2_b64 vcc, exec, s[18:19]
	s_cbranch_vccnz .LBB0_821
	v_lshl_add_u64 v[136:137], s[48:49], 0, v[132:133]
	v_mov_b32_e32 v152, v128
	v_mov_b32_e32 v153, v144
	v_lshl_add_u64 v[136:137], v[152:153], 1, v[136:137]
	v_cvt_pk_bf16_f32 v244, v60, v61
	v_cvt_pk_bf16_f32 v245, v62, v63

; __device__ __forceinline__ void store_bf16x4(bf16_t* p, f32x4 v) { u32x2 w; w.x = cvt_pk_bf16(v[0], v[1]); w.y = cvt_pk_bf16(v[2], v[3]); *(u32x2*)p = w; }
;   __device__ __forceinline__ void operator()(const f32x4 (&acc)[2][2][4][2], const pg8::Unit& u, int wr, int wc, int fr, int fq) const {
;     ...
;       else if (pn < 6) { store_bf16x4(DV + (size_t)row * 512 + (col - 1024), v); }
.LBB0_822:
	s_andn2_b64 vcc, exec, s[18:19]
	s_cbranch_vccnz .LBB0_824
	v_lshl_add_u64 v[136:137], s[90:91], 0, v[132:133]
	v_mov_b32_e32 v152, v128
	v_mov_b32_e32 v153, v144
	v_lshl_add_u64 v[136:137], v[152:153], 1, v[136:137]
	v_cvt_pk_bf16_f32 v244, v60, v61
	v_cvt_pk_bf16_f32 v245, v62, v63

; __device__ __forceinline__ float siluf_(float v) { return v * sigmoidf_(v); }
; __device__ __forceinline__ void store_bf16x4(bf16_t* p, f32x4 v) { u32x2 w; w.x = cvt_pk_bf16(v[0], v[1]); w.y = cvt_pk_bf16(v[2], v[3]); *(u32x2*)p = w; }
;   __device__ __forceinline__ void operator()(const f32x4 (&acc)[2][2][4][2], const pg8::Unit& u, int wr, int wc, int fr, int fq) const {
;     ...
;       else if (pn < 10) { store_bf16x4(RV + (size_t)row * 512 + (col - 2048), v); }
;       else { f32x4 o; for (int j = 0; j < 4; ++j) o[j] = siluf_(v[j]); store_bf16x4(RG + (size_t)row * 512 + (col - 2560), o); }
.LBB0_826:
	s_and_b64 vcc, exec, s[10:11]
	s_cbranch_vccnz .LBB0_832
	s_andn2_b64 vcc, exec, s[78:79]
	s_cbranch_vccnz .LBB0_829
	v_mul_f32_e32 v136, 0xbfb8aa3b, v57
	v_mul_f32_e32 v137, 0xbfb8aa3b, v58
	v_mul_f32_e32 v152, 0xbfb8aa3b, v59
	v_exp_f32_e32 v136, v136
	v_exp_f32_e32 v137, v137
	v_exp_f32_e32 v152, v152
	v_mul_f32_e32 v131, 0xbfb8aa3b, v56
	v_exp_f32_e32 v131, v131
	v_add_f32_e32 v136, 1.0, v136
	v_add_f32_e32 v137, 1.0, v137
	v_add_f32_e32 v152, 1.0, v152
	v_rcp_f32_e32 v136, v136
	v_rcp_f32_e32 v137, v137
	v_rcp_f32_e32 v152, v152
	v_add_f32_e32 v131, 1.0, v131
	v_rcp_f32_e32 v131, v131
	v_mul_f32_e32 v154, v57, v136
	v_mul_f32_e32 v155, v58, v137
	v_mul_f32_e32 v156, v59, v152
	v_lshl_add_u64 v[136:137], s[46:47], 0, v[132:133]
	v_mov_b32_e32 v152, v128
	v_mov_b32_e32 v153, v144
	v_lshl_add_u64 v[136:137], v[152:153], 1, v[136:137]
	v_add_co_u32_e32 v136, vcc, 0xfffff000, v136
	s_mov_b64 s[18:19], 0
	s_nop 0
	v_addc_co_u32_e32 v137, vcc, -1, v137, vcc
	v_mul_f32_e32 v131, v56, v131
	v_cvt_pk_bf16_f32 v246, v131, v154
	v_cvt_pk_bf16_f32 v247, v155, v156
	s_nop 1
	v_permlane16_swap_b32_e32 v244, v246
	v_permlane16_swap_b32_e32 v245, v247
	v_lshl_add_u64 v[248:249], v[136:137], 0, v[252:253]
	global_store_dwordx4 v[248:249], v[244:247], off offset:-1024
.LBB0_829:
	s_andn2_b64 vcc, exec, s[18:19]
	s_cbranch_vccnz .LBB0_831
	v_lshl_add_u64 v[136:137], s[48:49], 0, v[132:133]
	v_mov_b32_e32 v152, v128
	v_mov_b32_e32 v153, v144
	v_lshl_add_u64 v[136:137], v[152:153], 1, v[136:137]
	v_cvt_pk_bf16_f32 v246, v56, v57
	v_cvt_pk_bf16_f32 v247, v58, v59
	s_nop 1
	v_permlane16_swap_b32_e32 v244, v246
	v_permlane16_swap_b32_e32 v245, v247
	v_lshl_add_u64 v[248:249], v[136:137], 0, v[252:253]
	global_store_dwordx4 v[248:249], v[244:247], off offset:-4096

; __device__ __forceinline__ void store_bf16x4(bf16_t* p, f32x4 v) { u32x2 w; w.x = cvt_pk_bf16(v[0], v[1]); w.y = cvt_pk_bf16(v[2], v[3]); *(u32x2*)p = w; }
;   __device__ __forceinline__ void operator()(const f32x4 (&acc)[2][2][4][2], const pg8::Unit& u, int wr, int wc, int fr, int fq) const {
;     ...
;       else if (pn < 6) { store_bf16x4(DV + (size_t)row * 512 + (col - 1024), v); }
.LBB0_832:
	s_andn2_b64 vcc, exec, s[18:19]
	s_cbranch_vccnz .LBB0_834
	v_lshl_add_u64 v[136:137], s[90:91], 0, v[132:133]
	v_mov_b32_e32 v152, v128
	v_mov_b32_e32 v153, v144
	v_lshl_add_u64 v[136:137], v[152:153], 1, v[136:137]
	v_cvt_pk_bf16_f32 v246, v56, v57
	v_cvt_pk_bf16_f32 v247, v58, v59
	s_nop 1
	v_permlane16_swap_b32_e32 v244, v246
	v_permlane16_swap_b32_e32 v245, v247
	v_lshl_add_u64 v[248:249], v[136:137], 0, v[252:253]
	global_store_dwordx4 v[248:249], v[244:247], off offset:-2048

; __device__ __forceinline__ float siluf_(float v) { return v * sigmoidf_(v); }
; __device__ __forceinline__ void store_bf16x4(bf16_t* p, f32x4 v) { u32x2 w; w.x = cvt_pk_bf16(v[0], v[1]); w.y = cvt_pk_bf16(v[2], v[3]); *(u32x2*)p = w; }
;   __device__ __forceinline__ void operator()(const f32x4 (&acc)[2][2][4][2], const pg8::Unit& u, int wr, int wc, int fr, int fq) const {
;     ...
;       else if (pn < 10) { store_bf16x4(RV + (size_t)row * 512 + (col - 2048), v); }
;       else { f32x4 o; for (int j = 0; j < 4; ++j) o[j] = siluf_(v[j]); store_bf16x4(RG + (size_t)row * 512 + (col - 2560), o); }
.LBB0_836:
	s_and_b64 vcc, exec, s[10:11]
	s_cbranch_vccnz .LBB0_842
	s_andn2_b64 vcc, exec, s[78:79]
	s_cbranch_vccnz .LBB0_839
	v_mul_f32_e32 v136, 0xbfb8aa3b, v53
	v_mul_f32_e32 v137, 0xbfb8aa3b, v54
	v_mul_f32_e32 v152, 0xbfb8aa3b, v55
	v_exp_f32_e32 v136, v136
	v_exp_f32_e32 v137, v137
	v_exp_f32_e32 v152, v152
	v_mul_f32_e32 v131, 0xbfb8aa3b, v52
	v_exp_f32_e32 v131, v131
	v_add_f32_e32 v136, 1.0, v136
	v_add_f32_e32 v137, 1.0, v137
	v_add_f32_e32 v152, 1.0, v152
	v_rcp_f32_e32 v136, v136
	v_rcp_f32_e32 v137, v137
	v_rcp_f32_e32 v152, v152
	v_add_f32_e32 v131, 1.0, v131
	v_rcp_f32_e32 v131, v131
	v_mul_f32_e32 v154, v53, v136
	v_mul_f32_e32 v155, v54, v137
	v_mul_f32_e32 v156, v55, v152
	v_lshl_add_u64 v[136:137], s[46:47], 0, v[132:133]
	v_mov_b32_e32 v152, v128
	v_mov_b32_e32 v153, v144
	v_lshl_add_u64 v[136:137], v[152:153], 1, v[136:137]
	v_add_co_u32_e32 v136, vcc, 0xfffff000, v136
	s_mov_b64 s[18:19], 0
	s_nop 0
	v_addc_co_u32_e32 v137, vcc, -1, v137, vcc
	v_mul_f32_e32 v131, v52, v131
	v_cvt_pk_bf16_f32 v244, v131, v154
	v_cvt_pk_bf16_f32 v245, v155, v156
.LBB0_839:
	s_andn2_b64 vcc, exec, s[18:19]
	s_cbranch_vccnz .LBB0_841
	v_lshl_add_u64 v[136:137], s[48:49], 0, v[132:133]
	v_mov_b32_e32 v152, v128
	v_mov_b32_e32 v153, v144
	v_lshl_add_u64 v[136:137], v[152:153], 1, v[136:137]
	v_cvt_pk_bf16_f32 v244, v52, v53
	v_cvt_pk_bf16_f32 v245, v54, v55

; __device__ __forceinline__ void store_bf16x4(bf16_t* p, f32x4 v) { u32x2 w; w.x = cvt_pk_bf16(v[0], v[1]); w.y = cvt_pk_bf16(v[2], v[3]); *(u32x2*)p = w; }
;   __device__ __forceinline__ void operator()(const f32x4 (&acc)[2][2][4][2], const pg8::Unit& u, int wr, int wc, int fr, int fq) const {
;     ...
;       else if (pn < 6) { store_bf16x4(DV + (size_t)row * 512 + (col - 1024), v); }
.LBB0_842:
	s_andn2_b64 vcc, exec, s[18:19]
	s_cbranch_vccnz .LBB0_844
	v_lshl_add_u64 v[136:137], s[90:91], 0, v[132:133]
	v_mov_b32_e32 v152, v128
	v_mov_b32_e32 v153, v144
	v_lshl_add_u64 v[136:137], v[152:153], 1, v[136:137]
	v_cvt_pk_bf16_f32 v244, v52, v53
	v_cvt_pk_bf16_f32 v245, v54, v55

; __device__ __forceinline__ float siluf_(float v) { return v * sigmoidf_(v); }
; __device__ __forceinline__ void store_bf16x4(bf16_t* p, f32x4 v) { u32x2 w; w.x = cvt_pk_bf16(v[0], v[1]); w.y = cvt_pk_bf16(v[2], v[3]); *(u32x2*)p = w; }
;   __device__ __forceinline__ void operator()(const f32x4 (&acc)[2][2][4][2], const pg8::Unit& u, int wr, int wc, int fr, int fq) const {
;     ...
;       else if (pn < 10) { store_bf16x4(RV + (size_t)row * 512 + (col - 2048), v); }
;       else { f32x4 o; for (int j = 0; j < 4; ++j) o[j] = siluf_(v[j]); store_bf16x4(RG + (size_t)row * 512 + (col - 2560), o); }
.LBB0_846:
	s_and_b64 vcc, exec, s[10:11]
	s_cbranch_vccnz .LBB0_852
	s_andn2_b64 vcc, exec, s[78:79]
	s_cbranch_vccnz .LBB0_849
	v_mul_f32_e32 v136, 0xbfb8aa3b, v49
	v_mul_f32_e32 v137, 0xbfb8aa3b, v50
	v_mul_f32_e32 v152, 0xbfb8aa3b, v51
	v_exp_f32_e32 v136, v136
	v_exp_f32_e32 v137, v137
	v_exp_f32_e32 v152, v152
	v_mul_f32_e32 v131, 0xbfb8aa3b, v48
	v_exp_f32_e32 v131, v131
	v_add_f32_e32 v136, 1.0, v136
	v_add_f32_e32 v137, 1.0, v137
	v_add_f32_e32 v152, 1.0, v152
	v_rcp_f32_e32 v136, v136
	v_rcp_f32_e32 v137, v137
	v_rcp_f32_e32 v152, v152
	v_add_f32_e32 v131, 1.0, v131
	v_rcp_f32_e32 v131, v131
	v_mul_f32_e32 v154, v49, v136
	v_mul_f32_e32 v155, v50, v137
	v_mul_f32_e32 v156, v51, v152
	v_lshl_add_u64 v[136:137], s[46:47], 0, v[132:133]
	v_mov_b32_e32 v152, v128
	v_mov_b32_e32 v153, v144
	v_lshl_add_u64 v[136:137], v[152:153], 1, v[136:137]
	v_add_co_u32_e32 v136, vcc, 0xfffff000, v136
	s_mov_b64 s[18:19], 0
	s_nop 0
	v_addc_co_u32_e32 v137, vcc, -1, v137, vcc
	v_mul_f32_e32 v131, v48, v131
	v_cvt_pk_bf16_f32 v246, v131, v154
	v_cvt_pk_bf16_f32 v247, v155, v156
	s_nop 1
	v_permlane16_swap_b32_e32 v244, v246
	v_permlane16_swap_b32_e32 v245, v247
	v_lshl_add_u64 v[248:249], v[136:137], 0, v[252:253]
	global_store_dwordx4 v[248:249], v[244:247], off offset:-768
.LBB0_849:
	s_andn2_b64 vcc, exec, s[18:19]
	s_cbranch_vccnz .LBB0_851
	v_lshl_add_u64 v[136:137], s[48:49], 0, v[132:133]
	v_mov_b32_e32 v152, v128
	v_mov_b32_e32 v153, v144
	v_lshl_add_u64 v[136:137], v[152:153], 1, v[136:137]
	v_cvt_pk_bf16_f32 v246, v48, v49
	v_cvt_pk_bf16_f32 v247, v50, v51
	s_nop 1
	v_permlane16_swap_b32_e32 v244, v246
	v_permlane16_swap_b32_e32 v245, v247
	v_lshl_add_u64 v[248:249], v[136:137], 0, v[252:253]
	global_store_dwordx4 v[248:249], v[244:247], off offset:-3840

; __device__ __forceinline__ void store_bf16x4(bf16_t* p, f32x4 v) { u32x2 w; w.x = cvt_pk_bf16(v[0], v[1]); w.y = cvt_pk_bf16(v[2], v[3]); *(u32x2*)p = w; }
;   __device__ __forceinline__ void operator()(const f32x4 (&acc)[2][2][4][2], const pg8::Unit& u, int wr, int wc, int fr, int fq) const {
;     ...
;       else if (pn < 6) { store_bf16x4(DV + (size_t)row * 512 + (col - 1024), v); }
.LBB0_852:
	s_andn2_b64 vcc, exec, s[18:19]
	s_cbranch_vccnz .LBB0_854
	v_lshl_add_u64 v[132:133], s[90:91], 0, v[132:133]
	v_mov_b32_e32 v136, v128
	v_mov_b32_e32 v137, v144
	v_lshl_add_u64 v[132:133], v[136:137], 1, v[132:133]
	v_cvt_pk_bf16_f32 v246, v48, v49
	v_cvt_pk_bf16_f32 v247, v50, v51
	s_nop 1
	v_permlane16_swap_b32_e32 v244, v246
	v_permlane16_swap_b32_e32 v245, v247
	v_lshl_add_u64 v[248:249], v[132:133], 0, v[252:253]
	global_store_dwordx4 v[248:249], v[244:247], off offset:-1792

; __device__ __forceinline__ void store_bf16x4(bf16_t* p, f32x4 v) { u32x2 w; w.x = cvt_pk_bf16(v[0], v[1]); w.y = cvt_pk_bf16(v[2], v[3]); *(u32x2*)p = w; }
;   __device__ __forceinline__ void operator()(const f32x4 (&acc)[2][2][4][2], const pg8::Unit& u, int wr, int wc, int fr, int fq) const {
;     ...
;       if (pn < 4) { store_bf16x4(DQK + (size_t)row * 1024 + col, v); }
.LBB0_856:
	v_lshl_add_u64 v[136:137], v[128:129], 1, v[134:135]
	v_cvt_pk_bf16_f32 v244, v60, v61
	v_cvt_pk_bf16_f32 v245, v62, v63
	s_and_b64 vcc, exec, s[12:13]
	s_mov_b64 s[18:19], -1
	s_cbranch_vccz .LBB0_826

; __device__ __forceinline__ void store_bf16x4(bf16_t* p, f32x4 v) { u32x2 w; w.x = cvt_pk_bf16(v[0], v[1]); w.y = cvt_pk_bf16(v[2], v[3]); *(u32x2*)p = w; }
;   __device__ __forceinline__ void operator()(const f32x4 (&acc)[2][2][4][2], const pg8::Unit& u, int wr, int wc, int fr, int fq) const {
;     ...
;       if (pn < 4) { store_bf16x4(DQK + (size_t)row * 1024 + col, v); }
.LBB0_858:
	v_lshl_add_u64 v[136:137], v[128:129], 1, v[134:135]
	v_cvt_pk_bf16_f32 v246, v56, v57
	v_cvt_pk_bf16_f32 v247, v58, v59
	s_nop 1
	v_permlane16_swap_b32_e32 v244, v246
	v_permlane16_swap_b32_e32 v245, v247
	v_lshl_add_u64 v[248:249], v[136:137], 0, v[252:253]
	global_store_dwordx4 v[248:249], v[244:247], off
	s_and_b64 vcc, exec, s[12:13]
	s_mov_b64 s[18:19], -1
	s_cbranch_vccz .LBB0_836

; __device__ __forceinline__ void store_bf16x4(bf16_t* p, f32x4 v) { u32x2 w; w.x = cvt_pk_bf16(v[0], v[1]); w.y = cvt_pk_bf16(v[2], v[3]); *(u32x2*)p = w; }
;   __device__ __forceinline__ void operator()(const f32x4 (&acc)[2][2][4][2], const pg8::Unit& u, int wr, int wc, int fr, int fq) const {
;     ...
;       if (pn < 4) { store_bf16x4(DQK + (size_t)row * 1024 + col, v); }
.LBB0_860:
	v_lshl_add_u64 v[136:137], v[128:129], 1, v[134:135]
	v_cvt_pk_bf16_f32 v244, v52, v53
	v_cvt_pk_bf16_f32 v245, v54, v55
	s_and_b64 vcc, exec, s[12:13]
	s_mov_b64 s[18:19], -1
	s_cbranch_vccz .LBB0_846

; __device__ __forceinline__ float siluf_(float v) { return v * sigmoidf_(v); }
; __device__ __forceinline__ void store_bf16x4(bf16_t* p, f32x4 v) { u32x2 w; w.x = cvt_pk_bf16(v[0], v[1]); w.y = cvt_pk_bf16(v[2], v[3]); *(u32x2*)p = w; }
;   __device__ __forceinline__ void operator()(const f32x4 (&acc)[2][2][4][2], const pg8::Unit& u, int wr, int wc, int fr, int fq) const {
;     ...
;       if (pn < 4) { store_bf16x4(DQK + (size_t)row * 1024 + col, v); }
;       else if (pn < 6) { store_bf16x4(DV + (size_t)row * 512 + (col - 1024), v); }
;       else if (pn < 10) { store_bf16x4(RV + (size_t)row * 512 + (col - 2048), v); }
;       else { f32x4 o; for (int j = 0; j < 4; ++j) o[j] = siluf_(v[j]); store_bf16x4(RG + (size_t)row * 512 + (col - 2560), o); }
.LBB0_862:
	v_lshl_add_u64 v[132:133], v[128:129], 1, v[134:135]
	v_cvt_pk_bf16_f32 v246, v48, v49
	v_cvt_pk_bf16_f32 v247, v50, v51
	s_nop 1
	v_permlane16_swap_b32_e32 v244, v246
	v_permlane16_swap_b32_e32 v245, v247
	v_lshl_add_u64 v[248:249], v[132:133], 0, v[252:253]
	global_store_dwordx4 v[248:249], v[244:247], off offset:256
.LBB0_863:
	v_add_u32_e32 v134, 0x90, v130
	v_ashrrev_i32_e32 v135, 31, v134
	v_lshlrev_b64 v[132:133], 10, v[134:135]
	s_and_b64 vcc, exec, s[12:13]
	s_mov_b64 s[18:19], -1
	s_cbranch_vccnz .LBB0_903
	s_and_b64 vcc, exec, s[10:11]
	s_cbranch_vccnz .LBB0_870
	s_andn2_b64 vcc, exec, s[78:79]
	s_cbranch_vccnz .LBB0_867
	v_mul_f32_e32 v136, 0xbfb8aa3b, v45
	v_mul_f32_e32 v137, 0xbfb8aa3b, v46
	v_mul_f32_e32 v152, 0xbfb8aa3b, v47
	v_exp_f32_e32 v136, v136
	v_exp_f32_e32 v137, v137
	v_exp_f32_e32 v152, v152
	v_mul_f32_e32 v131, 0xbfb8aa3b, v44
	v_exp_f32_e32 v131, v131
	v_add_f32_e32 v136, 1.0, v136
	v_add_f32_e32 v137, 1.0, v137
	v_add_f32_e32 v152, 1.0, v152
	v_rcp_f32_e32 v136, v136
	v_rcp_f32_e32 v137, v137
	v_rcp_f32_e32 v152, v152
	v_add_f32_e32 v131, 1.0, v131
	v_rcp_f32_e32 v131, v131
	v_mul_f32_e32 v154, v45, v136
	v_mul_f32_e32 v155, v46, v137
	v_mul_f32_e32 v156, v47, v152
	v_lshl_add_u64 v[136:137], s[46:47], 0, v[132:133]
	v_mov_b32_e32 v152, v128
	v_mov_b32_e32 v153, v144
	v_lshl_add_u64 v[136:137], v[152:153], 1, v[136:137]
	v_add_co_u32_e32 v136, vcc, 0xfffff000, v136
	s_mov_b64 s[18:19], 0
	s_nop 0
	v_addc_co_u32_e32 v137, vcc, -1, v137, vcc
	v_mul_f32_e32 v131, v44, v131
	v_cvt_pk_bf16_f32 v244, v131, v154
	v_cvt_pk_bf16_f32 v245, v155, v156
.LBB0_867:
	s_andn2_b64 vcc, exec, s[18:19]
	s_cbranch_vccnz .LBB0_869
	v_lshl_add_u64 v[136:137], s[48:49], 0, v[132:133]
	v_mov_b32_e32 v152, v128
	v_mov_b32_e32 v153, v144
	v_lshl_add_u64 v[136:137], v[152:153], 1, v[136:137]
	v_cvt_pk_bf16_f32 v244, v44, v45
	v_cvt_pk_bf16_f32 v245, v46, v47

; __device__ __forceinline__ void store_bf16x4(bf16_t* p, f32x4 v) { u32x2 w; w.x = cvt_pk_bf16(v[0], v[1]); w.y = cvt_pk_bf16(v[2], v[3]); *(u32x2*)p = w; }
;   __device__ __forceinline__ void operator()(const f32x4 (&acc)[2][2][4][2], const pg8::Unit& u, int wr, int wc, int fr, int fq) const {
;     ...
;       else if (pn < 6) { store_bf16x4(DV + (size_t)row * 512 + (col - 1024), v); }
.LBB0_870:
	s_andn2_b64 vcc, exec, s[18:19]
	s_cbranch_vccnz .LBB0_872
	v_lshl_add_u64 v[136:137], s[90:91], 0, v[132:133]
	v_mov_b32_e32 v152, v128
	v_mov_b32_e32 v153, v144
	v_lshl_add_u64 v[136:137], v[152:153], 1, v[136:137]
	v_cvt_pk_bf16_f32 v244, v44, v45
	v_cvt_pk_bf16_f32 v245, v46, v47

; __device__ __forceinline__ float siluf_(float v) { return v * sigmoidf_(v); }
; __device__ __forceinline__ void store_bf16x4(bf16_t* p, f32x4 v) { u32x2 w; w.x = cvt_pk_bf16(v[0], v[1]); w.y = cvt_pk_bf16(v[2], v[3]); *(u32x2*)p = w; }
;   __device__ __forceinline__ void operator()(const f32x4 (&acc)[2][2][4][2], const pg8::Unit& u, int wr, int wc, int fr, int fq) const {
;     ...
;       else if (pn < 10) { store_bf16x4(RV + (size_t)row * 512 + (col - 2048), v); }
;       else { f32x4 o; for (int j = 0; j < 4; ++j) o[j] = siluf_(v[j]); store_bf16x4(RG + (size_t)row * 512 + (col - 2560), o); }
.LBB0_874:
	s_and_b64 vcc, exec, s[10:11]
	s_cbranch_vccnz .LBB0_880
	s_andn2_b64 vcc, exec, s[78:79]
	s_cbranch_vccnz .LBB0_877
	v_mul_f32_e32 v136, 0xbfb8aa3b, v41
	v_mul_f32_e32 v137, 0xbfb8aa3b, v42
	v_mul_f32_e32 v152, 0xbfb8aa3b, v43
	v_exp_f32_e32 v136, v136
	v_exp_f32_e32 v137, v137
	v_exp_f32_e32 v152, v152
	v_mul_f32_e32 v131, 0xbfb8aa3b, v40
	v_exp_f32_e32 v131, v131
	v_add_f32_e32 v136, 1.0, v136
	v_add_f32_e32 v137, 1.0, v137
	v_add_f32_e32 v152, 1.0, v152
	v_rcp_f32_e32 v136, v136
	v_rcp_f32_e32 v137, v137
	v_rcp_f32_e32 v152, v152
	v_add_f32_e32 v131, 1.0, v131
	v_rcp_f32_e32 v131, v131
	v_mul_f32_e32 v154, v41, v136
	v_mul_f32_e32 v155, v42, v137
	v_mul_f32_e32 v156, v43, v152
	v_lshl_add_u64 v[136:137], s[46:47], 0, v[132:133]
	v_mov_b32_e32 v152, v128
	v_mov_b32_e32 v153, v144
	v_lshl_add_u64 v[136:137], v[152:153], 1, v[136:137]
	v_add_co_u32_e32 v136, vcc, 0xfffff000, v136
	s_mov_b64 s[18:19], 0
	s_nop 0
	v_addc_co_u32_e32 v137, vcc, -1, v137, vcc
	v_mul_f32_e32 v131, v40, v131
	v_cvt_pk_bf16_f32 v246, v131, v154
	v_cvt_pk_bf16_f32 v247, v155, v156
	s_nop 1
	v_permlane16_swap_b32_e32 v244, v246
	v_permlane16_swap_b32_e32 v245, v247
	v_lshl_add_u64 v[248:249], v[136:137], 0, v[252:253]
	global_store_dwordx4 v[248:249], v[244:247], off offset:-1024
.LBB0_877:
	s_andn2_b64 vcc, exec, s[18:19]
	s_cbranch_vccnz .LBB0_879
	v_lshl_add_u64 v[136:137], s[48:49], 0, v[132:133]
	v_mov_b32_e32 v152, v128
	v_mov_b32_e32 v153, v144
	v_lshl_add_u64 v[136:137], v[152:153], 1, v[136:137]
	v_cvt_pk_bf16_f32 v246, v40, v41
	v_cvt_pk_bf16_f32 v247, v42, v43
	s_nop 1
	v_permlane16_swap_b32_e32 v244, v246
	v_permlane16_swap_b32_e32 v245, v247
	v_lshl_add_u64 v[248:249], v[136:137], 0, v[252:253]
	global_store_dwordx4 v[248:249], v[244:247], off offset:-4096

; __device__ __forceinline__ void store_bf16x4(bf16_t* p, f32x4 v) { u32x2 w; w.x = cvt_pk_bf16(v[0], v[1]); w.y = cvt_pk_bf16(v[2], v[3]); *(u32x2*)p = w; }
;   __device__ __forceinline__ void operator()(const f32x4 (&acc)[2][2][4][2], const pg8::Unit& u, int wr, int wc, int fr, int fq) const {
;     ...
;       else if (pn < 6) { store_bf16x4(DV + (size_t)row * 512 + (col - 1024), v); }
.LBB0_880:
	s_andn2_b64 vcc, exec, s[18:19]
	s_cbranch_vccnz .LBB0_882
	v_lshl_add_u64 v[136:137], s[90:91], 0, v[132:133]
	v_mov_b32_e32 v152, v128
	v_mov_b32_e32 v153, v144
	v_lshl_add_u64 v[136:137], v[152:153], 1, v[136:137]
	v_cvt_pk_bf16_f32 v246, v40, v41
	v_cvt_pk_bf16_f32 v247, v42, v43
	s_nop 1
	v_permlane16_swap_b32_e32 v244, v246
	v_permlane16_swap_b32_e32 v245, v247
	v_lshl_add_u64 v[248:249], v[136:137], 0, v[252:253]
	global_store_dwordx4 v[248:249], v[244:247], off offset:-2048

; __device__ __forceinline__ float siluf_(float v) { return v * sigmoidf_(v); }
; __device__ __forceinline__ void store_bf16x4(bf16_t* p, f32x4 v) { u32x2 w; w.x = cvt_pk_bf16(v[0], v[1]); w.y = cvt_pk_bf16(v[2], v[3]); *(u32x2*)p = w; }
;   __device__ __forceinline__ void operator()(const f32x4 (&acc)[2][2][4][2], const pg8::Unit& u, int wr, int wc, int fr, int fq) const {
;     ...
;       else if (pn < 10) { store_bf16x4(RV + (size_t)row * 512 + (col - 2048), v); }
;       else { f32x4 o; for (int j = 0; j < 4; ++j) o[j] = siluf_(v[j]); store_bf16x4(RG + (size_t)row * 512 + (col - 2560), o); }
.LBB0_884:
	s_and_b64 vcc, exec, s[10:11]
	s_cbranch_vccnz .LBB0_890
	s_andn2_b64 vcc, exec, s[78:79]
	s_cbranch_vccnz .LBB0_887
	v_mul_f32_e32 v136, 0xbfb8aa3b, v37
	v_mul_f32_e32 v137, 0xbfb8aa3b, v38
	v_mul_f32_e32 v152, 0xbfb8aa3b, v39
	v_exp_f32_e32 v136, v136
	v_exp_f32_e32 v137, v137
	v_exp_f32_e32 v152, v152
	v_mul_f32_e32 v131, 0xbfb8aa3b, v36
	v_exp_f32_e32 v131, v131
	v_add_f32_e32 v136, 1.0, v136
	v_add_f32_e32 v137, 1.0, v137
	v_add_f32_e32 v152, 1.0, v152
	v_rcp_f32_e32 v136, v136
	v_rcp_f32_e32 v137, v137
	v_rcp_f32_e32 v152, v152
	v_add_f32_e32 v131, 1.0, v131
	v_rcp_f32_e32 v131, v131
	v_mul_f32_e32 v154, v37, v136
	v_mul_f32_e32 v155, v38, v137
	v_mul_f32_e32 v156, v39, v152
	v_lshl_add_u64 v[136:137], s[46:47], 0, v[132:133]
	v_mov_b32_e32 v152, v128
	v_mov_b32_e32 v153, v144
	v_lshl_add_u64 v[136:137], v[152:153], 1, v[136:137]
	v_add_co_u32_e32 v136, vcc, 0xfffff000, v136
	s_mov_b64 s[18:19], 0
	s_nop 0
	v_addc_co_u32_e32 v137, vcc, -1, v137, vcc
	v_mul_f32_e32 v131, v36, v131
	v_cvt_pk_bf16_f32 v244, v131, v154
	v_cvt_pk_bf16_f32 v245, v155, v156
.LBB0_887:
	s_andn2_b64 vcc, exec, s[18:19]
	s_cbranch_vccnz .LBB0_889
	v_lshl_add_u64 v[136:137], s[48:49], 0, v[132:133]
	v_mov_b32_e32 v152, v128
	v_mov_b32_e32 v153, v144
	v_lshl_add_u64 v[136:137], v[152:153], 1, v[136:137]
	v_cvt_pk_bf16_f32 v244, v36, v37
	v_cvt_pk_bf16_f32 v245, v38, v39

; __device__ __forceinline__ void store_bf16x4(bf16_t* p, f32x4 v) { u32x2 w; w.x = cvt_pk_bf16(v[0], v[1]); w.y = cvt_pk_bf16(v[2], v[3]); *(u32x2*)p = w; }
;   __device__ __forceinline__ void operator()(const f32x4 (&acc)[2][2][4][2], const pg8::Unit& u, int wr, int wc, int fr, int fq) const {
;     ...
;       else if (pn < 6) { store_bf16x4(DV + (size_t)row * 512 + (col - 1024), v); }
.LBB0_890:
	s_andn2_b64 vcc, exec, s[18:19]
	s_cbranch_vccnz .LBB0_892
	v_lshl_add_u64 v[136:137], s[90:91], 0, v[132:133]
	v_mov_b32_e32 v152, v128
	v_mov_b32_e32 v153, v144
	v_lshl_add_u64 v[136:137], v[152:153], 1, v[136:137]
	v_cvt_pk_bf16_f32 v244, v36, v37
	v_cvt_pk_bf16_f32 v245, v38, v39

; __device__ __forceinline__ float siluf_(float v) { return v * sigmoidf_(v); }
; __device__ __forceinline__ void store_bf16x4(bf16_t* p, f32x4 v) { u32x2 w; w.x = cvt_pk_bf16(v[0], v[1]); w.y = cvt_pk_bf16(v[2], v[3]); *(u32x2*)p = w; }
;   __device__ __forceinline__ void operator()(const f32x4 (&acc)[2][2][4][2], const pg8::Unit& u, int wr, int wc, int fr, int fq) const {
;     ...
;       else if (pn < 10) { store_bf16x4(RV + (size_t)row * 512 + (col - 2048), v); }
;       else { f32x4 o; for (int j = 0; j < 4; ++j) o[j] = siluf_(v[j]); store_bf16x4(RG + (size_t)row * 512 + (col - 2560), o); }
.LBB0_894:
	s_and_b64 vcc, exec, s[10:11]
	s_cbranch_vccnz .LBB0_900
	s_andn2_b64 vcc, exec, s[78:79]
	s_cbranch_vccnz .LBB0_897
	v_mul_f32_e32 v136, 0xbfb8aa3b, v33
	v_mul_f32_e32 v137, 0xbfb8aa3b, v34
	v_mul_f32_e32 v152, 0xbfb8aa3b, v35
	v_exp_f32_e32 v136, v136
	v_exp_f32_e32 v137, v137
	v_exp_f32_e32 v152, v152
	v_mul_f32_e32 v131, 0xbfb8aa3b, v32
	v_exp_f32_e32 v131, v131
	v_add_f32_e32 v136, 1.0, v136
	v_add_f32_e32 v137, 1.0, v137
	v_add_f32_e32 v152, 1.0, v152
	v_rcp_f32_e32 v136, v136
	v_rcp_f32_e32 v137, v137
	v_rcp_f32_e32 v152, v152
	v_add_f32_e32 v131, 1.0, v131
	v_rcp_f32_e32 v131, v131
	v_mul_f32_e32 v154, v33, v136
	v_mul_f32_e32 v155, v34, v137
	v_mul_f32_e32 v156, v35, v152
	v_lshl_add_u64 v[136:137], s[46:47], 0, v[132:133]
	v_mov_b32_e32 v152, v128
	v_mov_b32_e32 v153, v144
	v_lshl_add_u64 v[136:137], v[152:153], 1, v[136:137]
	v_add_co_u32_e32 v136, vcc, 0xfffff000, v136
	s_mov_b64 s[18:19], 0
	s_nop 0
	v_addc_co_u32_e32 v137, vcc, -1, v137, vcc
	v_mul_f32_e32 v131, v32, v131
	v_cvt_pk_bf16_f32 v246, v131, v154
	v_cvt_pk_bf16_f32 v247, v155, v156
	s_nop 1
	v_permlane16_swap_b32_e32 v244, v246
	v_permlane16_swap_b32_e32 v245, v247
	v_lshl_add_u64 v[248:249], v[136:137], 0, v[252:253]
	global_store_dwordx4 v[248:249], v[244:247], off offset:-768
.LBB0_897:
	s_andn2_b64 vcc, exec, s[18:19]
	s_cbranch_vccnz .LBB0_899
	v_lshl_add_u64 v[136:137], s[48:49], 0, v[132:133]
	v_mov_b32_e32 v152, v128
	v_mov_b32_e32 v153, v144
	v_lshl_add_u64 v[136:137], v[152:153], 1, v[136:137]
	v_cvt_pk_bf16_f32 v246, v32, v33
	v_cvt_pk_bf16_f32 v247, v34, v35
	s_nop 1
	v_permlane16_swap_b32_e32 v244, v246
	v_permlane16_swap_b32_e32 v245, v247
	v_lshl_add_u64 v[248:249], v[136:137], 0, v[252:253]
	global_store_dwordx4 v[248:249], v[244:247], off offset:-3840

; __device__ __forceinline__ void store_bf16x4(bf16_t* p, f32x4 v) { u32x2 w; w.x = cvt_pk_bf16(v[0], v[1]); w.y = cvt_pk_bf16(v[2], v[3]); *(u32x2*)p = w; }
;   __device__ __forceinline__ void operator()(const f32x4 (&acc)[2][2][4][2], const pg8::Unit& u, int wr, int wc, int fr, int fq) const {
;     ...
;       else if (pn < 6) { store_bf16x4(DV + (size_t)row * 512 + (col - 1024), v); }
.LBB0_900:
	s_andn2_b64 vcc, exec, s[18:19]
	s_cbranch_vccnz .LBB0_902
	v_lshl_add_u64 v[132:133], s[90:91], 0, v[132:133]
	v_mov_b32_e32 v136, v128
	v_mov_b32_e32 v137, v144
	v_lshl_add_u64 v[132:133], v[136:137], 1, v[132:133]
	v_cvt_pk_bf16_f32 v246, v32, v33
	v_cvt_pk_bf16_f32 v247, v34, v35
	s_nop 1
	v_permlane16_swap_b32_e32 v244, v246
	v_permlane16_swap_b32_e32 v245, v247
	v_lshl_add_u64 v[248:249], v[132:133], 0, v[252:253]
	global_store_dwordx4 v[248:249], v[244:247], off offset:-1792

; __device__ __forceinline__ void store_bf16x4(bf16_t* p, f32x4 v) { u32x2 w; w.x = cvt_pk_bf16(v[0], v[1]); w.y = cvt_pk_bf16(v[2], v[3]); *(u32x2*)p = w; }
;   __device__ __forceinline__ void operator()(const f32x4 (&acc)[2][2][4][2], const pg8::Unit& u, int wr, int wc, int fr, int fq) const {
;     ...
;       if (pn < 4) { store_bf16x4(DQK + (size_t)row * 1024 + col, v); }
.LBB0_904:
	v_lshl_add_u64 v[136:137], v[128:129], 1, v[134:135]
	v_cvt_pk_bf16_f32 v244, v44, v45
	v_cvt_pk_bf16_f32 v245, v46, v47
	s_and_b64 vcc, exec, s[12:13]
	s_mov_b64 s[18:19], -1
	s_cbranch_vccz .LBB0_874

; __device__ __forceinline__ void store_bf16x4(bf16_t* p, f32x4 v) { u32x2 w; w.x = cvt_pk_bf16(v[0], v[1]); w.y = cvt_pk_bf16(v[2], v[3]); *(u32x2*)p = w; }
;   __device__ __forceinline__ void operator()(const f32x4 (&acc)[2][2][4][2], const pg8::Unit& u, int wr, int wc, int fr, int fq) const {
;     ...
;       if (pn < 4) { store_bf16x4(DQK + (size_t)row * 1024 + col, v); }
.LBB0_906:
	v_lshl_add_u64 v[136:137], v[128:129], 1, v[134:135]
	v_cvt_pk_bf16_f32 v246, v40, v41
	v_cvt_pk_bf16_f32 v247, v42, v43
	s_nop 1
	v_permlane16_swap_b32_e32 v244, v246
	v_permlane16_swap_b32_e32 v245, v247
	v_lshl_add_u64 v[248:249], v[136:137], 0, v[252:253]
	global_store_dwordx4 v[248:249], v[244:247], off
	s_and_b64 vcc, exec, s[12:13]
	s_mov_b64 s[18:19], -1
	s_cbranch_vccz .LBB0_884

; __device__ __forceinline__ void store_bf16x4(bf16_t* p, f32x4 v) { u32x2 w; w.x = cvt_pk_bf16(v[0], v[1]); w.y = cvt_pk_bf16(v[2], v[3]); *(u32x2*)p = w; }
;   __device__ __forceinline__ void operator()(const f32x4 (&acc)[2][2][4][2], const pg8::Unit& u, int wr, int wc, int fr, int fq) const {
;     ...
;       if (pn < 4) { store_bf16x4(DQK + (size_t)row * 1024 + col, v); }
.LBB0_908:
	v_lshl_add_u64 v[136:137], v[128:129], 1, v[134:135]
	v_cvt_pk_bf16_f32 v244, v36, v37
	v_cvt_pk_bf16_f32 v245, v38, v39
	s_and_b64 vcc, exec, s[12:13]
	s_mov_b64 s[18:19], -1
	s_cbranch_vccz .LBB0_894

; __device__ __forceinline__ float siluf_(float v) { return v * sigmoidf_(v); }
; __device__ __forceinline__ void store_bf16x4(bf16_t* p, f32x4 v) { u32x2 w; w.x = cvt_pk_bf16(v[0], v[1]); w.y = cvt_pk_bf16(v[2], v[3]); *(u32x2*)p = w; }
;   __device__ __forceinline__ void operator()(const f32x4 (&acc)[2][2][4][2], const pg8::Unit& u, int wr, int wc, int fr, int fq) const {
;     ...
;       if (pn < 4) { store_bf16x4(DQK + (size_t)row * 1024 + col, v); }
;       else if (pn < 6) { store_bf16x4(DV + (size_t)row * 512 + (col - 1024), v); }
;       else if (pn < 10) { store_bf16x4(RV + (size_t)row * 512 + (col - 2048), v); }
;       else { f32x4 o; for (int j = 0; j < 4; ++j) o[j] = siluf_(v[j]); store_bf16x4(RG + (size_t)row * 512 + (col - 2560), o); }
.LBB0_910:
	v_lshl_add_u64 v[132:133], v[128:129], 1, v[134:135]
	v_cvt_pk_bf16_f32 v246, v32, v33
	v_cvt_pk_bf16_f32 v247, v34, v35
	s_nop 1
	v_permlane16_swap_b32_e32 v244, v246
	v_permlane16_swap_b32_e32 v245, v247
	v_lshl_add_u64 v[248:249], v[132:133], 0, v[252:253]
	global_store_dwordx4 v[248:249], v[244:247], off offset:256
.LBB0_911:
	v_add_u32_e32 v134, 0xa0, v130
	v_ashrrev_i32_e32 v135, 31, v134
	v_lshlrev_b64 v[132:133], 10, v[134:135]
	s_and_b64 vcc, exec, s[12:13]
	s_mov_b64 s[18:19], -1
	s_cbranch_vccnz .LBB0_951
	s_and_b64 vcc, exec, s[10:11]
	s_cbranch_vccnz .LBB0_918
	s_andn2_b64 vcc, exec, s[78:79]
	s_cbranch_vccnz .LBB0_915
	v_mul_f32_e32 v136, 0xbfb8aa3b, v29
	v_mul_f32_e32 v137, 0xbfb8aa3b, v30
	v_mul_f32_e32 v152, 0xbfb8aa3b, v31
	v_exp_f32_e32 v136, v136
	v_exp_f32_e32 v137, v137
	v_exp_f32_e32 v152, v152
	v_mul_f32_e32 v131, 0xbfb8aa3b, v28
	v_exp_f32_e32 v131, v131
	v_add_f32_e32 v136, 1.0, v136
	v_add_f32_e32 v137, 1.0, v137
	v_add_f32_e32 v152, 1.0, v152
	v_rcp_f32_e32 v136, v136
	v_rcp_f32_e32 v137, v137
	v_rcp_f32_e32 v152, v152
	v_add_f32_e32 v131, 1.0, v131
	v_rcp_f32_e32 v131, v131
	v_mul_f32_e32 v154, v29, v136
	v_mul_f32_e32 v155, v30, v137
	v_mul_f32_e32 v156, v31, v152
	v_lshl_add_u64 v[136:137], s[46:47], 0, v[132:133]
	v_mov_b32_e32 v152, v128
	v_mov_b32_e32 v153, v144
	v_lshl_add_u64 v[136:137], v[152:153], 1, v[136:137]
	v_add_co_u32_e32 v136, vcc, 0xfffff000, v136
	s_mov_b64 s[18:19], 0
	s_nop 0
	v_addc_co_u32_e32 v137, vcc, -1, v137, vcc
	v_mul_f32_e32 v131, v28, v131
	v_cvt_pk_bf16_f32 v244, v131, v154
	v_cvt_pk_bf16_f32 v245, v155, v156
.LBB0_915:
	s_andn2_b64 vcc, exec, s[18:19]
	s_cbranch_vccnz .LBB0_917
	v_lshl_add_u64 v[136:137], s[48:49], 0, v[132:133]
	v_mov_b32_e32 v152, v128
	v_mov_b32_e32 v153, v144
	v_lshl_add_u64 v[136:137], v[152:153], 1, v[136:137]
	v_cvt_pk_bf16_f32 v244, v28, v29
	v_cvt_pk_bf16_f32 v245, v30, v31

; __device__ __forceinline__ void store_bf16x4(bf16_t* p, f32x4 v) { u32x2 w; w.x = cvt_pk_bf16(v[0], v[1]); w.y = cvt_pk_bf16(v[2], v[3]); *(u32x2*)p = w; }
;   __device__ __forceinline__ void operator()(const f32x4 (&acc)[2][2][4][2], const pg8::Unit& u, int wr, int wc, int fr, int fq) const {
;     ...
;       else if (pn < 6) { store_bf16x4(DV + (size_t)row * 512 + (col - 1024), v); }
.LBB0_918:
	s_andn2_b64 vcc, exec, s[18:19]
	s_cbranch_vccnz .LBB0_920
	v_lshl_add_u64 v[136:137], s[90:91], 0, v[132:133]
	v_mov_b32_e32 v152, v128
	v_mov_b32_e32 v153, v144
	v_lshl_add_u64 v[136:137], v[152:153], 1, v[136:137]
	v_cvt_pk_bf16_f32 v244, v28, v29
	v_cvt_pk_bf16_f32 v245, v30, v31

; __device__ __forceinline__ float siluf_(float v) { return v * sigmoidf_(v); }
; __device__ __forceinline__ void store_bf16x4(bf16_t* p, f32x4 v) { u32x2 w; w.x = cvt_pk_bf16(v[0], v[1]); w.y = cvt_pk_bf16(v[2], v[3]); *(u32x2*)p = w; }
;   __device__ __forceinline__ void operator()(const f32x4 (&acc)[2][2][4][2], const pg8::Unit& u, int wr, int wc, int fr, int fq) const {
;     ...
;       else if (pn < 10) { store_bf16x4(RV + (size_t)row * 512 + (col - 2048), v); }
;       else { f32x4 o; for (int j = 0; j < 4; ++j) o[j] = siluf_(v[j]); store_bf16x4(RG + (size_t)row * 512 + (col - 2560), o); }
.LBB0_922:
	s_and_b64 vcc, exec, s[10:11]
	s_cbranch_vccnz .LBB0_928
	s_andn2_b64 vcc, exec, s[78:79]
	s_cbranch_vccnz .LBB0_925
	v_mul_f32_e32 v136, 0xbfb8aa3b, v25
	v_mul_f32_e32 v137, 0xbfb8aa3b, v26
	v_mul_f32_e32 v152, 0xbfb8aa3b, v27
	v_exp_f32_e32 v136, v136
	v_exp_f32_e32 v137, v137
	v_exp_f32_e32 v152, v152
	v_mul_f32_e32 v131, 0xbfb8aa3b, v24
	v_exp_f32_e32 v131, v131
	v_add_f32_e32 v136, 1.0, v136
	v_add_f32_e32 v137, 1.0, v137
	v_add_f32_e32 v152, 1.0, v152
	v_rcp_f32_e32 v136, v136
	v_rcp_f32_e32 v137, v137
	v_rcp_f32_e32 v152, v152
	v_add_f32_e32 v131, 1.0, v131
	v_rcp_f32_e32 v131, v131
	v_mul_f32_e32 v154, v25, v136
	v_mul_f32_e32 v155, v26, v137
	v_mul_f32_e32 v156, v27, v152
	v_lshl_add_u64 v[136:137], s[46:47], 0, v[132:133]
	v_mov_b32_e32 v152, v128
	v_mov_b32_e32 v153, v144
	v_lshl_add_u64 v[136:137], v[152:153], 1, v[136:137]
	v_add_co_u32_e32 v136, vcc, 0xfffff000, v136
	s_mov_b64 s[18:19], 0
	s_nop 0
	v_addc_co_u32_e32 v137, vcc, -1, v137, vcc
	v_mul_f32_e32 v131, v24, v131
	v_cvt_pk_bf16_f32 v246, v131, v154
	v_cvt_pk_bf16_f32 v247, v155, v156
	s_nop 1
	v_permlane16_swap_b32_e32 v244, v246
	v_permlane16_swap_b32_e32 v245, v247
	v_lshl_add_u64 v[248:249], v[136:137], 0, v[252:253]
	global_store_dwordx4 v[248:249], v[244:247], off offset:-1024
.LBB0_925:
	s_andn2_b64 vcc, exec, s[18:19]
	s_cbranch_vccnz .LBB0_927
	v_lshl_add_u64 v[136:137], s[48:49], 0, v[132:133]
	v_mov_b32_e32 v152, v128
	v_mov_b32_e32 v153, v144
	v_lshl_add_u64 v[136:137], v[152:153], 1, v[136:137]
	v_cvt_pk_bf16_f32 v246, v24, v25
	v_cvt_pk_bf16_f32 v247, v26, v27
	s_nop 1
	v_permlane16_swap_b32_e32 v244, v246
	v_permlane16_swap_b32_e32 v245, v247
	v_lshl_add_u64 v[248:249], v[136:137], 0, v[252:253]
	global_store_dwordx4 v[248:249], v[244:247], off offset:-4096

; __device__ __forceinline__ void store_bf16x4(bf16_t* p, f32x4 v) { u32x2 w; w.x = cvt_pk_bf16(v[0], v[1]); w.y = cvt_pk_bf16(v[2], v[3]); *(u32x2*)p = w; }
;   __device__ __forceinline__ void operator()(const f32x4 (&acc)[2][2][4][2], const pg8::Unit& u, int wr, int wc, int fr, int fq) const {
;     ...
;       else if (pn < 6) { store_bf16x4(DV + (size_t)row * 512 + (col - 1024), v); }
.LBB0_928:
	s_andn2_b64 vcc, exec, s[18:19]
	s_cbranch_vccnz .LBB0_930
	v_lshl_add_u64 v[136:137], s[90:91], 0, v[132:133]
	v_mov_b32_e32 v152, v128
	v_mov_b32_e32 v153, v144
	v_lshl_add_u64 v[136:137], v[152:153], 1, v[136:137]
	v_cvt_pk_bf16_f32 v246, v24, v25
	v_cvt_pk_bf16_f32 v247, v26, v27
	s_nop 1
	v_permlane16_swap_b32_e32 v244, v246
	v_permlane16_swap_b32_e32 v245, v247
	v_lshl_add_u64 v[248:249], v[136:137], 0, v[252:253]
	global_store_dwordx4 v[248:249], v[244:247], off offset:-2048

; __device__ __forceinline__ float siluf_(float v) { return v * sigmoidf_(v); }
; __device__ __forceinline__ void store_bf16x4(bf16_t* p, f32x4 v) { u32x2 w; w.x = cvt_pk_bf16(v[0], v[1]); w.y = cvt_pk_bf16(v[2], v[3]); *(u32x2*)p = w; }
;   __device__ __forceinline__ void operator()(const f32x4 (&acc)[2][2][4][2], const pg8::Unit& u, int wr, int wc, int fr, int fq) const {
;     ...
;       else if (pn < 10) { store_bf16x4(RV + (size_t)row * 512 + (col - 2048), v); }
;       else { f32x4 o; for (int j = 0; j < 4; ++j) o[j] = siluf_(v[j]); store_bf16x4(RG + (size_t)row * 512 + (col - 2560), o); }
.LBB0_932:
	s_and_b64 vcc, exec, s[10:11]
	s_cbranch_vccnz .LBB0_938
	s_andn2_b64 vcc, exec, s[78:79]
	s_cbranch_vccnz .LBB0_935
	v_mul_f32_e32 v136, 0xbfb8aa3b, v21
	v_mul_f32_e32 v137, 0xbfb8aa3b, v22
	v_mul_f32_e32 v152, 0xbfb8aa3b, v23
	v_exp_f32_e32 v136, v136
	v_exp_f32_e32 v137, v137
	v_exp_f32_e32 v152, v152
	v_mul_f32_e32 v131, 0xbfb8aa3b, v20
	v_exp_f32_e32 v131, v131
	v_add_f32_e32 v136, 1.0, v136
	v_add_f32_e32 v137, 1.0, v137
	v_add_f32_e32 v152, 1.0, v152
	v_rcp_f32_e32 v136, v136
	v_rcp_f32_e32 v137, v137
	v_rcp_f32_e32 v152, v152
	v_add_f32_e32 v131, 1.0, v131
	v_rcp_f32_e32 v131, v131
	v_mul_f32_e32 v154, v21, v136
	v_mul_f32_e32 v155, v22, v137
	v_mul_f32_e32 v156, v23, v152
	v_lshl_add_u64 v[136:137], s[46:47], 0, v[132:133]
	v_mov_b32_e32 v152, v128
	v_mov_b32_e32 v153, v144
	v_lshl_add_u64 v[136:137], v[152:153], 1, v[136:137]
	v_add_co_u32_e32 v136, vcc, 0xfffff000, v136
	s_mov_b64 s[18:19], 0
	s_nop 0
	v_addc_co_u32_e32 v137, vcc, -1, v137, vcc
	v_mul_f32_e32 v131, v20, v131
	v_cvt_pk_bf16_f32 v244, v131, v154
	v_cvt_pk_bf16_f32 v245, v155, v156
.LBB0_935:
	s_andn2_b64 vcc, exec, s[18:19]
	s_cbranch_vccnz .LBB0_937
	v_lshl_add_u64 v[136:137], s[48:49], 0, v[132:133]
	v_mov_b32_e32 v152, v128
	v_mov_b32_e32 v153, v144
	v_lshl_add_u64 v[136:137], v[152:153], 1, v[136:137]
	v_cvt_pk_bf16_f32 v244, v20, v21
	v_cvt_pk_bf16_f32 v245, v22, v23

; __device__ __forceinline__ void store_bf16x4(bf16_t* p, f32x4 v) { u32x2 w; w.x = cvt_pk_bf16(v[0], v[1]); w.y = cvt_pk_bf16(v[2], v[3]); *(u32x2*)p = w; }
;   __device__ __forceinline__ void operator()(const f32x4 (&acc)[2][2][4][2], const pg8::Unit& u, int wr, int wc, int fr, int fq) const {
;     ...
;       else if (pn < 6) { store_bf16x4(DV + (size_t)row * 512 + (col - 1024), v); }
.LBB0_938:
	s_andn2_b64 vcc, exec, s[18:19]
	s_cbranch_vccnz .LBB0_940
	v_lshl_add_u64 v[136:137], s[90:91], 0, v[132:133]
	v_mov_b32_e32 v152, v128
	v_mov_b32_e32 v153, v144
	v_lshl_add_u64 v[136:137], v[152:153], 1, v[136:137]
	v_cvt_pk_bf16_f32 v244, v20, v21
	v_cvt_pk_bf16_f32 v245, v22, v23

; __device__ __forceinline__ float siluf_(float v) { return v * sigmoidf_(v); }
; __device__ __forceinline__ void store_bf16x4(bf16_t* p, f32x4 v) { u32x2 w; w.x = cvt_pk_bf16(v[0], v[1]); w.y = cvt_pk_bf16(v[2], v[3]); *(u32x2*)p = w; }
;   __device__ __forceinline__ void operator()(const f32x4 (&acc)[2][2][4][2], const pg8::Unit& u, int wr, int wc, int fr, int fq) const {
;     ...
;       else if (pn < 10) { store_bf16x4(RV + (size_t)row * 512 + (col - 2048), v); }
;       else { f32x4 o; for (int j = 0; j < 4; ++j) o[j] = siluf_(v[j]); store_bf16x4(RG + (size_t)row * 512 + (col - 2560), o); }
.LBB0_942:
	s_and_b64 vcc, exec, s[10:11]
	s_cbranch_vccnz .LBB0_948
	s_andn2_b64 vcc, exec, s[78:79]
	s_cbranch_vccnz .LBB0_945
	v_mul_f32_e32 v136, 0xbfb8aa3b, v17
	v_mul_f32_e32 v137, 0xbfb8aa3b, v18
	v_mul_f32_e32 v152, 0xbfb8aa3b, v19
	v_exp_f32_e32 v136, v136
	v_exp_f32_e32 v137, v137
	v_exp_f32_e32 v152, v152
	v_mul_f32_e32 v131, 0xbfb8aa3b, v16
	v_exp_f32_e32 v131, v131
	v_add_f32_e32 v136, 1.0, v136
	v_add_f32_e32 v137, 1.0, v137
	v_add_f32_e32 v152, 1.0, v152
	v_rcp_f32_e32 v136, v136
	v_rcp_f32_e32 v137, v137
	v_rcp_f32_e32 v152, v152
	v_add_f32_e32 v131, 1.0, v131
	v_rcp_f32_e32 v131, v131
	v_mul_f32_e32 v154, v17, v136
	v_mul_f32_e32 v155, v18, v137
	v_mul_f32_e32 v156, v19, v152
	v_lshl_add_u64 v[136:137], s[46:47], 0, v[132:133]
	v_mov_b32_e32 v152, v128
	v_mov_b32_e32 v153, v144
	v_lshl_add_u64 v[136:137], v[152:153], 1, v[136:137]
	v_add_co_u32_e32 v136, vcc, 0xfffff000, v136
	s_mov_b64 s[18:19], 0
	s_nop 0
	v_addc_co_u32_e32 v137, vcc, -1, v137, vcc
	v_mul_f32_e32 v131, v16, v131
	v_cvt_pk_bf16_f32 v246, v131, v154
	v_cvt_pk_bf16_f32 v247, v155, v156
	s_nop 1
	v_permlane16_swap_b32_e32 v244, v246
	v_permlane16_swap_b32_e32 v245, v247
	v_lshl_add_u64 v[248:249], v[136:137], 0, v[252:253]
	global_store_dwordx4 v[248:249], v[244:247], off offset:-768
.LBB0_945:
	s_andn2_b64 vcc, exec, s[18:19]
	s_cbranch_vccnz .LBB0_947
	v_lshl_add_u64 v[136:137], s[48:49], 0, v[132:133]
	v_mov_b32_e32 v152, v128
	v_mov_b32_e32 v153, v144
	v_lshl_add_u64 v[136:137], v[152:153], 1, v[136:137]
	v_cvt_pk_bf16_f32 v246, v16, v17
	v_cvt_pk_bf16_f32 v247, v18, v19
	s_nop 1
	v_permlane16_swap_b32_e32 v244, v246
	v_permlane16_swap_b32_e32 v245, v247
	v_lshl_add_u64 v[248:249], v[136:137], 0, v[252:253]
	global_store_dwordx4 v[248:249], v[244:247], off offset:-3840

; __device__ __forceinline__ void store_bf16x4(bf16_t* p, f32x4 v) { u32x2 w; w.x = cvt_pk_bf16(v[0], v[1]); w.y = cvt_pk_bf16(v[2], v[3]); *(u32x2*)p = w; }
;   __device__ __forceinline__ void operator()(const f32x4 (&acc)[2][2][4][2], const pg8::Unit& u, int wr, int wc, int fr, int fq) const {
;     ...
;       else if (pn < 6) { store_bf16x4(DV + (size_t)row * 512 + (col - 1024), v); }
.LBB0_948:
	s_andn2_b64 vcc, exec, s[18:19]
	s_cbranch_vccnz .LBB0_950
	v_lshl_add_u64 v[132:133], s[90:91], 0, v[132:133]
	v_mov_b32_e32 v136, v128
	v_mov_b32_e32 v137, v144
	v_lshl_add_u64 v[132:133], v[136:137], 1, v[132:133]
	v_cvt_pk_bf16_f32 v246, v16, v17
	v_cvt_pk_bf16_f32 v247, v18, v19
	s_nop 1
	v_permlane16_swap_b32_e32 v244, v246
	v_permlane16_swap_b32_e32 v245, v247
	v_lshl_add_u64 v[248:249], v[132:133], 0, v[252:253]
	global_store_dwordx4 v[248:249], v[244:247], off offset:-1792

; __device__ __forceinline__ void store_bf16x4(bf16_t* p, f32x4 v) { u32x2 w; w.x = cvt_pk_bf16(v[0], v[1]); w.y = cvt_pk_bf16(v[2], v[3]); *(u32x2*)p = w; }
;   __device__ __forceinline__ void operator()(const f32x4 (&acc)[2][2][4][2], const pg8::Unit& u, int wr, int wc, int fr, int fq) const {
;     ...
;       if (pn < 4) { store_bf16x4(DQK + (size_t)row * 1024 + col, v); }
.LBB0_952:
	v_lshl_add_u64 v[136:137], v[128:129], 1, v[134:135]
	v_cvt_pk_bf16_f32 v244, v28, v29
	v_cvt_pk_bf16_f32 v245, v30, v31
	s_and_b64 vcc, exec, s[12:13]
	s_mov_b64 s[18:19], -1
	s_cbranch_vccz .LBB0_922

; __device__ __forceinline__ void store_bf16x4(bf16_t* p, f32x4 v) { u32x2 w; w.x = cvt_pk_bf16(v[0], v[1]); w.y = cvt_pk_bf16(v[2], v[3]); *(u32x2*)p = w; }
;   __device__ __forceinline__ void operator()(const f32x4 (&acc)[2][2][4][2], const pg8::Unit& u, int wr, int wc, int fr, int fq) const {
;     ...
;       if (pn < 4) { store_bf16x4(DQK + (size_t)row * 1024 + col, v); }
.LBB0_954:
	v_lshl_add_u64 v[136:137], v[128:129], 1, v[134:135]
	v_cvt_pk_bf16_f32 v246, v24, v25
	v_cvt_pk_bf16_f32 v247, v26, v27
	s_nop 1
	v_permlane16_swap_b32_e32 v244, v246
	v_permlane16_swap_b32_e32 v245, v247
	v_lshl_add_u64 v[248:249], v[136:137], 0, v[252:253]
	global_store_dwordx4 v[248:249], v[244:247], off
	s_and_b64 vcc, exec, s[12:13]
	s_mov_b64 s[18:19], -1
	s_cbranch_vccz .LBB0_932

; __device__ __forceinline__ void store_bf16x4(bf16_t* p, f32x4 v) { u32x2 w; w.x = cvt_pk_bf16(v[0], v[1]); w.y = cvt_pk_bf16(v[2], v[3]); *(u32x2*)p = w; }
;   __device__ __forceinline__ void operator()(const f32x4 (&acc)[2][2][4][2], const pg8::Unit& u, int wr, int wc, int fr, int fq) const {
;     ...
;       if (pn < 4) { store_bf16x4(DQK + (size_t)row * 1024 + col, v); }
.LBB0_956:
	v_lshl_add_u64 v[136:137], v[128:129], 1, v[134:135]
	v_cvt_pk_bf16_f32 v244, v20, v21
	v_cvt_pk_bf16_f32 v245, v22, v23
	s_and_b64 vcc, exec, s[12:13]
	s_mov_b64 s[18:19], -1
	s_cbranch_vccz .LBB0_942

; __device__ __forceinline__ float siluf_(float v) { return v * sigmoidf_(v); }
; __device__ __forceinline__ void store_bf16x4(bf16_t* p, f32x4 v) { u32x2 w; w.x = cvt_pk_bf16(v[0], v[1]); w.y = cvt_pk_bf16(v[2], v[3]); *(u32x2*)p = w; }
;   __device__ __forceinline__ void operator()(const f32x4 (&acc)[2][2][4][2], const pg8::Unit& u, int wr, int wc, int fr, int fq) const {
;     ...
;       if (pn < 4) { store_bf16x4(DQK + (size_t)row * 1024 + col, v); }
;       else if (pn < 6) { store_bf16x4(DV + (size_t)row * 512 + (col - 1024), v); }
;       else if (pn < 10) { store_bf16x4(RV + (size_t)row * 512 + (col - 2048), v); }
;       else { f32x4 o; for (int j = 0; j < 4; ++j) o[j] = siluf_(v[j]); store_bf16x4(RG + (size_t)row * 512 + (col - 2560), o); }
.LBB0_958:
	v_lshl_add_u64 v[132:133], v[128:129], 1, v[134:135]
	v_cvt_pk_bf16_f32 v246, v16, v17
	v_cvt_pk_bf16_f32 v247, v18, v19
	s_nop 1
	v_permlane16_swap_b32_e32 v244, v246
	v_permlane16_swap_b32_e32 v245, v247
	v_lshl_add_u64 v[248:249], v[132:133], 0, v[252:253]
	global_store_dwordx4 v[248:249], v[244:247], off offset:256
.LBB0_959:
	v_add_u32_e32 v132, 0xb0, v130
	v_ashrrev_i32_e32 v133, 31, v132
	v_lshlrev_b64 v[130:131], 10, v[132:133]
	s_and_b64 vcc, exec, s[12:13]
	s_mov_b64 s[18:19], -1
	s_cbranch_vccnz .LBB0_999
	s_and_b64 vcc, exec, s[10:11]
	s_cbranch_vccnz .LBB0_966
	s_andn2_b64 vcc, exec, s[78:79]
	s_cbranch_vccnz .LBB0_963
	v_mul_f32_e32 v134, 0xbfb8aa3b, v12
	v_mul_f32_e32 v135, 0xbfb8aa3b, v13
	v_mul_f32_e32 v136, 0xbfb8aa3b, v14
	v_mul_f32_e32 v137, 0xbfb8aa3b, v15
	v_exp_f32_e32 v134, v134
	v_exp_f32_e32 v135, v135
	v_exp_f32_e32 v136, v136
	v_exp_f32_e32 v137, v137
	v_add_f32_e32 v134, 1.0, v134
	v_add_f32_e32 v135, 1.0, v135
	v_add_f32_e32 v136, 1.0, v136
	v_add_f32_e32 v137, 1.0, v137
	v_rcp_f32_e32 v134, v134
	v_rcp_f32_e32 v135, v135
	v_rcp_f32_e32 v136, v136
	v_rcp_f32_e32 v137, v137
	v_mul_f32_e32 v152, v12, v134
	v_mul_f32_e32 v153, v13, v135
	v_mul_f32_e32 v154, v14, v136
	v_mul_f32_e32 v155, v15, v137
	v_lshl_add_u64 v[134:135], s[46:47], 0, v[130:131]
	v_mov_b32_e32 v136, v128
	v_mov_b32_e32 v137, v144
	v_lshl_add_u64 v[134:135], v[136:137], 1, v[134:135]
	v_add_co_u32_e32 v134, vcc, 0xfffff000, v134
	s_mov_b64 s[18:19], 0
	s_nop 0
	v_addc_co_u32_e32 v135, vcc, -1, v135, vcc
	v_cvt_pk_bf16_f32 v244, v152, v153
	v_cvt_pk_bf16_f32 v245, v154, v155
.LBB0_963:
	s_andn2_b64 vcc, exec, s[18:19]
	s_cbranch_vccnz .LBB0_965
	v_lshl_add_u64 v[134:135], s[48:49], 0, v[130:131]
	v_mov_b32_e32 v136, v128
	v_mov_b32_e32 v137, v144
	v_lshl_add_u64 v[134:135], v[136:137], 1, v[134:135]
	v_cvt_pk_bf16_f32 v244, v12, v13
	v_cvt_pk_bf16_f32 v245, v14, v15

; __device__ __forceinline__ void store_bf16x4(bf16_t* p, f32x4 v) { u32x2 w; w.x = cvt_pk_bf16(v[0], v[1]); w.y = cvt_pk_bf16(v[2], v[3]); *(u32x2*)p = w; }
;   __device__ __forceinline__ void operator()(const f32x4 (&acc)[2][2][4][2], const pg8::Unit& u, int wr, int wc, int fr, int fq) const {
;     ...
;       else if (pn < 6) { store_bf16x4(DV + (size_t)row * 512 + (col - 1024), v); }
.LBB0_966:
	s_andn2_b64 vcc, exec, s[18:19]
	s_cbranch_vccnz .LBB0_968
	v_lshl_add_u64 v[134:135], s[90:91], 0, v[130:131]
	v_mov_b32_e32 v136, v128
	v_mov_b32_e32 v137, v144
	v_lshl_add_u64 v[134:135], v[136:137], 1, v[134:135]
	v_cvt_pk_bf16_f32 v244, v12, v13
	v_cvt_pk_bf16_f32 v245, v14, v15

; __device__ __forceinline__ float siluf_(float v) { return v * sigmoidf_(v); }
; __device__ __forceinline__ void store_bf16x4(bf16_t* p, f32x4 v) { u32x2 w; w.x = cvt_pk_bf16(v[0], v[1]); w.y = cvt_pk_bf16(v[2], v[3]); *(u32x2*)p = w; }
;   __device__ __forceinline__ void operator()(const f32x4 (&acc)[2][2][4][2], const pg8::Unit& u, int wr, int wc, int fr, int fq) const {
;     ...
;       else if (pn < 10) { store_bf16x4(RV + (size_t)row * 512 + (col - 2048), v); }
;       else { f32x4 o; for (int j = 0; j < 4; ++j) o[j] = siluf_(v[j]); store_bf16x4(RG + (size_t)row * 512 + (col - 2560), o); }
.LBB0_970:
	s_and_b64 vcc, exec, s[10:11]
	s_cbranch_vccnz .LBB0_976
	s_andn2_b64 vcc, exec, s[78:79]
	s_cbranch_vccnz .LBB0_973
	v_mul_f32_e32 v134, 0xbfb8aa3b, v8
	v_mul_f32_e32 v135, 0xbfb8aa3b, v9
	v_mul_f32_e32 v136, 0xbfb8aa3b, v10
	v_mul_f32_e32 v137, 0xbfb8aa3b, v11
	v_exp_f32_e32 v134, v134
	v_exp_f32_e32 v135, v135
	v_exp_f32_e32 v136, v136
	v_exp_f32_e32 v137, v137
	v_add_f32_e32 v134, 1.0, v134
	v_add_f32_e32 v135, 1.0, v135
	v_add_f32_e32 v136, 1.0, v136
	v_add_f32_e32 v137, 1.0, v137
	v_rcp_f32_e32 v134, v134
	v_rcp_f32_e32 v135, v135
	v_rcp_f32_e32 v136, v136
	v_rcp_f32_e32 v137, v137
	v_mul_f32_e32 v152, v8, v134
	v_mul_f32_e32 v153, v9, v135
	v_mul_f32_e32 v154, v10, v136
	v_mul_f32_e32 v155, v11, v137
	v_lshl_add_u64 v[134:135], s[46:47], 0, v[130:131]
	v_mov_b32_e32 v136, v128
	v_mov_b32_e32 v137, v144
	v_lshl_add_u64 v[134:135], v[136:137], 1, v[134:135]
	v_add_co_u32_e32 v134, vcc, 0xfffff000, v134
	s_mov_b64 s[18:19], 0
	s_nop 0
	v_addc_co_u32_e32 v135, vcc, -1, v135, vcc
	v_cvt_pk_bf16_f32 v246, v152, v153
	v_cvt_pk_bf16_f32 v247, v154, v155
	s_nop 1
	v_permlane16_swap_b32_e32 v244, v246
	v_permlane16_swap_b32_e32 v245, v247
	v_lshl_add_u64 v[248:249], v[134:135], 0, v[252:253]
	global_store_dwordx4 v[248:249], v[244:247], off offset:-1024
.LBB0_973:
	s_andn2_b64 vcc, exec, s[18:19]
	s_cbranch_vccnz .LBB0_975
	v_lshl_add_u64 v[134:135], s[48:49], 0, v[130:131]
	v_mov_b32_e32 v136, v128
	v_mov_b32_e32 v137, v144
	v_lshl_add_u64 v[134:135], v[136:137], 1, v[134:135]
	v_cvt_pk_bf16_f32 v246, v8, v9
	v_cvt_pk_bf16_f32 v247, v10, v11
	s_nop 1
	v_permlane16_swap_b32_e32 v244, v246
	v_permlane16_swap_b32_e32 v245, v247
	v_lshl_add_u64 v[248:249], v[134:135], 0, v[252:253]
	global_store_dwordx4 v[248:249], v[244:247], off offset:-4096

; __device__ __forceinline__ void store_bf16x4(bf16_t* p, f32x4 v) { u32x2 w; w.x = cvt_pk_bf16(v[0], v[1]); w.y = cvt_pk_bf16(v[2], v[3]); *(u32x2*)p = w; }
;   __device__ __forceinline__ void operator()(const f32x4 (&acc)[2][2][4][2], const pg8::Unit& u, int wr, int wc, int fr, int fq) const {
;     ...
;       else if (pn < 6) { store_bf16x4(DV + (size_t)row * 512 + (col - 1024), v); }
.LBB0_976:
	s_andn2_b64 vcc, exec, s[18:19]
	s_cbranch_vccnz .LBB0_978
	v_lshl_add_u64 v[134:135], s[90:91], 0, v[130:131]
	v_mov_b32_e32 v136, v128
	v_mov_b32_e32 v137, v144
	v_lshl_add_u64 v[134:135], v[136:137], 1, v[134:135]
	v_cvt_pk_bf16_f32 v246, v8, v9
	v_cvt_pk_bf16_f32 v247, v10, v11
	s_nop 1
	v_permlane16_swap_b32_e32 v244, v246
	v_permlane16_swap_b32_e32 v245, v247
	v_lshl_add_u64 v[248:249], v[134:135], 0, v[252:253]
	global_store_dwordx4 v[248:249], v[244:247], off offset:-2048

; __device__ __forceinline__ float siluf_(float v) { return v * sigmoidf_(v); }
; __device__ __forceinline__ void store_bf16x4(bf16_t* p, f32x4 v) { u32x2 w; w.x = cvt_pk_bf16(v[0], v[1]); w.y = cvt_pk_bf16(v[2], v[3]); *(u32x2*)p = w; }
;   __device__ __forceinline__ void operator()(const f32x4 (&acc)[2][2][4][2], const pg8::Unit& u, int wr, int wc, int fr, int fq) const {
;     ...
;       else if (pn < 10) { store_bf16x4(RV + (size_t)row * 512 + (col - 2048), v); }
;       else { f32x4 o; for (int j = 0; j < 4; ++j) o[j] = siluf_(v[j]); store_bf16x4(RG + (size_t)row * 512 + (col - 2560), o); }
.LBB0_980:
	s_and_b64 vcc, exec, s[10:11]
	s_cbranch_vccnz .LBB0_986
	s_andn2_b64 vcc, exec, s[78:79]
	s_cbranch_vccnz .LBB0_983
	v_mul_f32_e32 v134, 0xbfb8aa3b, v4
	v_mul_f32_e32 v135, 0xbfb8aa3b, v5
	v_mul_f32_e32 v136, 0xbfb8aa3b, v6
	v_mul_f32_e32 v137, 0xbfb8aa3b, v7
	v_exp_f32_e32 v134, v134
	v_exp_f32_e32 v135, v135
	v_exp_f32_e32 v136, v136
	v_exp_f32_e32 v137, v137
	v_add_f32_e32 v134, 1.0, v134
	v_add_f32_e32 v135, 1.0, v135
	v_add_f32_e32 v136, 1.0, v136
	v_add_f32_e32 v137, 1.0, v137
	v_rcp_f32_e32 v134, v134
	v_rcp_f32_e32 v135, v135
	v_rcp_f32_e32 v136, v136
	v_rcp_f32_e32 v137, v137
	v_mul_f32_e32 v152, v4, v134
	v_mul_f32_e32 v153, v5, v135
	v_mul_f32_e32 v154, v6, v136
	v_mul_f32_e32 v155, v7, v137
	v_lshl_add_u64 v[134:135], s[46:47], 0, v[130:131]
	v_mov_b32_e32 v136, v128
	v_mov_b32_e32 v137, v144
	v_lshl_add_u64 v[134:135], v[136:137], 1, v[134:135]
	v_add_co_u32_e32 v134, vcc, 0xfffff000, v134
	s_mov_b64 s[18:19], 0
	s_nop 0
	v_addc_co_u32_e32 v135, vcc, -1, v135, vcc
	v_cvt_pk_bf16_f32 v244, v152, v153
	v_cvt_pk_bf16_f32 v245, v154, v155
.LBB0_983:
	s_andn2_b64 vcc, exec, s[18:19]
	s_cbranch_vccnz .LBB0_985
	v_lshl_add_u64 v[134:135], s[48:49], 0, v[130:131]
	v_mov_b32_e32 v136, v128
	v_mov_b32_e32 v137, v144
	v_lshl_add_u64 v[134:135], v[136:137], 1, v[134:135]
	v_cvt_pk_bf16_f32 v244, v4, v5
	v_cvt_pk_bf16_f32 v245, v6, v7

; __device__ __forceinline__ void store_bf16x4(bf16_t* p, f32x4 v) { u32x2 w; w.x = cvt_pk_bf16(v[0], v[1]); w.y = cvt_pk_bf16(v[2], v[3]); *(u32x2*)p = w; }
;   __device__ __forceinline__ void operator()(const f32x4 (&acc)[2][2][4][2], const pg8::Unit& u, int wr, int wc, int fr, int fq) const {
;     ...
;       else if (pn < 6) { store_bf16x4(DV + (size_t)row * 512 + (col - 1024), v); }
.LBB0_986:
	s_andn2_b64 vcc, exec, s[18:19]
	s_cbranch_vccnz .LBB0_988
	v_lshl_add_u64 v[134:135], s[90:91], 0, v[130:131]
	v_mov_b32_e32 v136, v128
	v_mov_b32_e32 v137, v144
	v_lshl_add_u64 v[134:135], v[136:137], 1, v[134:135]
	v_cvt_pk_bf16_f32 v244, v4, v5
	v_cvt_pk_bf16_f32 v245, v6, v7

; __device__ __forceinline__ float siluf_(float v) { return v * sigmoidf_(v); }
; __device__ __forceinline__ void store_bf16x4(bf16_t* p, f32x4 v) { u32x2 w; w.x = cvt_pk_bf16(v[0], v[1]); w.y = cvt_pk_bf16(v[2], v[3]); *(u32x2*)p = w; }
;   __device__ __forceinline__ void operator()(const f32x4 (&acc)[2][2][4][2], const pg8::Unit& u, int wr, int wc, int fr, int fq) const {
;     ...
;       else if (pn < 10) { store_bf16x4(RV + (size_t)row * 512 + (col - 2048), v); }
;       else { f32x4 o; for (int j = 0; j < 4; ++j) o[j] = siluf_(v[j]); store_bf16x4(RG + (size_t)row * 512 + (col - 2560), o); }
.LBB0_990:
	s_and_b64 vcc, exec, s[10:11]
	s_mov_b64 s[10:11], -1
	s_cbranch_vccnz .LBB0_996
	s_andn2_b64 vcc, exec, s[78:79]
	s_cbranch_vccnz .LBB0_993
	v_mul_f32_e32 v134, 0xbfb8aa3b, v0
	v_mul_f32_e32 v135, 0xbfb8aa3b, v1
	v_mul_f32_e32 v136, 0xbfb8aa3b, v2
	v_mul_f32_e32 v137, 0xbfb8aa3b, v3
	v_exp_f32_e32 v134, v134
	v_exp_f32_e32 v135, v135
	v_exp_f32_e32 v136, v136
	v_exp_f32_e32 v137, v137
	v_add_f32_e32 v134, 1.0, v134
	v_add_f32_e32 v135, 1.0, v135
	v_add_f32_e32 v136, 1.0, v136
	v_add_f32_e32 v137, 1.0, v137
	v_rcp_f32_e32 v134, v134
	v_rcp_f32_e32 v135, v135
	v_rcp_f32_e32 v136, v136
	v_rcp_f32_e32 v137, v137
	v_mul_f32_e32 v152, v0, v134
	v_mul_f32_e32 v153, v1, v135
	v_mul_f32_e32 v154, v2, v136
	v_mul_f32_e32 v155, v3, v137
	v_lshl_add_u64 v[134:135], s[46:47], 0, v[130:131]
	v_mov_b32_e32 v136, v128
	v_mov_b32_e32 v137, v144
	v_lshl_add_u64 v[134:135], v[136:137], 1, v[134:135]
	v_add_co_u32_e32 v134, vcc, 0xfffff000, v134
	s_mov_b64 s[10:11], 0
	s_nop 0
	v_addc_co_u32_e32 v135, vcc, -1, v135, vcc
	v_cvt_pk_bf16_f32 v246, v152, v153
	v_cvt_pk_bf16_f32 v247, v154, v155
	s_nop 1
	v_permlane16_swap_b32_e32 v244, v246
	v_permlane16_swap_b32_e32 v245, v247
	v_lshl_add_u64 v[248:249], v[134:135], 0, v[252:253]
	global_store_dwordx4 v[248:249], v[244:247], off offset:-768
.LBB0_993:
	s_andn2_b64 vcc, exec, s[10:11]
	s_cbranch_vccnz .LBB0_995
	v_lshl_add_u64 v[134:135], s[48:49], 0, v[130:131]
	v_mov_b32_e32 v136, v128
	v_mov_b32_e32 v137, v144
	v_lshl_add_u64 v[134:135], v[136:137], 1, v[134:135]
	v_cvt_pk_bf16_f32 v246, v0, v1
	v_cvt_pk_bf16_f32 v247, v2, v3
	s_nop 1
	v_permlane16_swap_b32_e32 v244, v246
	v_permlane16_swap_b32_e32 v245, v247
	v_lshl_add_u64 v[248:249], v[134:135], 0, v[252:253]
	global_store_dwordx4 v[248:249], v[244:247], off offset:-3840

; __device__ __forceinline__ void store_bf16x4(bf16_t* p, f32x4 v) { u32x2 w; w.x = cvt_pk_bf16(v[0], v[1]); w.y = cvt_pk_bf16(v[2], v[3]); *(u32x2*)p = w; }
;   __device__ __forceinline__ void operator()(const f32x4 (&acc)[2][2][4][2], const pg8::Unit& u, int wr, int wc, int fr, int fq) const {
;     ...
;       else if (pn < 6) { store_bf16x4(DV + (size_t)row * 512 + (col - 1024), v); }
.LBB0_996:
	s_andn2_b64 vcc, exec, s[10:11]
	s_cbranch_vccnz .LBB0_998
	v_lshl_add_u64 v[130:131], s[90:91], 0, v[130:131]
	v_mov_b32_e32 v134, v128
	v_mov_b32_e32 v135, v144
	v_lshl_add_u64 v[130:131], v[134:135], 1, v[130:131]
	v_cvt_pk_bf16_f32 v246, v0, v1
	v_cvt_pk_bf16_f32 v247, v2, v3
	s_nop 1
	v_permlane16_swap_b32_e32 v244, v246
	v_permlane16_swap_b32_e32 v245, v247
	v_lshl_add_u64 v[248:249], v[130:131], 0, v[252:253]
	global_store_dwordx4 v[248:249], v[244:247], off offset:-1792

; __device__ __forceinline__ void store_bf16x4(bf16_t* p, f32x4 v) { u32x2 w; w.x = cvt_pk_bf16(v[0], v[1]); w.y = cvt_pk_bf16(v[2], v[3]); *(u32x2*)p = w; }
;   __device__ __forceinline__ void operator()(const f32x4 (&acc)[2][2][4][2], const pg8::Unit& u, int wr, int wc, int fr, int fq) const {
;     ...
;       if (pn < 4) { store_bf16x4(DQK + (size_t)row * 1024 + col, v); }
.LBB0_1000:
	v_lshl_add_u64 v[134:135], v[128:129], 1, v[132:133]
	v_cvt_pk_bf16_f32 v244, v12, v13
	v_cvt_pk_bf16_f32 v245, v14, v15
	s_and_b64 vcc, exec, s[12:13]
	s_mov_b64 s[18:19], -1
	s_cbranch_vccz .LBB0_970

; __device__ __forceinline__ void store_bf16x4(bf16_t* p, f32x4 v) { u32x2 w; w.x = cvt_pk_bf16(v[0], v[1]); w.y = cvt_pk_bf16(v[2], v[3]); *(u32x2*)p = w; }
;   __device__ __forceinline__ void operator()(const f32x4 (&acc)[2][2][4][2], const pg8::Unit& u, int wr, int wc, int fr, int fq) const {
;     ...
;       if (pn < 4) { store_bf16x4(DQK + (size_t)row * 1024 + col, v); }
.LBB0_1002:
	v_lshl_add_u64 v[134:135], v[128:129], 1, v[132:133]
	v_cvt_pk_bf16_f32 v246, v8, v9
	v_cvt_pk_bf16_f32 v247, v10, v11
	s_nop 1
	v_permlane16_swap_b32_e32 v244, v246
	v_permlane16_swap_b32_e32 v245, v247
	v_lshl_add_u64 v[248:249], v[134:135], 0, v[252:253]
	global_store_dwordx4 v[248:249], v[244:247], off
	s_and_b64 vcc, exec, s[12:13]
	s_mov_b64 s[18:19], -1
	s_cbranch_vccz .LBB0_980

; __device__ __forceinline__ void store_bf16x4(bf16_t* p, f32x4 v) { u32x2 w; w.x = cvt_pk_bf16(v[0], v[1]); w.y = cvt_pk_bf16(v[2], v[3]); *(u32x2*)p = w; }
;   __device__ __forceinline__ void operator()(const f32x4 (&acc)[2][2][4][2], const pg8::Unit& u, int wr, int wc, int fr, int fq) const {
;     ...
;       if (pn < 4) { store_bf16x4(DQK + (size_t)row * 1024 + col, v); }
.LBB0_1004:
	v_lshl_add_u64 v[134:135], v[128:129], 1, v[132:133]
	v_cvt_pk_bf16_f32 v244, v4, v5
	v_cvt_pk_bf16_f32 v245, v6, v7
	s_and_b64 vcc, exec, s[12:13]
	s_mov_b64 s[12:13], -1
	s_cbranch_vccz .LBB0_990

; __device__ __forceinline__ void store_bf16x4(bf16_t* p, f32x4 v) { u32x2 w; w.x = cvt_pk_bf16(v[0], v[1]); w.y = cvt_pk_bf16(v[2], v[3]); *(u32x2*)p = w; }
;   __device__ __forceinline__ void operator()(const f32x4 (&acc)[2][2][4][2], const pg8::Unit& u, int wr, int wc, int fr, int fq) const {
;     ...
;       if (pn < 4) { store_bf16x4(DQK + (size_t)row * 1024 + col, v); }
.LBB0_1006:
	v_lshl_add_u64 v[128:129], v[128:129], 1, v[132:133]
	v_cvt_pk_bf16_f32 v246, v0, v1
	v_cvt_pk_bf16_f32 v247, v2, v3
	s_nop 1
	v_permlane16_swap_b32_e32 v244, v246
	v_permlane16_swap_b32_e32 v245, v247
	v_lshl_add_u64 v[248:249], v[128:129], 0, v[252:253]
	global_store_dwordx4 v[248:249], v[244:247], off offset:256

; #define PG8_STAGE(bufoff, gbase, voff) do { _Pragma("unroll") for (int _i = 0; _i < 2; ++_i) \
;     __builtin_amdgcn_global_load_lds((const unsigned*)((const char*)(gbase) + (voff)[_i]), (LAS unsigned*)(lds + (bufoff) + ldsw + _i * 8192), 16, 0, 0); } while (0)
; #define PG8_LDA(dst, b, h) do { _Pragma("unroll") for (int m = 0; m < 4; ++m) _Pragma("unroll") for (int k = 0; k < 2; ++k) dst[m][k] = *(const LAS bf16x8*)(lds + PG8_SA(b, h) + aoff + m * 2048 + k * 1024); } while (0)
; #define PG8_LDB(dst, b, h) do { _Pragma("unroll") for (int n = 0; n < 2; ++n) _Pragma("unroll") for (int k = 0; k < 2; ++k) dst[n][k] = *(const LAS bf16x8*)(lds + PG8_SB(b, h) + boff + n * 2048 + k * 1024); } while (0)
; #define PG8_MMA(ai, bj, At, Bt) do { __builtin_amdgcn_s_setprio(1); _Pragma("unroll") for (int m = 0; m < 4; ++m) _Pragma("unroll") for (int n = 0; n < 2; ++n) _Pragma("unroll") for (int k = 0; k < 2; ++k) \
;     acc[ai][bj][m][n] = __builtin_amdgcn_mfma_f32_16x16x32_bf16(Bt[n][k], At[m][k], acc[ai][bj][m][n], 0, 0, 0); __builtin_amdgcn_s_setprio(0); } while (0)
; #define PG8_WAIT_V(n) asm volatile("s_waitcnt vmcnt(" #n ")" ::: "memory")
; #define PG8_WAIT_L(n) asm volatile("s_waitcnt lgkmcnt(" #n ")" ::: "memory")
; #define PG8_BAR __builtin_amdgcn_s_barrier()
; #define PG8_SCHED __builtin_amdgcn_sched_barrier(0)
; template <class Epi, class Sched>
; __device__ __forceinline__ void gemm_phase(LAS unsigned char* lds, const Gemm g, const Sched& S, const Epi& E) {
;     ...
;     for (int t = 0; t < nt; t += 2) {
;       const bool last = (t == nt - 2);
;       const char* a1 = cA + (size_t)(t + 1) * kstep;
;       const char* a2 = last ? nA : cA + (size_t)(t + 2) * kstep; const char* b2 = last ? nB : cB + (size_t)(t + 2) * kstep;
;       const char* a3 = a2 + kstep; const char* b3 = b2 + kstep;
;       PG8_LDB(B0, 0, 0); PG8_SCHED; PG8_LDA(At, 0, 0); PG8_STAGE(PG8_SA(1, 1), a1 + hstepA, voffA);
;       PG8_WAIT_L(8); PG8_BAR; PG8_WAIT_L(0); PG8_MMA(0, 0, At, B0); PG8_BAR; PG8_SCHED;
;       PG8_LDB(B1, 0, 1); PG8_STAGE(PG8_SB(0, 0), b2, voffB);
;       PG8_BAR; PG8_WAIT_L(0); PG8_MMA(0, 1, At, B1); PG8_BAR;
;       PG8_LDA(At, 0, 1); PG8_STAGE(PG8_SA(0, 0), a2, voffA);
;       PG8_BAR; PG8_WAIT_L(0); PG8_MMA(1, 0, At, B0); PG8_BAR; PG8_SCHED;
;       PG8_STAGE(PG8_SB(0, 1), b2 + hstepB, voffB);
;       PG8_WAIT_V(6); PG8_BAR; PG8_MMA(1, 1, At, B1); PG8_BAR;
.LBB0_2347:
	s_add_u32 s10, s14, 0x100
	s_addc_u32 s11, s15, 0
	s_add_i32 s36, 16, 0x10000
	v_add_u32_e32 v149, s36, v146
	ds_read_b128 v[140:143], v149
	ds_read_b128 v[150:153], v149 offset:1024
	ds_read_b128 v[154:157], v149 offset:2048
	ds_read_b128 v[158:161], v149 offset:3072
	s_cmp_eq_u32 s58, 2
	s_cselect_b32 s19, s5, s11
	s_cselect_b32 s18, s4, s10
	s_cselect_b32 s17, s9, s51
	s_cselect_b32 s16, s8, s49
	v_lshl_add_u64 v[218:219], s[14:15], 0, v[136:137]
	s_add_i32 m0, s24, 0xc000
	ds_read_b128 v[162:165], v148
	ds_read_b128 v[166:169], v148 offset:1024
	ds_read_b128 v[170:173], v148 offset:2048
	ds_read_b128 v[174:177], v148 offset:3072
	ds_read_b128 v[178:181], v148 offset:4096
	ds_read_b128 v[182:185], v148 offset:5120
	ds_read_b128 v[198:201], v148 offset:6144
	ds_read_b128 v[214:217], v148 offset:7168
	global_load_lds_dwordx4 v[218:219], off
	v_lshl_add_u64 v[218:219], s[14:15], 0, v[138:139]
	s_add_i32 m0, s24, 0xe000
	s_nop 0
	global_load_lds_dwordx4 v[218:219], off
	s_waitcnt lgkmcnt(8)
	s_barrier
	s_waitcnt lgkmcnt(0)
	s_setprio 1
	s_waitcnt lgkmcnt(0)
	v_mfma_f32_16x16x32_bf16 v[124:127], v[140:143], v[162:165], v[124:127]
	v_mfma_f32_16x16x32_bf16 v[120:123], v[154:157], v[162:165], v[120:123]
	v_mfma_f32_16x16x32_bf16 v[116:119], v[140:143], v[170:173], v[116:119]
	v_mfma_f32_16x16x32_bf16 v[108:111], v[154:157], v[170:173], v[108:111]
	v_mfma_f32_16x16x32_bf16 v[100:103], v[140:143], v[178:181], v[100:103]
	v_mfma_f32_16x16x32_bf16 v[92:95], v[154:157], v[178:181], v[92:95]
	v_mfma_f32_16x16x32_bf16 v[84:87], v[140:143], v[198:201], v[84:87]
	v_mfma_f32_16x16x32_bf16 v[76:79], v[154:157], v[198:201], v[76:79]
	v_mfma_f32_16x16x32_bf16 v[124:127], v[150:153], v[166:169], v[124:127]
	v_mfma_f32_16x16x32_bf16 v[120:123], v[158:161], v[166:169], v[120:123]
	v_mfma_f32_16x16x32_bf16 v[116:119], v[150:153], v[174:177], v[116:119]
	v_mfma_f32_16x16x32_bf16 v[108:111], v[158:161], v[174:177], v[108:111]
	v_mfma_f32_16x16x32_bf16 v[100:103], v[150:153], v[182:185], v[100:103]
	v_mfma_f32_16x16x32_bf16 v[92:95], v[158:161], v[182:185], v[92:95]
	v_mfma_f32_16x16x32_bf16 v[84:87], v[150:153], v[214:217], v[84:87]
	v_mfma_f32_16x16x32_bf16 v[76:79], v[158:161], v[214:217], v[76:79]
	s_setprio 0
	s_barrier
	s_add_i32 s37, 16, 0x14000
	s_add_i32 s14, s36, s23
	v_add_u32_e32 v149, s37, v146
	v_lshl_add_u64 v[234:235], s[16:17], 0, v[132:133]
	s_mov_b32 m0, s14
	ds_read_b128 v[218:221], v149
	ds_read_b128 v[222:225], v149 offset:1024
	ds_read_b128 v[226:229], v149 offset:2048
	ds_read_b128 v[230:233], v149 offset:3072
	global_load_lds_dwordx4 v[234:235], off
	v_lshl_add_u64 v[236:237], s[16:17], 0, v[128:129]
	s_add_i32 m0, s14, 0x2000
	s_nop 0
	global_load_lds_dwordx4 v[236:237], off
	s_barrier
	s_waitcnt lgkmcnt(0)
	s_setprio 1
	s_waitcnt lgkmcnt(0)
	v_mfma_f32_16x16x32_bf16 v[112:115], v[218:221], v[162:165], v[112:115]
	v_mfma_f32_16x16x32_bf16 v[104:107], v[226:229], v[162:165], v[104:107]
	v_mfma_f32_16x16x32_bf16 v[96:99], v[218:221], v[170:173], v[96:99]
	v_mfma_f32_16x16x32_bf16 v[88:91], v[226:229], v[170:173], v[88:91]
	v_mfma_f32_16x16x32_bf16 v[80:83], v[218:221], v[178:181], v[80:83]
	v_mfma_f32_16x16x32_bf16 v[72:75], v[226:229], v[178:181], v[72:75]
	v_mfma_f32_16x16x32_bf16 v[68:71], v[218:221], v[198:201], v[68:71]
	v_mfma_f32_16x16x32_bf16 v[64:67], v[226:229], v[198:201], v[64:67]
	v_mfma_f32_16x16x32_bf16 v[112:115], v[222:225], v[166:169], v[112:115]
	v_mfma_f32_16x16x32_bf16 v[104:107], v[230:233], v[166:169], v[104:107]
	v_mfma_f32_16x16x32_bf16 v[96:99], v[222:225], v[174:177], v[96:99]
	v_mfma_f32_16x16x32_bf16 v[88:91], v[230:233], v[174:177], v[88:91]
	v_mfma_f32_16x16x32_bf16 v[80:83], v[222:225], v[182:185], v[80:83]
	v_mfma_f32_16x16x32_bf16 v[72:75], v[230:233], v[182:185], v[72:75]
	v_mfma_f32_16x16x32_bf16 v[68:71], v[222:225], v[214:217], v[68:71]
	v_mfma_f32_16x16x32_bf16 v[64:67], v[230:233], v[214:217], v[64:67]
	s_setprio 0
	s_mov_b32 m0, s24
	v_lshl_add_u64 v[238:239], s[18:19], 0, v[134:135]
	s_barrier
	ds_read_b128 v[162:165], v148 offset:16384
	ds_read_b128 v[166:169], v148 offset:17408
	ds_read_b128 v[170:173], v148 offset:18432
	ds_read_b128 v[174:177], v148 offset:19456
	ds_read_b128 v[178:181], v148 offset:20480
	ds_read_b128 v[182:185], v148 offset:21504
	ds_read_b128 v[198:201], v148 offset:22528
	ds_read_b128 v[214:217], v148 offset:23552
	global_load_lds_dwordx4 v[238:239], off
	v_lshl_add_u64 v[240:241], s[18:19], 0, v[130:131]
	s_mov_b32 m0, s25
	s_nop 0
	global_load_lds_dwordx4 v[240:241], off
	s_barrier
	s_waitcnt lgkmcnt(0)
	s_setprio 1
	s_waitcnt lgkmcnt(0)
	v_mfma_f32_16x16x32_bf16 v[60:63], v[140:143], v[162:165], v[60:63]
	v_mfma_f32_16x16x32_bf16 v[56:59], v[154:157], v[162:165], v[56:59]
	v_mfma_f32_16x16x32_bf16 v[52:55], v[140:143], v[170:173], v[52:55]
	v_mfma_f32_16x16x32_bf16 v[44:47], v[154:157], v[170:173], v[44:47]
	v_mfma_f32_16x16x32_bf16 v[36:39], v[140:143], v[178:181], v[36:39]
	v_mfma_f32_16x16x32_bf16 v[28:31], v[154:157], v[178:181], v[28:31]
	v_mfma_f32_16x16x32_bf16 v[20:23], v[140:143], v[198:201], v[20:23]
	v_mfma_f32_16x16x32_bf16 v[12:15], v[154:157], v[198:201], v[12:15]
	v_mfma_f32_16x16x32_bf16 v[60:63], v[150:153], v[166:169], v[60:63]
	v_mfma_f32_16x16x32_bf16 v[56:59], v[158:161], v[166:169], v[56:59]
	v_mfma_f32_16x16x32_bf16 v[52:55], v[150:153], v[174:177], v[52:55]
	v_mfma_f32_16x16x32_bf16 v[44:47], v[158:161], v[174:177], v[44:47]
	v_mfma_f32_16x16x32_bf16 v[36:39], v[150:153], v[182:185], v[36:39]
	v_mfma_f32_16x16x32_bf16 v[28:31], v[158:161], v[182:185], v[28:31]
	v_mfma_f32_16x16x32_bf16 v[20:23], v[150:153], v[214:217], v[20:23]
	v_mfma_f32_16x16x32_bf16 v[12:15], v[158:161], v[214:217], v[12:15]
	s_setprio 0
	s_barrier
; #define PG8_STAGE(bufoff, gbase, voff) do { _Pragma("unroll") for (int _i = 0; _i < 2; ++_i) \
;     __builtin_amdgcn_global_load_lds((const unsigned*)((const char*)(gbase) + (voff)[_i]), (LAS unsigned*)(lds + (bufoff) + ldsw + _i * 8192), 16, 0, 0); } while (0)
; #define PG8_LDA(dst, b, h) do { _Pragma("unroll") for (int m = 0; m < 4; ++m) _Pragma("unroll") for (int k = 0; k < 2; ++k) dst[m][k] = *(const LAS bf16x8*)(lds + PG8_SA(b, h) + aoff + m * 2048 + k * 1024); } while (0)
; #define PG8_LDB(dst, b, h) do { _Pragma("unroll") for (int n = 0; n < 2; ++n) _Pragma("unroll") for (int k = 0; k < 2; ++k) dst[n][k] = *(const LAS bf16x8*)(lds + PG8_SB(b, h) + boff + n * 2048 + k * 1024); } while (0)
; #define PG8_MMA(ai, bj, At, Bt) do { __builtin_amdgcn_s_setprio(1); _Pragma("unroll") for (int m = 0; m < 4; ++m) _Pragma("unroll") for (int n = 0; n < 2; ++n) _Pragma("unroll") for (int k = 0; k < 2; ++k) \
;     acc[ai][bj][m][n] = __builtin_amdgcn_mfma_f32_16x16x32_bf16(Bt[n][k], At[m][k], acc[ai][bj][m][n], 0, 0, 0); __builtin_amdgcn_s_setprio(0); } while (0)
; #define PG8_WAIT_V(n) asm volatile("s_waitcnt vmcnt(" #n ")" ::: "memory")
; #define PG8_WAIT_L(n) asm volatile("s_waitcnt lgkmcnt(" #n ")" ::: "memory")
; #define PG8_BAR __builtin_amdgcn_s_barrier()
; #define PG8_SCHED __builtin_amdgcn_sched_barrier(0)
; template <class Epi, class Sched>
; __device__ __forceinline__ void gemm_phase(LAS unsigned char* lds, const Gemm g, const Sched& S, const Epi& E) {
;     ...
;       PG8_STAGE(PG8_SB(0, 1), b2 + hstepB, voffB);
;       PG8_WAIT_V(6); PG8_BAR; PG8_MMA(1, 1, At, B1); PG8_BAR;
;       PG8_LDB(B0, 1, 0); PG8_SCHED; PG8_LDA(At, 1, 0); PG8_STAGE(PG8_SA(0, 1), a2 + hstepA, voffA);
;       PG8_WAIT_L(8); PG8_BAR; PG8_WAIT_L(0); PG8_MMA(0, 0, At, B0); PG8_BAR; PG8_SCHED;
;       PG8_LDB(B1, 1, 1); PG8_STAGE(PG8_SB(1, 0), b3, voffB);
;       PG8_BAR; PG8_WAIT_L(0); PG8_MMA(0, 1, At, B1); PG8_BAR;
;       PG8_LDA(At, 1, 1); PG8_STAGE(PG8_SA(1, 0), a3, voffA);
;       PG8_BAR; PG8_WAIT_L(0); PG8_MMA(1, 0, At, B0); PG8_BAR; PG8_SCHED;
	s_add_u32 s14, s16, 0x18000
	s_addc_u32 s15, s17, 0
	s_add_i32 s36, s37, s23
	v_lshl_add_u64 v[140:141], s[14:15], 0, v[132:133]
	s_mov_b32 m0, s36
	s_nop 0
	global_load_lds_dwordx4 v[140:141], off
	v_lshl_add_u64 v[140:141], s[14:15], 0, v[128:129]
	s_add_i32 m0, s36, 0x2000
	s_nop 0
	global_load_lds_dwordx4 v[140:141], off
	s_waitcnt vmcnt(6)
	s_barrier
	s_setprio 1
	v_mfma_f32_16x16x32_bf16 v[48:51], v[218:221], v[162:165], v[48:51]
	v_mfma_f32_16x16x32_bf16 v[40:43], v[226:229], v[162:165], v[40:43]
	v_mfma_f32_16x16x32_bf16 v[32:35], v[218:221], v[170:173], v[32:35]
	v_mfma_f32_16x16x32_bf16 v[24:27], v[226:229], v[170:173], v[24:27]
	v_mfma_f32_16x16x32_bf16 v[16:19], v[218:221], v[178:181], v[16:19]
	v_mfma_f32_16x16x32_bf16 v[8:11], v[226:229], v[178:181], v[8:11]
	v_mfma_f32_16x16x32_bf16 v[4:7], v[218:221], v[198:201], v[4:7]
	v_mfma_f32_16x16x32_bf16 v[0:3], v[226:229], v[198:201], v[0:3]
	v_mfma_f32_16x16x32_bf16 v[48:51], v[222:225], v[166:169], v[48:51]
	v_mfma_f32_16x16x32_bf16 v[40:43], v[230:233], v[166:169], v[40:43]
	v_mfma_f32_16x16x32_bf16 v[32:35], v[222:225], v[174:177], v[32:35]
	v_mfma_f32_16x16x32_bf16 v[24:27], v[230:233], v[174:177], v[24:27]
	v_mfma_f32_16x16x32_bf16 v[16:19], v[222:225], v[182:185], v[16:19]
	v_mfma_f32_16x16x32_bf16 v[8:11], v[230:233], v[182:185], v[8:11]
	v_mfma_f32_16x16x32_bf16 v[4:7], v[222:225], v[214:217], v[4:7]
	v_mfma_f32_16x16x32_bf16 v[0:3], v[230:233], v[214:217], v[0:3]
	s_setprio 0
	s_add_i32 s36, 16, 0x18000
	v_add_u32_e32 v149, s36, v146
	s_barrier
	ds_read_b128 v[140:143], v149
	ds_read_b128 v[150:153], v149 offset:1024
	ds_read_b128 v[154:157], v149 offset:2048
	ds_read_b128 v[158:161], v149 offset:3072
	s_add_u32 s14, s18, 0x30000
	s_addc_u32 s15, s19, 0
	s_mov_b32 m0, s26
	v_lshl_add_u64 v[218:219], s[14:15], 0, v[134:135]
	ds_read_b128 v[162:165], v148 offset:32768
	ds_read_b128 v[166:169], v148 offset:33792
	ds_read_b128 v[170:173], v148 offset:34816
	ds_read_b128 v[174:177], v148 offset:35840
	ds_read_b128 v[178:181], v148 offset:36864
	ds_read_b128 v[182:185], v148 offset:37888
	ds_read_b128 v[198:201], v148 offset:38912
	ds_read_b128 v[214:217], v148 offset:39936
	global_load_lds_dwordx4 v[218:219], off
	v_lshl_add_u64 v[218:219], s[14:15], 0, v[130:131]
	s_mov_b32 m0, s27
	s_nop 0
	global_load_lds_dwordx4 v[218:219], off
	s_waitcnt lgkmcnt(8)
	s_barrier
	s_waitcnt lgkmcnt(0)
	s_setprio 1
	s_waitcnt lgkmcnt(0)
	v_mfma_f32_16x16x32_bf16 v[124:127], v[140:143], v[162:165], v[124:127]
	v_mfma_f32_16x16x32_bf16 v[120:123], v[154:157], v[162:165], v[120:123]
	v_mfma_f32_16x16x32_bf16 v[116:119], v[140:143], v[170:173], v[116:119]
	v_mfma_f32_16x16x32_bf16 v[108:111], v[154:157], v[170:173], v[108:111]
	v_mfma_f32_16x16x32_bf16 v[100:103], v[140:143], v[178:181], v[100:103]
	v_mfma_f32_16x16x32_bf16 v[92:95], v[154:157], v[178:181], v[92:95]
	v_mfma_f32_16x16x32_bf16 v[84:87], v[140:143], v[198:201], v[84:87]
	v_mfma_f32_16x16x32_bf16 v[76:79], v[154:157], v[198:201], v[76:79]
	v_mfma_f32_16x16x32_bf16 v[124:127], v[150:153], v[166:169], v[124:127]
	v_mfma_f32_16x16x32_bf16 v[120:123], v[158:161], v[166:169], v[120:123]
	v_mfma_f32_16x16x32_bf16 v[116:119], v[150:153], v[174:177], v[116:119]
	v_mfma_f32_16x16x32_bf16 v[108:111], v[158:161], v[174:177], v[108:111]
	v_mfma_f32_16x16x32_bf16 v[100:103], v[150:153], v[182:185], v[100:103]
	v_mfma_f32_16x16x32_bf16 v[92:95], v[158:161], v[182:185], v[92:95]
	v_mfma_f32_16x16x32_bf16 v[84:87], v[150:153], v[214:217], v[84:87]
	v_mfma_f32_16x16x32_bf16 v[76:79], v[158:161], v[214:217], v[76:79]
	s_setprio 0
	s_barrier
	s_add_i32 s18, 16, 0x1c000
	s_add_i32 s14, s36, s23
	v_add_u32_e32 v149, s18, v146
	v_lshl_add_u64 v[234:235], v[234:235], 0, s[62:63]
	s_mov_b32 m0, s14
	ds_read_b128 v[218:221], v149
	ds_read_b128 v[222:225], v149 offset:1024
	ds_read_b128 v[226:229], v149 offset:2048
	ds_read_b128 v[230:233], v149 offset:3072
	global_load_lds_dwordx4 v[234:235], off
	v_lshl_add_u64 v[234:235], v[236:237], 0, s[62:63]
	s_add_i32 m0, s14, 0x2000
	s_nop 0
	global_load_lds_dwordx4 v[234:235], off
	s_barrier
	s_waitcnt lgkmcnt(0)
	s_setprio 1
	s_waitcnt lgkmcnt(0)
	v_mfma_f32_16x16x32_bf16 v[112:115], v[218:221], v[162:165], v[112:115]
	v_mfma_f32_16x16x32_bf16 v[104:107], v[226:229], v[162:165], v[104:107]
	v_mfma_f32_16x16x32_bf16 v[96:99], v[218:221], v[170:173], v[96:99]
	v_mfma_f32_16x16x32_bf16 v[88:91], v[226:229], v[170:173], v[88:91]
	v_mfma_f32_16x16x32_bf16 v[80:83], v[218:221], v[178:181], v[80:83]
	v_mfma_f32_16x16x32_bf16 v[72:75], v[226:229], v[178:181], v[72:75]
	v_mfma_f32_16x16x32_bf16 v[68:71], v[218:221], v[198:201], v[68:71]
	v_mfma_f32_16x16x32_bf16 v[64:67], v[226:229], v[198:201], v[64:67]
	v_mfma_f32_16x16x32_bf16 v[112:115], v[222:225], v[166:169], v[112:115]
	v_mfma_f32_16x16x32_bf16 v[104:107], v[230:233], v[166:169], v[104:107]
	v_mfma_f32_16x16x32_bf16 v[96:99], v[222:225], v[174:177], v[96:99]
	v_mfma_f32_16x16x32_bf16 v[88:91], v[230:233], v[174:177], v[88:91]
	v_mfma_f32_16x16x32_bf16 v[80:83], v[222:225], v[182:185], v[80:83]
	v_mfma_f32_16x16x32_bf16 v[72:75], v[230:233], v[182:185], v[72:75]
	v_mfma_f32_16x16x32_bf16 v[68:71], v[222:225], v[214:217], v[68:71]
	v_mfma_f32_16x16x32_bf16 v[64:67], v[230:233], v[214:217], v[64:67]
	s_setprio 0
	s_mov_b32 m0, s28
	v_lshl_add_u64 v[234:235], v[238:239], 0, s[62:63]
	s_barrier
	ds_read_b128 v[162:165], v148 offset:49152
	ds_read_b128 v[166:169], v148 offset:50176
	ds_read_b128 v[170:173], v148 offset:51200
	ds_read_b128 v[174:177], v148 offset:52224
	ds_read_b128 v[178:181], v148 offset:53248
	ds_read_b128 v[182:185], v148 offset:54272
	ds_read_b128 v[198:201], v148 offset:55296
	ds_read_b128 v[214:217], v148 offset:56320
	global_load_lds_dwordx4 v[234:235], off
	v_lshl_add_u64 v[234:235], v[240:241], 0, s[62:63]
	s_mov_b32 m0, s29
	s_nop 0
	global_load_lds_dwordx4 v[234:235], off
	s_barrier
; #define PG8_STAGE(bufoff, gbase, voff) do { _Pragma("unroll") for (int _i = 0; _i < 2; ++_i) \
;     __builtin_amdgcn_global_load_lds((const unsigned*)((const char*)(gbase) + (voff)[_i]), (LAS unsigned*)(lds + (bufoff) + ldsw + _i * 8192), 16, 0, 0); } while (0)
; #define PG8_MMA(ai, bj, At, Bt) do { __builtin_amdgcn_s_setprio(1); _Pragma("unroll") for (int m = 0; m < 4; ++m) _Pragma("unroll") for (int n = 0; n < 2; ++n) _Pragma("unroll") for (int k = 0; k < 2; ++k) \
;     acc[ai][bj][m][n] = __builtin_amdgcn_mfma_f32_16x16x32_bf16(Bt[n][k], At[m][k], acc[ai][bj][m][n], 0, 0, 0); __builtin_amdgcn_s_setprio(0); } while (0)
; #define PG8_WAIT_V(n) asm volatile("s_waitcnt vmcnt(" #n ")" ::: "memory")
; #define PG8_WAIT_L(n) asm volatile("s_waitcnt lgkmcnt(" #n ")" ::: "memory")
; #define PG8_BAR __builtin_amdgcn_s_barrier()
; #define PG8_SCHED __builtin_amdgcn_sched_barrier(0)
; template <class Epi, class Sched>
; __device__ __forceinline__ void gemm_phase(LAS unsigned char* lds, const Gemm g, const Sched& S, const Epi& E) {
;     ...
;       PG8_BAR; PG8_WAIT_L(0); PG8_MMA(1, 0, At, B0); PG8_BAR; PG8_SCHED;
;       PG8_STAGE(PG8_SB(1, 1), b3 + hstepB, voffB);
;       PG8_WAIT_V(6); PG8_BAR; PG8_MMA(1, 1, At, B1); PG8_BAR;
	s_waitcnt lgkmcnt(0)
	s_setprio 1
	s_waitcnt lgkmcnt(0)
	v_mfma_f32_16x16x32_bf16 v[60:63], v[140:143], v[162:165], v[60:63]
	v_mfma_f32_16x16x32_bf16 v[56:59], v[154:157], v[162:165], v[56:59]
	v_mfma_f32_16x16x32_bf16 v[52:55], v[140:143], v[170:173], v[52:55]
	v_mfma_f32_16x16x32_bf16 v[44:47], v[154:157], v[170:173], v[44:47]
	v_mfma_f32_16x16x32_bf16 v[36:39], v[140:143], v[178:181], v[36:39]
	v_mfma_f32_16x16x32_bf16 v[28:31], v[154:157], v[178:181], v[28:31]
	v_mfma_f32_16x16x32_bf16 v[20:23], v[140:143], v[198:201], v[20:23]
	v_mfma_f32_16x16x32_bf16 v[12:15], v[154:157], v[198:201], v[12:15]
	v_mfma_f32_16x16x32_bf16 v[60:63], v[150:153], v[166:169], v[60:63]
	v_mfma_f32_16x16x32_bf16 v[56:59], v[158:161], v[166:169], v[56:59]
	v_mfma_f32_16x16x32_bf16 v[52:55], v[150:153], v[174:177], v[52:55]
	v_mfma_f32_16x16x32_bf16 v[44:47], v[158:161], v[174:177], v[44:47]
	v_mfma_f32_16x16x32_bf16 v[36:39], v[150:153], v[182:185], v[36:39]
	v_mfma_f32_16x16x32_bf16 v[28:31], v[158:161], v[182:185], v[28:31]
	v_mfma_f32_16x16x32_bf16 v[20:23], v[150:153], v[214:217], v[20:23]
	v_mfma_f32_16x16x32_bf16 v[12:15], v[158:161], v[214:217], v[12:15]
	s_setprio 0
	s_barrier
	s_add_u32 s14, s16, 0x18080
	s_addc_u32 s15, s17, 0
	s_add_i32 s16, s18, s23
	v_lshl_add_u64 v[140:141], s[14:15], 0, v[132:133]
	s_mov_b32 m0, s16
	s_nop 0
	global_load_lds_dwordx4 v[140:141], off
	v_lshl_add_u64 v[140:141], s[14:15], 0, v[128:129]
	s_add_i32 m0, s16, 0x2000
	s_nop 0
	global_load_lds_dwordx4 v[140:141], off
	s_waitcnt vmcnt(6)
	s_barrier
	s_setprio 1
	v_mfma_f32_16x16x32_bf16 v[48:51], v[218:221], v[162:165], v[48:51]
	v_mfma_f32_16x16x32_bf16 v[40:43], v[226:229], v[162:165], v[40:43]
	v_mfma_f32_16x16x32_bf16 v[32:35], v[218:221], v[170:173], v[32:35]
	v_mfma_f32_16x16x32_bf16 v[24:27], v[226:229], v[170:173], v[24:27]
	v_mfma_f32_16x16x32_bf16 v[16:19], v[218:221], v[178:181], v[16:19]
	v_mfma_f32_16x16x32_bf16 v[8:11], v[226:229], v[178:181], v[8:11]
	v_mfma_f32_16x16x32_bf16 v[4:7], v[218:221], v[198:201], v[4:7]
	v_mfma_f32_16x16x32_bf16 v[0:3], v[226:229], v[198:201], v[0:3]
	v_mfma_f32_16x16x32_bf16 v[48:51], v[222:225], v[166:169], v[48:51]
	v_mfma_f32_16x16x32_bf16 v[40:43], v[230:233], v[166:169], v[40:43]
	v_mfma_f32_16x16x32_bf16 v[32:35], v[222:225], v[174:177], v[32:35]
	v_mfma_f32_16x16x32_bf16 v[24:27], v[230:233], v[174:177], v[24:27]
	v_mfma_f32_16x16x32_bf16 v[16:19], v[222:225], v[182:185], v[16:19]
	v_mfma_f32_16x16x32_bf16 v[8:11], v[230:233], v[182:185], v[8:11]
	v_mfma_f32_16x16x32_bf16 v[4:7], v[222:225], v[214:217], v[4:7]
	v_mfma_f32_16x16x32_bf16 v[0:3], v[230:233], v[214:217], v[0:3]
	s_setprio 0
	s_add_i32 s58, s58, 2
	s_add_u32 s49, s49, 0x100
	s_addc_u32 s51, s51, 0
	s_cmp_gt_u32 s58, 3
	s_mov_b64 s[14:15], s[10:11]
	s_barrier
	s_cbranch_scc0 .LBB0_2347
	v_lshl_or_b32 v142, s45, 8, v147
	v_and_b32_e32 v250, 16, v187
	v_lshrrev_b32_e32 v251, 2, v250
	v_sub_u32_e32 v250, v250, v251
	v_add_u32_e32 v142, v142, v250
	v_lshl_add_u32 v149, s48, 8, v145
	v_mov_b64_e32 v[140:141], s[12:13]
	v_ashrrev_i32_e32 v143, 31, v142
	v_mad_i64_i32 v[150:151], s[10:11], v149, s40, v[140:141]
	v_lshlrev_b64 v[142:143], 1, v[142:143]
	v_lshl_add_u64 v[150:151], v[150:151], 0, v[142:143]
	v_cvt_pk_bf16_f32 v242, v124, v125
	v_cvt_pk_bf16_f32 v243, v126, v127
	v_cvt_pk_bf16_f32 v244, v120, v121
	v_cvt_pk_bf16_f32 v245, v122, v123
	s_nop 1
	v_permlane16_swap_b32_e32 v242, v244
	v_permlane16_swap_b32_e32 v243, v245
	global_store_dwordx4 v[150:151], v[242:245], off
	v_cvt_pk_bf16_f32 v246, v112, v113
	v_cvt_pk_bf16_f32 v247, v114, v115
	v_cvt_pk_bf16_f32 v248, v104, v105
	v_cvt_pk_bf16_f32 v249, v106, v107
	s_nop 1
	v_permlane16_swap_b32_e32 v246, v248
	v_permlane16_swap_b32_e32 v247, v249
	global_store_dwordx4 v[150:151], v[246:249], off offset:256
	v_or_b32_e32 v104, 16, v149
	v_mad_i64_i32 v[104:105], s[10:11], v104, s40, v[140:141]
	v_lshl_add_u64 v[104:105], v[104:105], 0, v[142:143]
	v_cvt_pk_bf16_f32 v242, v116, v117
	v_cvt_pk_bf16_f32 v243, v118, v119
	v_cvt_pk_bf16_f32 v244, v108, v109
	v_cvt_pk_bf16_f32 v245, v110, v111
	s_nop 1
	v_permlane16_swap_b32_e32 v242, v244
	v_permlane16_swap_b32_e32 v243, v245
	global_store_dwordx4 v[104:105], v[242:245], off
	v_cvt_pk_bf16_f32 v246, v96, v97
	v_cvt_pk_bf16_f32 v247, v98, v99
	v_cvt_pk_bf16_f32 v248, v88, v89
	v_cvt_pk_bf16_f32 v249, v90, v91
	s_nop 1
	v_permlane16_swap_b32_e32 v246, v248
	v_permlane16_swap_b32_e32 v247, v249
	global_store_dwordx4 v[104:105], v[246:249], off offset:256
	v_or_b32_e32 v88, 32, v149
	v_mad_i64_i32 v[88:89], s[10:11], v88, s40, v[140:141]
	v_lshl_add_u64 v[88:89], v[88:89], 0, v[142:143]
	v_cvt_pk_bf16_f32 v242, v100, v101
	v_cvt_pk_bf16_f32 v243, v102, v103
	v_cvt_pk_bf16_f32 v244, v92, v93
	v_cvt_pk_bf16_f32 v245, v94, v95
	s_nop 1
	v_permlane16_swap_b32_e32 v242, v244
	v_permlane16_swap_b32_e32 v243, v245
	global_store_dwordx4 v[88:89], v[242:245], off
	v_cvt_pk_bf16_f32 v246, v80, v81
	v_cvt_pk_bf16_f32 v247, v82, v83
	v_cvt_pk_bf16_f32 v248, v72, v73
	v_cvt_pk_bf16_f32 v249, v74, v75
	s_nop 1
	v_permlane16_swap_b32_e32 v246, v248
	v_permlane16_swap_b32_e32 v247, v249
	global_store_dwordx4 v[88:89], v[246:249], off offset:256
	v_or_b32_e32 v72, 48, v149
	v_mad_i64_i32 v[72:73], s[10:11], v72, s40, v[140:141]
	v_lshl_add_u64 v[72:73], v[72:73], 0, v[142:143]
	v_cvt_pk_bf16_f32 v242, v84, v85
	v_cvt_pk_bf16_f32 v243, v86, v87
	v_cvt_pk_bf16_f32 v244, v76, v77
	v_cvt_pk_bf16_f32 v245, v78, v79
	s_nop 1
	v_permlane16_swap_b32_e32 v242, v244
	v_permlane16_swap_b32_e32 v243, v245
	global_store_dwordx4 v[72:73], v[242:245], off
	v_cvt_pk_bf16_f32 v246, v68, v69
	v_cvt_pk_bf16_f32 v247, v70, v71
	v_cvt_pk_bf16_f32 v248, v64, v65
	v_cvt_pk_bf16_f32 v249, v66, v67
	s_nop 1
	v_permlane16_swap_b32_e32 v246, v248
	v_permlane16_swap_b32_e32 v247, v249
	global_store_dwordx4 v[72:73], v[246:249], off offset:256
	v_add_u32_e32 v64, 0x80, v149
	v_mad_i64_i32 v[64:65], s[10:11], v64, s40, v[140:141]
	v_lshl_add_u64 v[64:65], v[64:65], 0, v[142:143]
	v_cvt_pk_bf16_f32 v242, v60, v61
	v_cvt_pk_bf16_f32 v243, v62, v63
	v_cvt_pk_bf16_f32 v244, v56, v57
	v_cvt_pk_bf16_f32 v245, v58, v59
	s_nop 1
	v_permlane16_swap_b32_e32 v242, v244
	v_permlane16_swap_b32_e32 v243, v245
	global_store_dwordx4 v[64:65], v[242:245], off
	v_cvt_pk_bf16_f32 v246, v48, v49
	v_cvt_pk_bf16_f32 v247, v50, v51
	v_cvt_pk_bf16_f32 v248, v40, v41
	v_cvt_pk_bf16_f32 v249, v42, v43
	s_nop 1
	v_permlane16_swap_b32_e32 v246, v248
	v_permlane16_swap_b32_e32 v247, v249
	global_store_dwordx4 v[64:65], v[246:249], off offset:256
	v_add_u32_e32 v40, 0x90, v149
	v_mad_i64_i32 v[40:41], s[10:11], v40, s40, v[140:141]
	v_lshl_add_u64 v[40:41], v[40:41], 0, v[142:143]
	v_cvt_pk_bf16_f32 v242, v52, v53
	v_cvt_pk_bf16_f32 v243, v54, v55
	v_cvt_pk_bf16_f32 v244, v44, v45
	v_cvt_pk_bf16_f32 v245, v46, v47
	s_nop 1
	v_permlane16_swap_b32_e32 v242, v244
	v_permlane16_swap_b32_e32 v243, v245
	global_store_dwordx4 v[40:41], v[242:245], off
	v_cvt_pk_bf16_f32 v246, v32, v33
	v_cvt_pk_bf16_f32 v247, v34, v35
	v_cvt_pk_bf16_f32 v248, v24, v25
	v_cvt_pk_bf16_f32 v249, v26, v27
	s_nop 1
	v_permlane16_swap_b32_e32 v246, v248
	v_permlane16_swap_b32_e32 v247, v249
	global_store_dwordx4 v[40:41], v[246:249], off offset:256
	v_add_u32_e32 v24, 0xa0, v149
	v_mad_i64_i32 v[24:25], s[10:11], v24, s40, v[140:141]
	v_lshl_add_u64 v[24:25], v[24:25], 0, v[142:143]
	v_cvt_pk_bf16_f32 v242, v36, v37
	v_cvt_pk_bf16_f32 v243, v38, v39
	v_cvt_pk_bf16_f32 v244, v28, v29
	v_cvt_pk_bf16_f32 v245, v30, v31
	s_nop 1
	v_permlane16_swap_b32_e32 v242, v244
	v_permlane16_swap_b32_e32 v243, v245
	global_store_dwordx4 v[24:25], v[242:245], off
	v_cvt_pk_bf16_f32 v246, v16, v17
	v_cvt_pk_bf16_f32 v247, v18, v19
	v_cvt_pk_bf16_f32 v248, v8, v9
	v_cvt_pk_bf16_f32 v249, v10, v11
	s_nop 1
	v_permlane16_swap_b32_e32 v246, v248
	v_permlane16_swap_b32_e32 v247, v249
	global_store_dwordx4 v[24:25], v[246:249], off offset:256
	v_add_u32_e32 v8, 0xb0, v149
	v_mad_i64_i32 v[8:9], s[10:11], v8, s40, v[140:141]
	v_lshl_add_u64 v[8:9], v[8:9], 0, v[142:143]
	v_cvt_pk_bf16_f32 v242, v20, v21
	v_cvt_pk_bf16_f32 v243, v22, v23
	s_and_b64 vcc, exec, s[6:7]
	s_mov_b32 s45, s39
	s_mov_b32 s48, s44
	s_mov_b64 s[16:17], s[8:9]
	s_mov_b64 s[14:15], s[4:5]
	s_movk_i32 s58, 0x6000
	s_movk_i32 s51, 0x4000
	v_cvt_pk_bf16_f32 v244, v12, v13
	v_cvt_pk_bf16_f32 v245, v14, v15
	s_nop 1
	v_permlane16_swap_b32_e32 v242, v244
	v_permlane16_swap_b32_e32 v243, v245
	global_store_dwordx4 v[8:9], v[242:245], off
	v_cvt_pk_bf16_f32 v246, v4, v5
	v_cvt_pk_bf16_f32 v247, v6, v7
	v_cvt_pk_bf16_f32 v248, v0, v1
	v_cvt_pk_bf16_f32 v249, v2, v3
	s_nop 1
	v_permlane16_swap_b32_e32 v246, v248
	v_permlane16_swap_b32_e32 v247, v249
	global_store_dwordx4 v[8:9], v[246:249], off offset:256
	s_cbranch_vccz .LBB0_2336
	s_waitcnt vmcnt(0)
	s_cmpk_gt_u32 s20, 0xff
	v_readlane_b32 s44, v255, 32
	v_readlane_b32 s45, v255, 33
	s_cbranch_scc1 .LBB0_2351
	s_barrier

; #define PG8_STAGE(bufoff, gbase, voff) do { _Pragma("unroll") for (int _i = 0; _i < 2; ++_i) \
;     __builtin_amdgcn_global_load_lds((const unsigned*)((const char*)(gbase) + (voff)[_i]), (LAS unsigned*)(lds + (bufoff) + ldsw + _i * 8192), 16, 0, 0); } while (0)
; #define PG8_LDA(dst, b, h) do { _Pragma("unroll") for (int m = 0; m < 4; ++m) _Pragma("unroll") for (int k = 0; k < 2; ++k) dst[m][k] = *(const LAS bf16x8*)(lds + PG8_SA(b, h) + aoff + m * 2048 + k * 1024); } while (0)
; #define PG8_LDB(dst, b, h) do { _Pragma("unroll") for (int n = 0; n < 2; ++n) _Pragma("unroll") for (int k = 0; k < 2; ++k) dst[n][k] = *(const LAS bf16x8*)(lds + PG8_SB(b, h) + boff + n * 2048 + k * 1024); } while (0)
; #define PG8_MMA(ai, bj, At, Bt) do { __builtin_amdgcn_s_setprio(1); _Pragma("unroll") for (int m = 0; m < 4; ++m) _Pragma("unroll") for (int n = 0; n < 2; ++n) _Pragma("unroll") for (int k = 0; k < 2; ++k) \
;     acc[ai][bj][m][n] = __builtin_amdgcn_mfma_f32_16x16x32_bf16(Bt[n][k], At[m][k], acc[ai][bj][m][n], 0, 0, 0); __builtin_amdgcn_s_setprio(0); } while (0)
; #define PG8_WAIT_V(n) asm volatile("s_waitcnt vmcnt(" #n ")" ::: "memory")
; #define PG8_WAIT_L(n) asm volatile("s_waitcnt lgkmcnt(" #n ")" ::: "memory")
; #define PG8_BAR __builtin_amdgcn_s_barrier()
; #define PG8_SCHED __builtin_amdgcn_sched_barrier(0)
; template <class Epi, class Sched>
; __device__ __forceinline__ void gemm_phase(LAS unsigned char* lds, const Gemm g, const Sched& S, const Epi& E) {
;     ...
;     for (int t = 0; t < nt; t += 2) {
;       const bool last = (t == nt - 2);
;       const char* a1 = cA + (size_t)(t + 1) * kstep;
;       const char* a2 = last ? nA : cA + (size_t)(t + 2) * kstep; const char* b2 = last ? nB : cB + (size_t)(t + 2) * kstep;
;       const char* a3 = a2 + kstep; const char* b3 = b2 + kstep;
;       PG8_LDB(B0, 0, 0); PG8_SCHED; PG8_LDA(At, 0, 0); PG8_STAGE(PG8_SA(1, 1), a1 + hstepA, voffA);
;       PG8_WAIT_L(8); PG8_BAR; PG8_WAIT_L(0); PG8_MMA(0, 0, At, B0); PG8_BAR; PG8_SCHED;
;       PG8_LDB(B1, 0, 1); PG8_STAGE(PG8_SB(0, 0), b2, voffB);
;       PG8_BAR; PG8_WAIT_L(0); PG8_MMA(0, 1, At, B1); PG8_BAR;
;       PG8_LDA(At, 0, 1); PG8_STAGE(PG8_SA(0, 0), a2, voffA);
;       PG8_BAR; PG8_WAIT_L(0); PG8_MMA(1, 0, At, B0); PG8_BAR; PG8_SCHED;
;       PG8_STAGE(PG8_SB(0, 1), b2 + hstepB, voffB);
;       PG8_WAIT_V(6); PG8_BAR; PG8_MMA(1, 1, At, B1); PG8_BAR;
.LBB0_2365:
	s_add_u32 s23, s18, s22
	s_addc_u32 s36, s19, 0
	s_add_u32 s28, s23, 0x100
	s_addc_u32 s29, s36, 0
	s_and_b64 s[26:27], s[20:21], exec
	s_cselect_b32 s29, s11, s29
	s_cselect_b32 s28, s10, s28
	s_add_u32 s22, s14, s22
	s_addc_u32 s26, s15, 0
	s_add_u32 s22, s22, 0x100
	s_addc_u32 s26, s26, 0
	s_add_i32 s37, 16, 0x10000
	s_and_b64 s[20:21], s[20:21], exec
	s_cselect_b32 s39, s5, s26
	s_cselect_b32 s38, s83, s22
	s_add_u32 s48, s23, 0x30080
	s_addc_u32 s49, s36, 0
	s_add_i32 vcc_lo, s37, s58
	s_add_i32 m0, s59, 0xc000
	s_add_i32 s36, s59, 0xe000
	s_add_i32 s95, 16, 0x14000
	s_add_i32 s94, vcc_lo, 0x2000
	s_add_u32 s26, s38, 0x10000
	v_add_u32_e32 v145, s37, v141
	s_addc_u32 s27, s39, 0
	s_add_i32 s89, s95, s58
	ds_read_b128 v[136:139], v145
	ds_read_b128 v[146:149], v145 offset:1024
	ds_read_b128 v[150:153], v145 offset:2048
	ds_read_b128 v[154:157], v145 offset:3072
	s_add_i32 s88, s89, 0x2000
	s_add_i32 s87, 16, 0x18000
	s_add_u32 s22, s28, 0x30000
	s_addc_u32 s23, s29, 0
	s_add_i32 s86, s87, s58
	s_add_i32 s85, 16, 0x1c000
	s_add_i32 s84, s86, 0x2000
	s_add_u32 s20, s38, 0x10080
	s_addc_u32 s21, s39, 0
	s_add_i32 s91, s85, s58
	s_add_i32 s90, s91, 0x2000
	v_lshl_add_u64 v[214:215], s[48:49], 0, v[134:135]
	ds_read_b128 v[158:161], v143
	ds_read_b128 v[162:165], v143 offset:1024
	ds_read_b128 v[166:169], v143 offset:2048
	ds_read_b128 v[170:173], v143 offset:3072
	ds_read_b128 v[174:177], v143 offset:4096
	ds_read_b128 v[178:181], v143 offset:5120
	ds_read_b128 v[182:185], v143 offset:6144
	ds_read_b128 v[198:201], v143 offset:7168
	global_load_lds_dwordx4 v[214:215], off
	v_lshl_add_u64 v[214:215], s[48:49], 0, v[130:131]
	s_mov_b32 m0, s36
	s_nop 0
	global_load_lds_dwordx4 v[214:215], off
	s_waitcnt lgkmcnt(8)
	s_barrier
	s_waitcnt lgkmcnt(0)
	s_setprio 1
	s_waitcnt lgkmcnt(0)
	v_mfma_f32_16x16x32_bf16 v[124:127], v[136:139], v[158:161], v[124:127]
	v_mfma_f32_16x16x32_bf16 v[120:123], v[150:153], v[158:161], v[120:123]
	v_mfma_f32_16x16x32_bf16 v[116:119], v[136:139], v[166:169], v[116:119]
	v_mfma_f32_16x16x32_bf16 v[108:111], v[150:153], v[166:169], v[108:111]
	v_mfma_f32_16x16x32_bf16 v[100:103], v[136:139], v[174:177], v[100:103]
	v_mfma_f32_16x16x32_bf16 v[92:95], v[150:153], v[174:177], v[92:95]
	v_mfma_f32_16x16x32_bf16 v[84:87], v[136:139], v[182:185], v[84:87]
	v_mfma_f32_16x16x32_bf16 v[76:79], v[150:153], v[182:185], v[76:79]
	v_mfma_f32_16x16x32_bf16 v[124:127], v[146:149], v[162:165], v[124:127]
	v_mfma_f32_16x16x32_bf16 v[120:123], v[154:157], v[162:165], v[120:123]
	v_mfma_f32_16x16x32_bf16 v[116:119], v[146:149], v[170:173], v[116:119]
	v_mfma_f32_16x16x32_bf16 v[108:111], v[154:157], v[170:173], v[108:111]
	v_mfma_f32_16x16x32_bf16 v[100:103], v[146:149], v[178:181], v[100:103]
	v_mfma_f32_16x16x32_bf16 v[92:95], v[154:157], v[178:181], v[92:95]
	v_mfma_f32_16x16x32_bf16 v[84:87], v[146:149], v[198:201], v[84:87]
	v_mfma_f32_16x16x32_bf16 v[76:79], v[154:157], v[198:201], v[76:79]
	s_setprio 0
	s_barrier
	s_mov_b32 m0, vcc_lo
	v_add_u32_e32 v145, s95, v141
	v_lshl_add_u64 v[230:231], s[38:39], 0, v[132:133]
	ds_read_b128 v[214:217], v145
	ds_read_b128 v[218:221], v145 offset:1024
	ds_read_b128 v[222:225], v145 offset:2048
	ds_read_b128 v[226:229], v145 offset:3072
	global_load_lds_dwordx4 v[230:231], off
	v_lshl_add_u64 v[232:233], s[38:39], 0, v[128:129]
	s_mov_b32 m0, s94
	s_nop 0
	global_load_lds_dwordx4 v[232:233], off
	s_barrier
	s_waitcnt lgkmcnt(0)
	s_setprio 1
	s_waitcnt lgkmcnt(0)
	v_mfma_f32_16x16x32_bf16 v[112:115], v[214:217], v[158:161], v[112:115]
	v_mfma_f32_16x16x32_bf16 v[104:107], v[222:225], v[158:161], v[104:107]
	v_mfma_f32_16x16x32_bf16 v[96:99], v[214:217], v[166:169], v[96:99]
	v_mfma_f32_16x16x32_bf16 v[88:91], v[222:225], v[166:169], v[88:91]
	v_mfma_f32_16x16x32_bf16 v[80:83], v[214:217], v[174:177], v[80:83]
	v_mfma_f32_16x16x32_bf16 v[72:75], v[222:225], v[174:177], v[72:75]
	v_mfma_f32_16x16x32_bf16 v[68:71], v[214:217], v[182:185], v[68:71]
	v_mfma_f32_16x16x32_bf16 v[64:67], v[222:225], v[182:185], v[64:67]
	v_mfma_f32_16x16x32_bf16 v[112:115], v[218:221], v[162:165], v[112:115]
	v_mfma_f32_16x16x32_bf16 v[104:107], v[226:229], v[162:165], v[104:107]
	v_mfma_f32_16x16x32_bf16 v[96:99], v[218:221], v[170:173], v[96:99]
	v_mfma_f32_16x16x32_bf16 v[88:91], v[226:229], v[170:173], v[88:91]
	v_mfma_f32_16x16x32_bf16 v[80:83], v[218:221], v[178:181], v[80:83]
	v_mfma_f32_16x16x32_bf16 v[72:75], v[226:229], v[178:181], v[72:75]
	v_mfma_f32_16x16x32_bf16 v[68:71], v[218:221], v[198:201], v[68:71]
	v_mfma_f32_16x16x32_bf16 v[64:67], v[226:229], v[198:201], v[64:67]
	s_setprio 0
	s_mov_b32 m0, s59
	v_lshl_add_u64 v[234:235], s[28:29], 0, v[134:135]
	s_barrier
	ds_read_b128 v[158:161], v143 offset:16384
	ds_read_b128 v[162:165], v143 offset:17408
	ds_read_b128 v[166:169], v143 offset:18432
	ds_read_b128 v[170:173], v143 offset:19456
	ds_read_b128 v[174:177], v143 offset:20480
	ds_read_b128 v[178:181], v143 offset:21504
	ds_read_b128 v[182:185], v143 offset:22528
	ds_read_b128 v[198:201], v143 offset:23552
	global_load_lds_dwordx4 v[234:235], off
	v_lshl_add_u64 v[236:237], s[28:29], 0, v[130:131]
	s_mov_b32 m0, s66
	s_nop 0
	global_load_lds_dwordx4 v[236:237], off
	s_barrier
; #define PG8_STAGE(bufoff, gbase, voff) do { _Pragma("unroll") for (int _i = 0; _i < 2; ++_i) \
;     __builtin_amdgcn_global_load_lds((const unsigned*)((const char*)(gbase) + (voff)[_i]), (LAS unsigned*)(lds + (bufoff) + ldsw + _i * 8192), 16, 0, 0); } while (0)
; #define PG8_LDA(dst, b, h) do { _Pragma("unroll") for (int m = 0; m < 4; ++m) _Pragma("unroll") for (int k = 0; k < 2; ++k) dst[m][k] = *(const LAS bf16x8*)(lds + PG8_SA(b, h) + aoff + m * 2048 + k * 1024); } while (0)
; #define PG8_LDB(dst, b, h) do { _Pragma("unroll") for (int n = 0; n < 2; ++n) _Pragma("unroll") for (int k = 0; k < 2; ++k) dst[n][k] = *(const LAS bf16x8*)(lds + PG8_SB(b, h) + boff + n * 2048 + k * 1024); } while (0)
; #define PG8_MMA(ai, bj, At, Bt) do { __builtin_amdgcn_s_setprio(1); _Pragma("unroll") for (int m = 0; m < 4; ++m) _Pragma("unroll") for (int n = 0; n < 2; ++n) _Pragma("unroll") for (int k = 0; k < 2; ++k) \
;     acc[ai][bj][m][n] = __builtin_amdgcn_mfma_f32_16x16x32_bf16(Bt[n][k], At[m][k], acc[ai][bj][m][n], 0, 0, 0); __builtin_amdgcn_s_setprio(0); } while (0)
; #define PG8_WAIT_V(n) asm volatile("s_waitcnt vmcnt(" #n ")" ::: "memory")
; #define PG8_WAIT_L(n) asm volatile("s_waitcnt lgkmcnt(" #n ")" ::: "memory")
; #define PG8_BAR __builtin_amdgcn_s_barrier()
; #define PG8_SCHED __builtin_amdgcn_sched_barrier(0)
; template <class Epi, class Sched>
; __device__ __forceinline__ void gemm_phase(LAS unsigned char* lds, const Gemm g, const Sched& S, const Epi& E) {
;     ...
;       PG8_STAGE(PG8_SB(0, 1), b2 + hstepB, voffB);
;       PG8_WAIT_V(6); PG8_BAR; PG8_MMA(1, 1, At, B1); PG8_BAR;
;       PG8_LDB(B0, 1, 0); PG8_SCHED; PG8_LDA(At, 1, 0); PG8_STAGE(PG8_SA(0, 1), a2 + hstepA, voffA);
;       PG8_WAIT_L(8); PG8_BAR; PG8_WAIT_L(0); PG8_MMA(0, 0, At, B0); PG8_BAR; PG8_SCHED;
;       PG8_LDB(B1, 1, 1); PG8_STAGE(PG8_SB(1, 0), b3, voffB);
;       PG8_BAR; PG8_WAIT_L(0); PG8_MMA(0, 1, At, B1); PG8_BAR;
;       PG8_LDA(At, 1, 1); PG8_STAGE(PG8_SA(1, 0), a3, voffA);
;       PG8_BAR; PG8_WAIT_L(0); PG8_MMA(1, 0, At, B0); PG8_BAR; PG8_SCHED;
	s_waitcnt lgkmcnt(0)
	s_setprio 1
	s_waitcnt lgkmcnt(0)
	v_mfma_f32_16x16x32_bf16 v[60:63], v[136:139], v[158:161], v[60:63]
	v_mfma_f32_16x16x32_bf16 v[56:59], v[150:153], v[158:161], v[56:59]
	v_mfma_f32_16x16x32_bf16 v[52:55], v[136:139], v[166:169], v[52:55]
	v_mfma_f32_16x16x32_bf16 v[44:47], v[150:153], v[166:169], v[44:47]
	v_mfma_f32_16x16x32_bf16 v[36:39], v[136:139], v[174:177], v[36:39]
	v_mfma_f32_16x16x32_bf16 v[28:31], v[150:153], v[174:177], v[28:31]
	v_mfma_f32_16x16x32_bf16 v[20:23], v[136:139], v[182:185], v[20:23]
	v_mfma_f32_16x16x32_bf16 v[12:15], v[150:153], v[182:185], v[12:15]
	v_mfma_f32_16x16x32_bf16 v[60:63], v[146:149], v[162:165], v[60:63]
	v_mfma_f32_16x16x32_bf16 v[56:59], v[154:157], v[162:165], v[56:59]
	v_mfma_f32_16x16x32_bf16 v[52:55], v[146:149], v[170:173], v[52:55]
	v_mfma_f32_16x16x32_bf16 v[44:47], v[154:157], v[170:173], v[44:47]
	v_mfma_f32_16x16x32_bf16 v[36:39], v[146:149], v[178:181], v[36:39]
	v_mfma_f32_16x16x32_bf16 v[28:31], v[154:157], v[178:181], v[28:31]
	v_mfma_f32_16x16x32_bf16 v[20:23], v[146:149], v[198:201], v[20:23]
	v_mfma_f32_16x16x32_bf16 v[12:15], v[154:157], v[198:201], v[12:15]
	s_setprio 0
	s_barrier
	s_mov_b32 m0, s89
	v_lshl_add_u64 v[136:137], s[26:27], 0, v[132:133]
	global_load_lds_dwordx4 v[136:137], off
	v_lshl_add_u64 v[136:137], s[26:27], 0, v[128:129]
	s_mov_b32 m0, s88
	s_nop 0
	global_load_lds_dwordx4 v[136:137], off
	s_waitcnt vmcnt(6)
	s_barrier
	s_setprio 1
	v_mfma_f32_16x16x32_bf16 v[48:51], v[214:217], v[158:161], v[48:51]
	v_mfma_f32_16x16x32_bf16 v[40:43], v[222:225], v[158:161], v[40:43]
	v_mfma_f32_16x16x32_bf16 v[32:35], v[214:217], v[166:169], v[32:35]
	v_mfma_f32_16x16x32_bf16 v[24:27], v[222:225], v[166:169], v[24:27]
	v_mfma_f32_16x16x32_bf16 v[16:19], v[214:217], v[174:177], v[16:19]
	v_mfma_f32_16x16x32_bf16 v[8:11], v[222:225], v[174:177], v[8:11]
	v_mfma_f32_16x16x32_bf16 v[4:7], v[214:217], v[182:185], v[4:7]
	v_mfma_f32_16x16x32_bf16 v[0:3], v[222:225], v[182:185], v[0:3]
	v_mfma_f32_16x16x32_bf16 v[48:51], v[218:221], v[162:165], v[48:51]
	v_mfma_f32_16x16x32_bf16 v[40:43], v[226:229], v[162:165], v[40:43]
	v_mfma_f32_16x16x32_bf16 v[32:35], v[218:221], v[170:173], v[32:35]
	v_mfma_f32_16x16x32_bf16 v[24:27], v[226:229], v[170:173], v[24:27]
	v_mfma_f32_16x16x32_bf16 v[16:19], v[218:221], v[178:181], v[16:19]
	v_mfma_f32_16x16x32_bf16 v[8:11], v[226:229], v[178:181], v[8:11]
	v_mfma_f32_16x16x32_bf16 v[4:7], v[218:221], v[198:201], v[4:7]
	v_mfma_f32_16x16x32_bf16 v[0:3], v[226:229], v[198:201], v[0:3]
	s_setprio 0
	v_add_u32_e32 v145, s87, v141
	s_barrier
	ds_read_b128 v[136:139], v145
	ds_read_b128 v[146:149], v145 offset:1024
	ds_read_b128 v[150:153], v145 offset:2048
	ds_read_b128 v[154:157], v145 offset:3072
	s_mov_b32 m0, s67
	v_lshl_add_u64 v[214:215], s[22:23], 0, v[134:135]
	ds_read_b128 v[158:161], v143 offset:32768
	ds_read_b128 v[162:165], v143 offset:33792
	ds_read_b128 v[166:169], v143 offset:34816
	ds_read_b128 v[170:173], v143 offset:35840
	ds_read_b128 v[174:177], v143 offset:36864
	ds_read_b128 v[178:181], v143 offset:37888
	ds_read_b128 v[182:185], v143 offset:38912
	ds_read_b128 v[198:201], v143 offset:39936
	global_load_lds_dwordx4 v[214:215], off
	v_lshl_add_u64 v[214:215], s[22:23], 0, v[130:131]
	s_mov_b32 m0, s68
	s_nop 0
	global_load_lds_dwordx4 v[214:215], off
	s_waitcnt lgkmcnt(8)
	s_barrier
	s_waitcnt lgkmcnt(0)
	s_setprio 1
	s_waitcnt lgkmcnt(0)
	v_mfma_f32_16x16x32_bf16 v[124:127], v[136:139], v[158:161], v[124:127]
	v_mfma_f32_16x16x32_bf16 v[120:123], v[150:153], v[158:161], v[120:123]
	v_mfma_f32_16x16x32_bf16 v[116:119], v[136:139], v[166:169], v[116:119]
	v_mfma_f32_16x16x32_bf16 v[108:111], v[150:153], v[166:169], v[108:111]
	v_mfma_f32_16x16x32_bf16 v[100:103], v[136:139], v[174:177], v[100:103]
	v_mfma_f32_16x16x32_bf16 v[92:95], v[150:153], v[174:177], v[92:95]
	v_mfma_f32_16x16x32_bf16 v[84:87], v[136:139], v[182:185], v[84:87]
	v_mfma_f32_16x16x32_bf16 v[76:79], v[150:153], v[182:185], v[76:79]
	v_mfma_f32_16x16x32_bf16 v[124:127], v[146:149], v[162:165], v[124:127]
	v_mfma_f32_16x16x32_bf16 v[120:123], v[154:157], v[162:165], v[120:123]
	v_mfma_f32_16x16x32_bf16 v[116:119], v[146:149], v[170:173], v[116:119]
	v_mfma_f32_16x16x32_bf16 v[108:111], v[154:157], v[170:173], v[108:111]
	v_mfma_f32_16x16x32_bf16 v[100:103], v[146:149], v[178:181], v[100:103]
	v_mfma_f32_16x16x32_bf16 v[92:95], v[154:157], v[178:181], v[92:95]
	v_mfma_f32_16x16x32_bf16 v[84:87], v[146:149], v[198:201], v[84:87]
	v_mfma_f32_16x16x32_bf16 v[76:79], v[154:157], v[198:201], v[76:79]
	s_setprio 0
	s_barrier
	s_mov_b32 m0, s86
	v_add_u32_e32 v145, s85, v141
	v_lshl_add_u64 v[230:231], v[230:231], 0, s[62:63]
	ds_read_b128 v[214:217], v145
	ds_read_b128 v[218:221], v145 offset:1024
	ds_read_b128 v[222:225], v145 offset:2048
	ds_read_b128 v[226:229], v145 offset:3072
	global_load_lds_dwordx4 v[230:231], off
	v_lshl_add_u64 v[230:231], v[232:233], 0, s[62:63]
	s_mov_b32 m0, s84
	s_nop 0
	global_load_lds_dwordx4 v[230:231], off
	s_barrier
; #define PG8_STAGE(bufoff, gbase, voff) do { _Pragma("unroll") for (int _i = 0; _i < 2; ++_i) \
;     __builtin_amdgcn_global_load_lds((const unsigned*)((const char*)(gbase) + (voff)[_i]), (LAS unsigned*)(lds + (bufoff) + ldsw + _i * 8192), 16, 0, 0); } while (0)
; #define PG8_MMA(ai, bj, At, Bt) do { __builtin_amdgcn_s_setprio(1); _Pragma("unroll") for (int m = 0; m < 4; ++m) _Pragma("unroll") for (int n = 0; n < 2; ++n) _Pragma("unroll") for (int k = 0; k < 2; ++k) \
;     acc[ai][bj][m][n] = __builtin_amdgcn_mfma_f32_16x16x32_bf16(Bt[n][k], At[m][k], acc[ai][bj][m][n], 0, 0, 0); __builtin_amdgcn_s_setprio(0); } while (0)
; #define PG8_WAIT_V(n) asm volatile("s_waitcnt vmcnt(" #n ")" ::: "memory")
; #define PG8_WAIT_L(n) asm volatile("s_waitcnt lgkmcnt(" #n ")" ::: "memory")
; #define PG8_BAR __builtin_amdgcn_s_barrier()
; #define PG8_SCHED __builtin_amdgcn_sched_barrier(0)
; template <class Epi, class Sched>
; __device__ __forceinline__ void gemm_phase(LAS unsigned char* lds, const Gemm g, const Sched& S, const Epi& E) {
;     ...
;       PG8_BAR; PG8_WAIT_L(0); PG8_MMA(1, 0, At, B0); PG8_BAR; PG8_SCHED;
;       PG8_STAGE(PG8_SB(1, 1), b3 + hstepB, voffB);
;       PG8_WAIT_V(6); PG8_BAR; PG8_MMA(1, 1, At, B1); PG8_BAR;
	s_waitcnt lgkmcnt(0)
	s_setprio 1
	s_waitcnt lgkmcnt(0)
	v_mfma_f32_16x16x32_bf16 v[112:115], v[214:217], v[158:161], v[112:115]
	v_mfma_f32_16x16x32_bf16 v[104:107], v[222:225], v[158:161], v[104:107]
	v_mfma_f32_16x16x32_bf16 v[96:99], v[214:217], v[166:169], v[96:99]
	v_mfma_f32_16x16x32_bf16 v[88:91], v[222:225], v[166:169], v[88:91]
	v_mfma_f32_16x16x32_bf16 v[80:83], v[214:217], v[174:177], v[80:83]
	v_mfma_f32_16x16x32_bf16 v[72:75], v[222:225], v[174:177], v[72:75]
	v_mfma_f32_16x16x32_bf16 v[68:71], v[214:217], v[182:185], v[68:71]
	v_mfma_f32_16x16x32_bf16 v[64:67], v[222:225], v[182:185], v[64:67]
	v_mfma_f32_16x16x32_bf16 v[112:115], v[218:221], v[162:165], v[112:115]
	v_mfma_f32_16x16x32_bf16 v[104:107], v[226:229], v[162:165], v[104:107]
	v_mfma_f32_16x16x32_bf16 v[96:99], v[218:221], v[170:173], v[96:99]
	v_mfma_f32_16x16x32_bf16 v[88:91], v[226:229], v[170:173], v[88:91]
	v_mfma_f32_16x16x32_bf16 v[80:83], v[218:221], v[178:181], v[80:83]
	v_mfma_f32_16x16x32_bf16 v[72:75], v[226:229], v[178:181], v[72:75]
	v_mfma_f32_16x16x32_bf16 v[68:71], v[218:221], v[198:201], v[68:71]
	v_mfma_f32_16x16x32_bf16 v[64:67], v[226:229], v[198:201], v[64:67]
	s_setprio 0
	s_mov_b32 m0, s69
	v_lshl_add_u64 v[230:231], v[234:235], 0, s[62:63]
	s_barrier
	ds_read_b128 v[158:161], v143 offset:49152
	ds_read_b128 v[162:165], v143 offset:50176
	ds_read_b128 v[166:169], v143 offset:51200
	ds_read_b128 v[170:173], v143 offset:52224
	ds_read_b128 v[174:177], v143 offset:53248
	ds_read_b128 v[178:181], v143 offset:54272
	ds_read_b128 v[182:185], v143 offset:55296
	ds_read_b128 v[198:201], v143 offset:56320
	global_load_lds_dwordx4 v[230:231], off
	v_lshl_add_u64 v[230:231], v[236:237], 0, s[62:63]
	s_mov_b32 m0, s74
	s_nop 0
	global_load_lds_dwordx4 v[230:231], off
	s_barrier
	s_waitcnt lgkmcnt(0)
	s_setprio 1
	s_waitcnt lgkmcnt(0)
	v_mfma_f32_16x16x32_bf16 v[60:63], v[136:139], v[158:161], v[60:63]
	v_mfma_f32_16x16x32_bf16 v[56:59], v[150:153], v[158:161], v[56:59]
	v_mfma_f32_16x16x32_bf16 v[52:55], v[136:139], v[166:169], v[52:55]
	v_mfma_f32_16x16x32_bf16 v[44:47], v[150:153], v[166:169], v[44:47]
	v_mfma_f32_16x16x32_bf16 v[36:39], v[136:139], v[174:177], v[36:39]
	v_mfma_f32_16x16x32_bf16 v[28:31], v[150:153], v[174:177], v[28:31]
	v_mfma_f32_16x16x32_bf16 v[20:23], v[136:139], v[182:185], v[20:23]
	v_mfma_f32_16x16x32_bf16 v[12:15], v[150:153], v[182:185], v[12:15]
	v_mfma_f32_16x16x32_bf16 v[60:63], v[146:149], v[162:165], v[60:63]
	v_mfma_f32_16x16x32_bf16 v[56:59], v[154:157], v[162:165], v[56:59]
	v_mfma_f32_16x16x32_bf16 v[52:55], v[146:149], v[170:173], v[52:55]
	v_mfma_f32_16x16x32_bf16 v[44:47], v[154:157], v[170:173], v[44:47]
	v_mfma_f32_16x16x32_bf16 v[36:39], v[146:149], v[178:181], v[36:39]
	v_mfma_f32_16x16x32_bf16 v[28:31], v[154:157], v[178:181], v[28:31]
	v_mfma_f32_16x16x32_bf16 v[20:23], v[146:149], v[198:201], v[20:23]
	v_mfma_f32_16x16x32_bf16 v[12:15], v[154:157], v[198:201], v[12:15]
	s_setprio 0
	s_barrier
	s_mov_b32 m0, s91
	v_lshl_add_u64 v[136:137], s[20:21], 0, v[132:133]
	global_load_lds_dwordx4 v[136:137], off
	v_lshl_add_u64 v[136:137], s[20:21], 0, v[128:129]
	s_mov_b32 m0, s90
	s_nop 0
	global_load_lds_dwordx4 v[136:137], off
	s_waitcnt vmcnt(6)
	s_barrier
	s_setprio 1
	v_mfma_f32_16x16x32_bf16 v[48:51], v[214:217], v[158:161], v[48:51]
	v_mfma_f32_16x16x32_bf16 v[40:43], v[222:225], v[158:161], v[40:43]
	v_mfma_f32_16x16x32_bf16 v[32:35], v[214:217], v[166:169], v[32:35]
	v_mfma_f32_16x16x32_bf16 v[24:27], v[222:225], v[166:169], v[24:27]
	v_mfma_f32_16x16x32_bf16 v[16:19], v[214:217], v[174:177], v[16:19]
	v_mfma_f32_16x16x32_bf16 v[8:11], v[222:225], v[174:177], v[8:11]
	v_mfma_f32_16x16x32_bf16 v[4:7], v[214:217], v[182:185], v[4:7]
	v_mfma_f32_16x16x32_bf16 v[0:3], v[222:225], v[182:185], v[0:3]
	v_mfma_f32_16x16x32_bf16 v[48:51], v[218:221], v[162:165], v[48:51]
	v_mfma_f32_16x16x32_bf16 v[40:43], v[226:229], v[162:165], v[40:43]
	v_mfma_f32_16x16x32_bf16 v[32:35], v[218:221], v[170:173], v[32:35]
	v_mfma_f32_16x16x32_bf16 v[24:27], v[226:229], v[170:173], v[24:27]
	v_mfma_f32_16x16x32_bf16 v[16:19], v[218:221], v[178:181], v[16:19]
	v_mfma_f32_16x16x32_bf16 v[8:11], v[226:229], v[178:181], v[8:11]
	v_mfma_f32_16x16x32_bf16 v[4:7], v[218:221], v[198:201], v[4:7]
	v_mfma_f32_16x16x32_bf16 v[0:3], v[226:229], v[198:201], v[0:3]
	s_setprio 0
	s_movk_i32 s22, 0x100
	s_andn2_b64 vcc, exec, s[8:9]
	s_mov_b64 s[20:21], -1
	s_mov_b64 s[8:9], 0
	s_barrier
	s_cbranch_vccz .LBB0_2365
	v_lshl_or_b32 v138, s79, 8, v142
	v_and_b32_e32 v250, 16, v187
	v_lshrrev_b32_e32 v251, 2, v250
	v_sub_u32_e32 v250, v250, v251
	v_add_u32_e32 v138, v138, v250
	v_lshl_add_u32 v145, s82, 8, v140
	v_mov_b64_e32 v[136:137], s[12:13]
	v_ashrrev_i32_e32 v139, 31, v138
	v_mad_i64_i32 v[146:147], s[8:9], v145, s40, v[136:137]
	v_lshlrev_b64 v[138:139], 1, v[138:139]
	v_lshl_add_u64 v[146:147], v[146:147], 0, v[138:139]
	v_cvt_pk_bf16_f32 v242, v124, v125
	v_cvt_pk_bf16_f32 v243, v126, v127
	v_cvt_pk_bf16_f32 v244, v120, v121
	v_cvt_pk_bf16_f32 v245, v122, v123
	s_nop 1
	v_permlane16_swap_b32_e32 v242, v244
	v_permlane16_swap_b32_e32 v243, v245
	global_store_dwordx4 v[146:147], v[242:245], off offset:1536
	v_cvt_pk_bf16_f32 v246, v112, v113
	v_cvt_pk_bf16_f32 v247, v114, v115
	v_cvt_pk_bf16_f32 v248, v104, v105
	v_cvt_pk_bf16_f32 v249, v106, v107
	s_nop 1
	v_permlane16_swap_b32_e32 v246, v248
	v_permlane16_swap_b32_e32 v247, v249
	global_store_dwordx4 v[146:147], v[246:249], off offset:1792
	v_or_b32_e32 v104, 16, v145
	v_mad_i64_i32 v[104:105], s[8:9], v104, s40, v[136:137]
	v_lshl_add_u64 v[104:105], v[104:105], 0, v[138:139]
	v_cvt_pk_bf16_f32 v242, v116, v117
	v_cvt_pk_bf16_f32 v243, v118, v119
	v_cvt_pk_bf16_f32 v244, v108, v109
	v_cvt_pk_bf16_f32 v245, v110, v111
	s_nop 1
	v_permlane16_swap_b32_e32 v242, v244
	v_permlane16_swap_b32_e32 v243, v245
	global_store_dwordx4 v[104:105], v[242:245], off offset:1536
	v_cvt_pk_bf16_f32 v246, v96, v97
	v_cvt_pk_bf16_f32 v247, v98, v99
	v_cvt_pk_bf16_f32 v248, v88, v89
	v_cvt_pk_bf16_f32 v249, v90, v91
	s_nop 1
	v_permlane16_swap_b32_e32 v246, v248
	v_permlane16_swap_b32_e32 v247, v249
	global_store_dwordx4 v[104:105], v[246:249], off offset:1792
	v_or_b32_e32 v88, 32, v145
	v_mad_i64_i32 v[88:89], s[8:9], v88, s40, v[136:137]
	v_lshl_add_u64 v[88:89], v[88:89], 0, v[138:139]
	v_cvt_pk_bf16_f32 v242, v100, v101
	v_cvt_pk_bf16_f32 v243, v102, v103
	v_cvt_pk_bf16_f32 v244, v92, v93
	v_cvt_pk_bf16_f32 v245, v94, v95
	s_nop 1
	v_permlane16_swap_b32_e32 v242, v244
	v_permlane16_swap_b32_e32 v243, v245
	global_store_dwordx4 v[88:89], v[242:245], off offset:1536
	v_cvt_pk_bf16_f32 v246, v80, v81
	v_cvt_pk_bf16_f32 v247, v82, v83
	v_cvt_pk_bf16_f32 v248, v72, v73
	v_cvt_pk_bf16_f32 v249, v74, v75
	s_nop 1
	v_permlane16_swap_b32_e32 v246, v248
	v_permlane16_swap_b32_e32 v247, v249
	global_store_dwordx4 v[88:89], v[246:249], off offset:1792
	v_or_b32_e32 v72, 48, v145
	v_mad_i64_i32 v[72:73], s[8:9], v72, s40, v[136:137]
	v_lshl_add_u64 v[72:73], v[72:73], 0, v[138:139]
	v_cvt_pk_bf16_f32 v242, v84, v85
	v_cvt_pk_bf16_f32 v243, v86, v87
	v_cvt_pk_bf16_f32 v244, v76, v77
	v_cvt_pk_bf16_f32 v245, v78, v79
	s_nop 1
	v_permlane16_swap_b32_e32 v242, v244
	v_permlane16_swap_b32_e32 v243, v245
	global_store_dwordx4 v[72:73], v[242:245], off offset:1536
	v_cvt_pk_bf16_f32 v246, v68, v69
	v_cvt_pk_bf16_f32 v247, v70, v71
	v_cvt_pk_bf16_f32 v248, v64, v65
	v_cvt_pk_bf16_f32 v249, v66, v67
	s_nop 1
	v_permlane16_swap_b32_e32 v246, v248
	v_permlane16_swap_b32_e32 v247, v249
	global_store_dwordx4 v[72:73], v[246:249], off offset:1792
	v_add_u32_e32 v64, 0x80, v145
	v_mad_i64_i32 v[64:65], s[8:9], v64, s40, v[136:137]
	v_lshl_add_u64 v[64:65], v[64:65], 0, v[138:139]
	v_cvt_pk_bf16_f32 v242, v60, v61
	v_cvt_pk_bf16_f32 v243, v62, v63
	v_cvt_pk_bf16_f32 v244, v56, v57
	v_cvt_pk_bf16_f32 v245, v58, v59
	s_nop 1
	v_permlane16_swap_b32_e32 v242, v244
	v_permlane16_swap_b32_e32 v243, v245
	global_store_dwordx4 v[64:65], v[242:245], off offset:1536
	v_cvt_pk_bf16_f32 v246, v48, v49
	v_cvt_pk_bf16_f32 v247, v50, v51
	v_cvt_pk_bf16_f32 v248, v40, v41
	v_cvt_pk_bf16_f32 v249, v42, v43
	s_nop 1
	v_permlane16_swap_b32_e32 v246, v248
	v_permlane16_swap_b32_e32 v247, v249
	global_store_dwordx4 v[64:65], v[246:249], off offset:1792
	v_add_u32_e32 v40, 0x90, v145
	v_mad_i64_i32 v[40:41], s[8:9], v40, s40, v[136:137]
	v_lshl_add_u64 v[40:41], v[40:41], 0, v[138:139]
	v_cvt_pk_bf16_f32 v242, v52, v53
	v_cvt_pk_bf16_f32 v243, v54, v55
	v_cvt_pk_bf16_f32 v244, v44, v45
	v_cvt_pk_bf16_f32 v245, v46, v47
	s_nop 1
	v_permlane16_swap_b32_e32 v242, v244
	v_permlane16_swap_b32_e32 v243, v245
	global_store_dwordx4 v[40:41], v[242:245], off offset:1536
	v_cvt_pk_bf16_f32 v246, v32, v33
	v_cvt_pk_bf16_f32 v247, v34, v35
	v_cvt_pk_bf16_f32 v248, v24, v25
	v_cvt_pk_bf16_f32 v249, v26, v27
	s_nop 1
	v_permlane16_swap_b32_e32 v246, v248
	v_permlane16_swap_b32_e32 v247, v249
	global_store_dwordx4 v[40:41], v[246:249], off offset:1792
	v_add_u32_e32 v24, 0xa0, v145
	v_mad_i64_i32 v[24:25], s[8:9], v24, s40, v[136:137]
	v_lshl_add_u64 v[24:25], v[24:25], 0, v[138:139]
	v_cvt_pk_bf16_f32 v242, v36, v37
	v_cvt_pk_bf16_f32 v243, v38, v39
	v_cvt_pk_bf16_f32 v244, v28, v29
	v_cvt_pk_bf16_f32 v245, v30, v31
	s_nop 1
	v_permlane16_swap_b32_e32 v242, v244
	v_permlane16_swap_b32_e32 v243, v245
	global_store_dwordx4 v[24:25], v[242:245], off offset:1536
	v_cvt_pk_bf16_f32 v246, v16, v17
	v_cvt_pk_bf16_f32 v247, v18, v19
	v_cvt_pk_bf16_f32 v248, v8, v9
	v_cvt_pk_bf16_f32 v249, v10, v11
	s_nop 1
	v_permlane16_swap_b32_e32 v246, v248
	v_permlane16_swap_b32_e32 v247, v249
	global_store_dwordx4 v[24:25], v[246:249], off offset:1792
	v_add_u32_e32 v8, 0xb0, v145
	v_mad_i64_i32 v[8:9], s[8:9], v8, s40, v[136:137]
	v_lshl_add_u64 v[8:9], v[8:9], 0, v[138:139]
	v_cvt_pk_bf16_f32 v242, v20, v21
	v_cvt_pk_bf16_f32 v243, v22, v23
	s_and_b64 vcc, exec, s[6:7]
	s_mov_b32 s79, s4
	s_mov_b32 s82, s78
	s_mov_b64 s[14:15], s[16:17]
	s_mov_b64 s[18:19], s[10:11]
	s_movk_i32 s90, 0x300
	s_movk_i32 s94, 0x104
	s_movk_i32 s91, 0x60
	s_movk_i32 s95, 0xf8
	s_mov_b32 s88, 0x30000
	s_mov_b32 s89, 0xe000
	s_mov_b32 s87, 0x80000
	s_movk_i32 s86, 0x4100
	v_cvt_pk_bf16_f32 v244, v12, v13
	v_cvt_pk_bf16_f32 v245, v14, v15
	s_nop 1
	v_permlane16_swap_b32_e32 v242, v244
	v_permlane16_swap_b32_e32 v243, v245
	global_store_dwordx4 v[8:9], v[242:245], off offset:1536
	v_cvt_pk_bf16_f32 v246, v4, v5
	v_cvt_pk_bf16_f32 v247, v6, v7
	v_cvt_pk_bf16_f32 v248, v0, v1
	v_cvt_pk_bf16_f32 v249, v2, v3
	s_nop 1
	v_permlane16_swap_b32_e32 v246, v248
	v_permlane16_swap_b32_e32 v247, v249
	global_store_dwordx4 v[8:9], v[246:249], off offset:1792
	s_cbranch_vccz .LBB0_2356
	s_waitcnt vmcnt(0)
	s_cmpk_gt_u32 s24, 0xff
	s_mov_b32 s74, 0x8000
	s_mov_b32 s75, 0x10000
	s_movk_i32 s79, 0x40ff
	s_movk_i32 s78, 0x2000
	s_cbranch_scc1 .LBB0_2369
	s_barrier

; #define PG8_STAGE(bufoff, gbase, voff) do { _Pragma("unroll") for (int _i = 0; _i < 2; ++_i) \
;     __builtin_amdgcn_global_load_lds((const unsigned*)((const char*)(gbase) + (voff)[_i]), (LAS unsigned*)(lds + (bufoff) + ldsw + _i * 8192), 16, 0, 0); } while (0)
; #define PG8_LDA(dst, b, h) do { _Pragma("unroll") for (int m = 0; m < 4; ++m) _Pragma("unroll") for (int k = 0; k < 2; ++k) dst[m][k] = *(const LAS bf16x8*)(lds + PG8_SA(b, h) + aoff + m * 2048 + k * 1024); } while (0)
; #define PG8_LDB(dst, b, h) do { _Pragma("unroll") for (int n = 0; n < 2; ++n) _Pragma("unroll") for (int k = 0; k < 2; ++k) dst[n][k] = *(const LAS bf16x8*)(lds + PG8_SB(b, h) + boff + n * 2048 + k * 1024); } while (0)
; #define PG8_MMA(ai, bj, At, Bt) do { __builtin_amdgcn_s_setprio(1); _Pragma("unroll") for (int m = 0; m < 4; ++m) _Pragma("unroll") for (int n = 0; n < 2; ++n) _Pragma("unroll") for (int k = 0; k < 2; ++k) \
;     acc[ai][bj][m][n] = __builtin_amdgcn_mfma_f32_16x16x32_bf16(Bt[n][k], At[m][k], acc[ai][bj][m][n], 0, 0, 0); __builtin_amdgcn_s_setprio(0); } while (0)
; #define PG8_WAIT_V(n) asm volatile("s_waitcnt vmcnt(" #n ")" ::: "memory")
; #define PG8_WAIT_L(n) asm volatile("s_waitcnt lgkmcnt(" #n ")" ::: "memory")
; #define PG8_BAR __builtin_amdgcn_s_barrier()
; #define PG8_SCHED __builtin_amdgcn_sched_barrier(0)
; template <class Epi, class Sched>
; __device__ __forceinline__ void gemm_phase(LAS unsigned char* lds, const Gemm g, const Sched& S, const Epi& E) {
;     ...
;     for (int t = 0; t < nt; t += 2) {
;       const bool last = (t == nt - 2);
;       const char* a1 = cA + (size_t)(t + 1) * kstep;
;       const char* a2 = last ? nA : cA + (size_t)(t + 2) * kstep; const char* b2 = last ? nB : cB + (size_t)(t + 2) * kstep;
;       const char* a3 = a2 + kstep; const char* b3 = b2 + kstep;
;       PG8_LDB(B0, 0, 0); PG8_SCHED; PG8_LDA(At, 0, 0); PG8_STAGE(PG8_SA(1, 1), a1 + hstepA, voffA);
;       PG8_WAIT_L(8); PG8_BAR; PG8_WAIT_L(0); PG8_MMA(0, 0, At, B0); PG8_BAR; PG8_SCHED;
;       PG8_LDB(B1, 0, 1); PG8_STAGE(PG8_SB(0, 0), b2, voffB);
;       PG8_BAR; PG8_WAIT_L(0); PG8_MMA(0, 1, At, B1); PG8_BAR;
;       PG8_LDA(At, 0, 1); PG8_STAGE(PG8_SA(0, 0), a2, voffA);
;       PG8_BAR; PG8_WAIT_L(0); PG8_MMA(1, 0, At, B0); PG8_BAR; PG8_SCHED;
;       PG8_STAGE(PG8_SB(0, 1), b2 + hstepB, voffB);
;       PG8_WAIT_V(6); PG8_BAR; PG8_MMA(1, 1, At, B1); PG8_BAR;
.LBB0_2773:
	s_add_u32 s28, s26, 0xfffc0080
	s_addc_u32 s29, s27, -1
	s_add_i32 s76, 16, 0x10000
	v_add_u32_e32 v145, s76, v137
	ds_read_b128 v[140:143], v145
	ds_read_b128 v[146:149], v145 offset:1024
	ds_read_b128 v[150:153], v145 offset:2048
	ds_read_b128 v[154:157], v145 offset:3072
	s_cmp_eq_u32 s78, 12
	s_cselect_b32 s37, s15, s29
	s_cselect_b32 s36, s68, s28
	s_cselect_b32 s29, s11, s75
	s_cselect_b32 s28, s69, s74
	v_lshl_add_u64 v[214:215], s[26:27], 0, v[132:133]
	s_add_i32 m0, s21, 0xc000
	ds_read_b128 v[158:161], v139
	ds_read_b128 v[162:165], v139 offset:1024
	ds_read_b128 v[166:169], v139 offset:2048
	ds_read_b128 v[170:173], v139 offset:3072
	ds_read_b128 v[174:177], v139 offset:4096
	ds_read_b128 v[178:181], v139 offset:5120
	ds_read_b128 v[182:185], v139 offset:6144
	ds_read_b128 v[198:201], v139 offset:7168
	global_load_lds_dwordx4 v[214:215], off
	v_lshl_add_u64 v[214:215], s[26:27], 0, v[134:135]
	s_add_i32 m0, s21, 0xe000
	s_nop 0
	global_load_lds_dwordx4 v[214:215], off
	s_waitcnt lgkmcnt(8)
	s_barrier
	s_waitcnt lgkmcnt(0)
	s_setprio 1
	s_waitcnt lgkmcnt(0)
	v_mfma_f32_16x16x32_bf16 v[124:127], v[140:143], v[158:161], v[124:127]
	v_mfma_f32_16x16x32_bf16 v[120:123], v[150:153], v[158:161], v[120:123]
	v_mfma_f32_16x16x32_bf16 v[112:115], v[140:143], v[166:169], v[112:115]
	v_mfma_f32_16x16x32_bf16 v[104:107], v[150:153], v[166:169], v[104:107]
	v_mfma_f32_16x16x32_bf16 v[96:99], v[140:143], v[174:177], v[96:99]
	v_mfma_f32_16x16x32_bf16 v[88:91], v[150:153], v[174:177], v[88:91]
	v_mfma_f32_16x16x32_bf16 v[80:83], v[140:143], v[182:185], v[80:83]
	v_mfma_f32_16x16x32_bf16 v[72:75], v[150:153], v[182:185], v[72:75]
	v_mfma_f32_16x16x32_bf16 v[124:127], v[146:149], v[162:165], v[124:127]
	v_mfma_f32_16x16x32_bf16 v[120:123], v[154:157], v[162:165], v[120:123]
	v_mfma_f32_16x16x32_bf16 v[112:115], v[146:149], v[170:173], v[112:115]
	v_mfma_f32_16x16x32_bf16 v[104:107], v[154:157], v[170:173], v[104:107]
	v_mfma_f32_16x16x32_bf16 v[96:99], v[146:149], v[178:181], v[96:99]
	v_mfma_f32_16x16x32_bf16 v[88:91], v[154:157], v[178:181], v[88:91]
	v_mfma_f32_16x16x32_bf16 v[80:83], v[146:149], v[198:201], v[80:83]
	v_mfma_f32_16x16x32_bf16 v[72:75], v[154:157], v[198:201], v[72:75]
	s_setprio 0
	s_barrier
	s_add_i32 s79, 16, 0x14000
	s_add_i32 s76, s76, s48
	v_add_u32_e32 v145, s79, v137
	v_lshl_add_u64 v[230:231], s[28:29], 0, v[130:131]
	s_mov_b32 m0, s76
	ds_read_b128 v[214:217], v145
	ds_read_b128 v[218:221], v145 offset:1024
	ds_read_b128 v[222:225], v145 offset:2048
	ds_read_b128 v[226:229], v145 offset:3072
	global_load_lds_dwordx4 v[230:231], off
	v_lshl_add_u64 v[232:233], s[28:29], 0, v[128:129]
	s_add_i32 m0, s76, 0x2000
	s_nop 0
	global_load_lds_dwordx4 v[232:233], off
	s_barrier
	s_waitcnt lgkmcnt(0)
	s_setprio 1
	s_waitcnt lgkmcnt(0)
	v_mfma_f32_16x16x32_bf16 v[116:119], v[214:217], v[158:161], v[116:119]
	v_mfma_f32_16x16x32_bf16 v[108:111], v[222:225], v[158:161], v[108:111]
	v_mfma_f32_16x16x32_bf16 v[100:103], v[214:217], v[166:169], v[100:103]
	v_mfma_f32_16x16x32_bf16 v[92:95], v[222:225], v[166:169], v[92:95]
	v_mfma_f32_16x16x32_bf16 v[84:87], v[214:217], v[174:177], v[84:87]
	v_mfma_f32_16x16x32_bf16 v[76:79], v[222:225], v[174:177], v[76:79]
	v_mfma_f32_16x16x32_bf16 v[68:71], v[214:217], v[182:185], v[68:71]
	v_mfma_f32_16x16x32_bf16 v[64:67], v[222:225], v[182:185], v[64:67]
	v_mfma_f32_16x16x32_bf16 v[116:119], v[218:221], v[162:165], v[116:119]
	v_mfma_f32_16x16x32_bf16 v[108:111], v[226:229], v[162:165], v[108:111]
	v_mfma_f32_16x16x32_bf16 v[100:103], v[218:221], v[170:173], v[100:103]
	v_mfma_f32_16x16x32_bf16 v[92:95], v[226:229], v[170:173], v[92:95]
	v_mfma_f32_16x16x32_bf16 v[84:87], v[218:221], v[178:181], v[84:87]
	v_mfma_f32_16x16x32_bf16 v[76:79], v[226:229], v[178:181], v[76:79]
	v_mfma_f32_16x16x32_bf16 v[68:71], v[218:221], v[198:201], v[68:71]
	v_mfma_f32_16x16x32_bf16 v[64:67], v[226:229], v[198:201], v[64:67]
	s_setprio 0
	s_mov_b32 m0, s21
	v_lshl_add_u64 v[234:235], s[36:37], 0, v[130:131]
	s_barrier
	ds_read_b128 v[158:161], v139 offset:16384
	ds_read_b128 v[162:165], v139 offset:17408
	ds_read_b128 v[166:169], v139 offset:18432
	ds_read_b128 v[170:173], v139 offset:19456
	ds_read_b128 v[174:177], v139 offset:20480
	ds_read_b128 v[178:181], v139 offset:21504
	ds_read_b128 v[182:185], v139 offset:22528
	ds_read_b128 v[198:201], v139 offset:23552
	global_load_lds_dwordx4 v[234:235], off
	v_lshl_add_u64 v[236:237], s[36:37], 0, v[128:129]
	s_mov_b32 m0, s23
	s_nop 0
	global_load_lds_dwordx4 v[236:237], off
	s_barrier
	s_waitcnt lgkmcnt(0)
	s_setprio 1
	s_waitcnt lgkmcnt(0)
	v_mfma_f32_16x16x32_bf16 v[60:63], v[140:143], v[158:161], v[60:63]
	v_mfma_f32_16x16x32_bf16 v[56:59], v[150:153], v[158:161], v[56:59]
	v_mfma_f32_16x16x32_bf16 v[48:51], v[140:143], v[166:169], v[48:51]
	v_mfma_f32_16x16x32_bf16 v[40:43], v[150:153], v[166:169], v[40:43]
	v_mfma_f32_16x16x32_bf16 v[32:35], v[140:143], v[174:177], v[32:35]
	v_mfma_f32_16x16x32_bf16 v[24:27], v[150:153], v[174:177], v[24:27]
	v_mfma_f32_16x16x32_bf16 v[16:19], v[140:143], v[182:185], v[16:19]
	v_mfma_f32_16x16x32_bf16 v[8:11], v[150:153], v[182:185], v[8:11]
	v_mfma_f32_16x16x32_bf16 v[60:63], v[146:149], v[162:165], v[60:63]
	v_mfma_f32_16x16x32_bf16 v[56:59], v[154:157], v[162:165], v[56:59]
	v_mfma_f32_16x16x32_bf16 v[48:51], v[146:149], v[170:173], v[48:51]
	v_mfma_f32_16x16x32_bf16 v[40:43], v[154:157], v[170:173], v[40:43]
	v_mfma_f32_16x16x32_bf16 v[32:35], v[146:149], v[178:181], v[32:35]
	v_mfma_f32_16x16x32_bf16 v[24:27], v[154:157], v[178:181], v[24:27]
	v_mfma_f32_16x16x32_bf16 v[16:19], v[146:149], v[198:201], v[16:19]
	v_mfma_f32_16x16x32_bf16 v[8:11], v[154:157], v[198:201], v[8:11]
	s_setprio 0
	s_barrier
; #define PG8_STAGE(bufoff, gbase, voff) do { _Pragma("unroll") for (int _i = 0; _i < 2; ++_i) \
;     __builtin_amdgcn_global_load_lds((const unsigned*)((const char*)(gbase) + (voff)[_i]), (LAS unsigned*)(lds + (bufoff) + ldsw + _i * 8192), 16, 0, 0); } while (0)
; #define PG8_LDA(dst, b, h) do { _Pragma("unroll") for (int m = 0; m < 4; ++m) _Pragma("unroll") for (int k = 0; k < 2; ++k) dst[m][k] = *(const LAS bf16x8*)(lds + PG8_SA(b, h) + aoff + m * 2048 + k * 1024); } while (0)
; #define PG8_LDB(dst, b, h) do { _Pragma("unroll") for (int n = 0; n < 2; ++n) _Pragma("unroll") for (int k = 0; k < 2; ++k) dst[n][k] = *(const LAS bf16x8*)(lds + PG8_SB(b, h) + boff + n * 2048 + k * 1024); } while (0)
; #define PG8_MMA(ai, bj, At, Bt) do { __builtin_amdgcn_s_setprio(1); _Pragma("unroll") for (int m = 0; m < 4; ++m) _Pragma("unroll") for (int n = 0; n < 2; ++n) _Pragma("unroll") for (int k = 0; k < 2; ++k) \
;     acc[ai][bj][m][n] = __builtin_amdgcn_mfma_f32_16x16x32_bf16(Bt[n][k], At[m][k], acc[ai][bj][m][n], 0, 0, 0); __builtin_amdgcn_s_setprio(0); } while (0)
; #define PG8_WAIT_V(n) asm volatile("s_waitcnt vmcnt(" #n ")" ::: "memory")
; #define PG8_WAIT_L(n) asm volatile("s_waitcnt lgkmcnt(" #n ")" ::: "memory")
; #define PG8_BAR __builtin_amdgcn_s_barrier()
; #define PG8_SCHED __builtin_amdgcn_sched_barrier(0)
; template <class Epi, class Sched>
; __device__ __forceinline__ void gemm_phase(LAS unsigned char* lds, const Gemm g, const Sched& S, const Epi& E) {
;     ...
;       PG8_STAGE(PG8_SB(0, 1), b2 + hstepB, voffB);
;       PG8_WAIT_V(6); PG8_BAR; PG8_MMA(1, 1, At, B1); PG8_BAR;
;       PG8_LDB(B0, 1, 0); PG8_SCHED; PG8_LDA(At, 1, 0); PG8_STAGE(PG8_SA(0, 1), a2 + hstepA, voffA);
;       PG8_WAIT_L(8); PG8_BAR; PG8_WAIT_L(0); PG8_MMA(0, 0, At, B0); PG8_BAR; PG8_SCHED;
;       PG8_LDB(B1, 1, 1); PG8_STAGE(PG8_SB(1, 0), b3, voffB);
;       PG8_BAR; PG8_WAIT_L(0); PG8_MMA(0, 1, At, B1); PG8_BAR;
;       PG8_LDA(At, 1, 1); PG8_STAGE(PG8_SA(1, 0), a3, voffA);
;       PG8_BAR; PG8_WAIT_L(0); PG8_MMA(1, 0, At, B0); PG8_BAR; PG8_SCHED;
	s_add_u32 s76, s28, 0x40000
	s_addc_u32 s77, s29, 0
	s_add_i32 s79, s79, s48
	v_lshl_add_u64 v[140:141], s[76:77], 0, v[130:131]
	s_mov_b32 m0, s79
	s_nop 0
	global_load_lds_dwordx4 v[140:141], off
	v_lshl_add_u64 v[140:141], s[76:77], 0, v[128:129]
	s_add_i32 m0, s79, 0x2000
	s_nop 0
	global_load_lds_dwordx4 v[140:141], off
	s_waitcnt vmcnt(6)
	s_barrier
	s_setprio 1
	v_mfma_f32_16x16x32_bf16 v[52:55], v[214:217], v[158:161], v[52:55]
	v_mfma_f32_16x16x32_bf16 v[44:47], v[222:225], v[158:161], v[44:47]
	v_mfma_f32_16x16x32_bf16 v[36:39], v[214:217], v[166:169], v[36:39]
	v_mfma_f32_16x16x32_bf16 v[28:31], v[222:225], v[166:169], v[28:31]
	v_mfma_f32_16x16x32_bf16 v[20:23], v[214:217], v[174:177], v[20:23]
	v_mfma_f32_16x16x32_bf16 v[12:15], v[222:225], v[174:177], v[12:15]
	v_mfma_f32_16x16x32_bf16 v[4:7], v[214:217], v[182:185], v[4:7]
	v_mfma_f32_16x16x32_bf16 v[0:3], v[222:225], v[182:185], v[0:3]
	v_mfma_f32_16x16x32_bf16 v[52:55], v[218:221], v[162:165], v[52:55]
	v_mfma_f32_16x16x32_bf16 v[44:47], v[226:229], v[162:165], v[44:47]
	v_mfma_f32_16x16x32_bf16 v[36:39], v[218:221], v[170:173], v[36:39]
	v_mfma_f32_16x16x32_bf16 v[28:31], v[226:229], v[170:173], v[28:31]
	v_mfma_f32_16x16x32_bf16 v[20:23], v[218:221], v[178:181], v[20:23]
	v_mfma_f32_16x16x32_bf16 v[12:15], v[226:229], v[178:181], v[12:15]
	v_mfma_f32_16x16x32_bf16 v[4:7], v[218:221], v[198:201], v[4:7]
	v_mfma_f32_16x16x32_bf16 v[0:3], v[226:229], v[198:201], v[0:3]
	s_setprio 0
	s_add_i32 s76, 16, 0x18000
	v_add_u32_e32 v145, s76, v137
	s_barrier
	ds_read_b128 v[140:143], v145
	ds_read_b128 v[146:149], v145 offset:1024
	ds_read_b128 v[150:153], v145 offset:2048
	ds_read_b128 v[154:157], v145 offset:3072
	s_add_u32 s36, s36, 0x40000
	s_addc_u32 s37, s37, 0
	s_mov_b32 m0, s51
	v_lshl_add_u64 v[214:215], s[36:37], 0, v[130:131]
	ds_read_b128 v[158:161], v139 offset:32768
	ds_read_b128 v[162:165], v139 offset:33792
	ds_read_b128 v[166:169], v139 offset:34816
	ds_read_b128 v[170:173], v139 offset:35840
	ds_read_b128 v[174:177], v139 offset:36864
	ds_read_b128 v[178:181], v139 offset:37888
	ds_read_b128 v[182:185], v139 offset:38912
	ds_read_b128 v[198:201], v139 offset:39936
	global_load_lds_dwordx4 v[214:215], off
	v_lshl_add_u64 v[214:215], s[36:37], 0, v[128:129]
	s_mov_b32 m0, s58
	s_nop 0
	global_load_lds_dwordx4 v[214:215], off
	s_waitcnt lgkmcnt(8)
	s_barrier
	s_waitcnt lgkmcnt(0)
	s_setprio 1
	s_waitcnt lgkmcnt(0)
	v_mfma_f32_16x16x32_bf16 v[124:127], v[140:143], v[158:161], v[124:127]
	v_mfma_f32_16x16x32_bf16 v[120:123], v[150:153], v[158:161], v[120:123]
	v_mfma_f32_16x16x32_bf16 v[112:115], v[140:143], v[166:169], v[112:115]
	v_mfma_f32_16x16x32_bf16 v[104:107], v[150:153], v[166:169], v[104:107]
	v_mfma_f32_16x16x32_bf16 v[96:99], v[140:143], v[174:177], v[96:99]
	v_mfma_f32_16x16x32_bf16 v[88:91], v[150:153], v[174:177], v[88:91]
	v_mfma_f32_16x16x32_bf16 v[80:83], v[140:143], v[182:185], v[80:83]
	v_mfma_f32_16x16x32_bf16 v[72:75], v[150:153], v[182:185], v[72:75]
	v_mfma_f32_16x16x32_bf16 v[124:127], v[146:149], v[162:165], v[124:127]
	v_mfma_f32_16x16x32_bf16 v[120:123], v[154:157], v[162:165], v[120:123]
	v_mfma_f32_16x16x32_bf16 v[112:115], v[146:149], v[170:173], v[112:115]
	v_mfma_f32_16x16x32_bf16 v[104:107], v[154:157], v[170:173], v[104:107]
	v_mfma_f32_16x16x32_bf16 v[96:99], v[146:149], v[178:181], v[96:99]
	v_mfma_f32_16x16x32_bf16 v[88:91], v[154:157], v[178:181], v[88:91]
	v_mfma_f32_16x16x32_bf16 v[80:83], v[146:149], v[198:201], v[80:83]
	v_mfma_f32_16x16x32_bf16 v[72:75], v[154:157], v[198:201], v[72:75]
	s_setprio 0
	s_barrier
	s_add_i32 s36, 16, 0x1c000
	s_add_i32 s37, s76, s48
	v_add_u32_e32 v145, s36, v137
	v_lshl_add_u64 v[230:231], v[230:231], 0, s[62:63]
	s_mov_b32 m0, s37
	ds_read_b128 v[214:217], v145
	ds_read_b128 v[218:221], v145 offset:1024
	ds_read_b128 v[222:225], v145 offset:2048
	ds_read_b128 v[226:229], v145 offset:3072
	global_load_lds_dwordx4 v[230:231], off
	v_lshl_add_u64 v[230:231], v[232:233], 0, s[62:63]
	s_add_i32 m0, s37, 0x2000
	s_nop 0
	global_load_lds_dwordx4 v[230:231], off
	s_barrier
	s_waitcnt lgkmcnt(0)
	s_setprio 1
	s_waitcnt lgkmcnt(0)
	v_mfma_f32_16x16x32_bf16 v[116:119], v[214:217], v[158:161], v[116:119]
	v_mfma_f32_16x16x32_bf16 v[108:111], v[222:225], v[158:161], v[108:111]
	v_mfma_f32_16x16x32_bf16 v[100:103], v[214:217], v[166:169], v[100:103]
	v_mfma_f32_16x16x32_bf16 v[92:95], v[222:225], v[166:169], v[92:95]
	v_mfma_f32_16x16x32_bf16 v[84:87], v[214:217], v[174:177], v[84:87]
	v_mfma_f32_16x16x32_bf16 v[76:79], v[222:225], v[174:177], v[76:79]
	v_mfma_f32_16x16x32_bf16 v[68:71], v[214:217], v[182:185], v[68:71]
	v_mfma_f32_16x16x32_bf16 v[64:67], v[222:225], v[182:185], v[64:67]
	v_mfma_f32_16x16x32_bf16 v[116:119], v[218:221], v[162:165], v[116:119]
	v_mfma_f32_16x16x32_bf16 v[108:111], v[226:229], v[162:165], v[108:111]
	v_mfma_f32_16x16x32_bf16 v[100:103], v[218:221], v[170:173], v[100:103]
	v_mfma_f32_16x16x32_bf16 v[92:95], v[226:229], v[170:173], v[92:95]
	v_mfma_f32_16x16x32_bf16 v[84:87], v[218:221], v[178:181], v[84:87]
	v_mfma_f32_16x16x32_bf16 v[76:79], v[226:229], v[178:181], v[76:79]
	v_mfma_f32_16x16x32_bf16 v[68:71], v[218:221], v[198:201], v[68:71]
	v_mfma_f32_16x16x32_bf16 v[64:67], v[226:229], v[198:201], v[64:67]
	s_setprio 0
	s_mov_b32 m0, s59
	v_lshl_add_u64 v[230:231], v[234:235], 0, s[62:63]
	s_barrier
	ds_read_b128 v[158:161], v139 offset:49152
	ds_read_b128 v[162:165], v139 offset:50176
	ds_read_b128 v[166:169], v139 offset:51200
	ds_read_b128 v[170:173], v139 offset:52224
	ds_read_b128 v[174:177], v139 offset:53248
	ds_read_b128 v[178:181], v139 offset:54272
	ds_read_b128 v[182:185], v139 offset:55296
	ds_read_b128 v[198:201], v139 offset:56320
	global_load_lds_dwordx4 v[230:231], off
	v_lshl_add_u64 v[230:231], v[236:237], 0, s[62:63]
	s_mov_b32 m0, s66
	s_nop 0
	global_load_lds_dwordx4 v[230:231], off
	s_barrier
; #define PG8_STAGE(bufoff, gbase, voff) do { _Pragma("unroll") for (int _i = 0; _i < 2; ++_i) \
;     __builtin_amdgcn_global_load_lds((const unsigned*)((const char*)(gbase) + (voff)[_i]), (LAS unsigned*)(lds + (bufoff) + ldsw + _i * 8192), 16, 0, 0); } while (0)
; #define PG8_MMA(ai, bj, At, Bt) do { __builtin_amdgcn_s_setprio(1); _Pragma("unroll") for (int m = 0; m < 4; ++m) _Pragma("unroll") for (int n = 0; n < 2; ++n) _Pragma("unroll") for (int k = 0; k < 2; ++k) \
;     acc[ai][bj][m][n] = __builtin_amdgcn_mfma_f32_16x16x32_bf16(Bt[n][k], At[m][k], acc[ai][bj][m][n], 0, 0, 0); __builtin_amdgcn_s_setprio(0); } while (0)
; #define PG8_WAIT_V(n) asm volatile("s_waitcnt vmcnt(" #n ")" ::: "memory")
; #define PG8_WAIT_L(n) asm volatile("s_waitcnt lgkmcnt(" #n ")" ::: "memory")
; #define PG8_BAR __builtin_amdgcn_s_barrier()
; #define PG8_SCHED __builtin_amdgcn_sched_barrier(0)
; template <class Epi, class Sched>
; __device__ __forceinline__ void gemm_phase(LAS unsigned char* lds, const Gemm g, const Sched& S, const Epi& E) {
;     ...
;       PG8_BAR; PG8_WAIT_L(0); PG8_MMA(1, 0, At, B0); PG8_BAR; PG8_SCHED;
;       PG8_STAGE(PG8_SB(1, 1), b3 + hstepB, voffB);
;       PG8_WAIT_V(6); PG8_BAR; PG8_MMA(1, 1, At, B1); PG8_BAR;
	s_waitcnt lgkmcnt(0)
	s_setprio 1
	s_waitcnt lgkmcnt(0)
	v_mfma_f32_16x16x32_bf16 v[60:63], v[140:143], v[158:161], v[60:63]
	v_mfma_f32_16x16x32_bf16 v[56:59], v[150:153], v[158:161], v[56:59]
	v_mfma_f32_16x16x32_bf16 v[48:51], v[140:143], v[166:169], v[48:51]
	v_mfma_f32_16x16x32_bf16 v[40:43], v[150:153], v[166:169], v[40:43]
	v_mfma_f32_16x16x32_bf16 v[32:35], v[140:143], v[174:177], v[32:35]
	v_mfma_f32_16x16x32_bf16 v[24:27], v[150:153], v[174:177], v[24:27]
	v_mfma_f32_16x16x32_bf16 v[16:19], v[140:143], v[182:185], v[16:19]
	v_mfma_f32_16x16x32_bf16 v[8:11], v[150:153], v[182:185], v[8:11]
	v_mfma_f32_16x16x32_bf16 v[60:63], v[146:149], v[162:165], v[60:63]
	v_mfma_f32_16x16x32_bf16 v[56:59], v[154:157], v[162:165], v[56:59]
	v_mfma_f32_16x16x32_bf16 v[48:51], v[146:149], v[170:173], v[48:51]
	v_mfma_f32_16x16x32_bf16 v[40:43], v[154:157], v[170:173], v[40:43]
	v_mfma_f32_16x16x32_bf16 v[32:35], v[146:149], v[178:181], v[32:35]
	v_mfma_f32_16x16x32_bf16 v[24:27], v[154:157], v[178:181], v[24:27]
	v_mfma_f32_16x16x32_bf16 v[16:19], v[146:149], v[198:201], v[16:19]
	v_mfma_f32_16x16x32_bf16 v[8:11], v[154:157], v[198:201], v[8:11]
	s_setprio 0
	s_barrier
	s_add_u32 s28, s28, 0x40080
	s_addc_u32 s29, s29, 0
	s_add_i32 s36, s36, s48
	v_lshl_add_u64 v[140:141], s[28:29], 0, v[130:131]
	s_mov_b32 m0, s36
	s_nop 0
	global_load_lds_dwordx4 v[140:141], off
	v_lshl_add_u64 v[140:141], s[28:29], 0, v[128:129]
	s_add_i32 m0, s36, 0x2000
	s_nop 0
	global_load_lds_dwordx4 v[140:141], off
	s_waitcnt vmcnt(6)
	s_barrier
	s_setprio 1
	v_mfma_f32_16x16x32_bf16 v[52:55], v[214:217], v[158:161], v[52:55]
	v_mfma_f32_16x16x32_bf16 v[44:47], v[222:225], v[158:161], v[44:47]
	v_mfma_f32_16x16x32_bf16 v[36:39], v[214:217], v[166:169], v[36:39]
	v_mfma_f32_16x16x32_bf16 v[28:31], v[222:225], v[166:169], v[28:31]
	v_mfma_f32_16x16x32_bf16 v[20:23], v[214:217], v[174:177], v[20:23]
	v_mfma_f32_16x16x32_bf16 v[12:15], v[222:225], v[174:177], v[12:15]
	v_mfma_f32_16x16x32_bf16 v[4:7], v[214:217], v[182:185], v[4:7]
	v_mfma_f32_16x16x32_bf16 v[0:3], v[222:225], v[182:185], v[0:3]
	v_mfma_f32_16x16x32_bf16 v[52:55], v[218:221], v[162:165], v[52:55]
	v_mfma_f32_16x16x32_bf16 v[44:47], v[226:229], v[162:165], v[44:47]
	v_mfma_f32_16x16x32_bf16 v[36:39], v[218:221], v[170:173], v[36:39]
	v_mfma_f32_16x16x32_bf16 v[28:31], v[226:229], v[170:173], v[28:31]
	v_mfma_f32_16x16x32_bf16 v[20:23], v[218:221], v[178:181], v[20:23]
	v_mfma_f32_16x16x32_bf16 v[12:15], v[226:229], v[178:181], v[12:15]
	v_mfma_f32_16x16x32_bf16 v[4:7], v[218:221], v[198:201], v[4:7]
	v_mfma_f32_16x16x32_bf16 v[0:3], v[226:229], v[198:201], v[0:3]
	s_setprio 0
	s_add_i32 s78, s78, 2
	s_add_u32 s26, s26, 0x100
	s_addc_u32 s27, s27, 0
	s_add_u32 s74, s74, 0x100
	s_addc_u32 s75, s75, 0
	s_cmp_gt_u32 s78, 13
	s_barrier
	s_cbranch_scc0 .LBB0_2773
	v_max_f32_e32 v124, v124, v124
	v_max_f32_e32 v124, 0, v124
	v_mul_f32_e32 v145, v124, v124
	v_max_f32_e32 v124, v125, v125
	v_max_f32_e32 v124, 0, v124
	v_mul_f32_e32 v146, v124, v124
	v_max_f32_e32 v124, v126, v126
	v_max_f32_e32 v124, 0, v124
	v_lshl_add_u32 v140, s22, 8, v136
	v_mul_f32_e32 v147, v124, v124
	v_max_f32_e32 v124, v127, v127
	v_lshl_or_b32 v142, s20, 8, v138
	v_and_b32_e32 v250, 16, v187
	v_lshrrev_b32_e32 v251, 2, v250
	v_sub_u32_e32 v250, v250, v251
	v_add_u32_e32 v142, v142, v250
	v_ashrrev_i32_e32 v141, 31, v140
	v_max_f32_e32 v124, 0, v124
	v_mul_f32_e32 v148, v124, v124
	v_lshlrev_b64 v[124:125], 13, v[140:141]
	v_ashrrev_i32_e32 v143, 31, v142
	v_max_f32_e32 v120, v120, v120
	v_max_f32_e32 v121, v121, v121
	v_max_f32_e32 v116, v116, v116
	v_max_f32_e32 v117, v117, v117
	v_max_f32_e32 v108, v108, v108
	v_lshl_add_u64 v[124:125], s[12:13], 0, v[124:125]
	v_lshlrev_b64 v[126:127], 1, v[142:143]
	v_max_f32_e32 v120, 0, v120
	v_max_f32_e32 v121, 0, v121
	v_max_f32_e32 v122, v122, v122
	v_max_f32_e32 v123, v123, v123
	v_max_f32_e32 v116, 0, v116
	v_max_f32_e32 v117, 0, v117
	v_max_f32_e32 v118, v118, v118
	v_max_f32_e32 v119, v119, v119
	v_max_f32_e32 v108, 0, v108
	v_max_f32_e32 v109, v109, v109
	v_lshl_add_u64 v[124:125], v[124:125], 0, v[126:127]
	v_mul_f32_e32 v120, v120, v120
	v_mul_f32_e32 v121, v121, v121
	v_max_f32_e32 v122, 0, v122
	v_max_f32_e32 v123, 0, v123
	v_mul_f32_e32 v116, v116, v116
	v_mul_f32_e32 v117, v117, v117
	v_max_f32_e32 v118, 0, v118
	v_max_f32_e32 v119, 0, v119
	v_mul_f32_e32 v108, v108, v108
	v_max_f32_e32 v109, 0, v109
	v_max_f32_e32 v110, v110, v110
	v_max_f32_e32 v111, v111, v111
	v_cvt_pk_bf16_f32 v238, v145, v146
	v_cvt_pk_bf16_f32 v239, v147, v148
	v_mul_f32_e32 v122, v122, v122
	v_mul_f32_e32 v123, v123, v123
	v_cvt_pk_bf16_f32 v240, v120, v121
	v_cvt_pk_bf16_f32 v241, v122, v123
	s_nop 1
	v_permlane16_swap_b32_e32 v238, v240
	v_permlane16_swap_b32_e32 v239, v241
	global_store_dwordx4 v[124:125], v[238:241], off
	v_mul_f32_e32 v118, v118, v118
	v_mul_f32_e32 v119, v119, v119
	v_cvt_pk_bf16_f32 v242, v116, v117
	v_cvt_pk_bf16_f32 v243, v118, v119
	v_mul_f32_e32 v109, v109, v109
	v_max_f32_e32 v110, 0, v110
	v_max_f32_e32 v111, 0, v111
	v_cvt_pk_bf16_f32 v244, v108, v109
	v_mul_f32_e32 v110, v110, v110
	v_mul_f32_e32 v111, v111, v111
	v_cvt_pk_bf16_f32 v245, v110, v111
	s_nop 1
	v_permlane16_swap_b32_e32 v242, v244
	v_permlane16_swap_b32_e32 v243, v245
	global_store_dwordx4 v[124:125], v[242:245], off offset:256
	v_or_b32_e32 v108, 16, v140
	v_ashrrev_i32_e32 v109, 31, v108
	v_max_f32_e32 v110, v112, v112
	v_max_f32_e32 v111, v113, v113
	v_lshlrev_b64 v[108:109], 13, v[108:109]
	v_max_f32_e32 v104, v104, v104
	v_max_f32_e32 v105, v105, v105
	v_max_f32_e32 v100, v100, v100
	v_max_f32_e32 v101, v101, v101
	v_max_f32_e32 v92, v92, v92
	v_max_f32_e32 v110, 0, v110
	v_max_f32_e32 v111, 0, v111
	v_max_f32_e32 v112, v114, v114
	v_max_f32_e32 v113, v115, v115
	v_lshl_add_u64 v[108:109], s[12:13], 0, v[108:109]
	v_max_f32_e32 v104, 0, v104
	v_max_f32_e32 v105, 0, v105
	v_max_f32_e32 v106, v106, v106
	v_max_f32_e32 v107, v107, v107
	v_max_f32_e32 v100, 0, v100
	v_max_f32_e32 v101, 0, v101
	v_max_f32_e32 v102, v102, v102
	v_max_f32_e32 v103, v103, v103
	v_max_f32_e32 v92, 0, v92
	v_max_f32_e32 v93, v93, v93
	v_mul_f32_e32 v110, v110, v110
	v_mul_f32_e32 v111, v111, v111
	v_max_f32_e32 v112, 0, v112
	v_max_f32_e32 v113, 0, v113
	v_lshl_add_u64 v[108:109], v[108:109], 0, v[126:127]
	v_mul_f32_e32 v104, v104, v104
	v_mul_f32_e32 v105, v105, v105
	v_max_f32_e32 v106, 0, v106
	v_max_f32_e32 v107, 0, v107
	v_mul_f32_e32 v100, v100, v100
	v_mul_f32_e32 v101, v101, v101
	v_max_f32_e32 v102, 0, v102
	v_max_f32_e32 v103, 0, v103
	v_mul_f32_e32 v92, v92, v92
	v_max_f32_e32 v93, 0, v93
	v_max_f32_e32 v94, v94, v94
	v_max_f32_e32 v95, v95, v95
	v_mul_f32_e32 v112, v112, v112
	v_mul_f32_e32 v113, v113, v113
	v_cvt_pk_bf16_f32 v246, v110, v111
	v_cvt_pk_bf16_f32 v247, v112, v113
	v_mul_f32_e32 v106, v106, v106
	v_mul_f32_e32 v107, v107, v107
	v_cvt_pk_bf16_f32 v248, v104, v105
	v_cvt_pk_bf16_f32 v249, v106, v107
	s_nop 1
	v_permlane16_swap_b32_e32 v246, v248
	v_permlane16_swap_b32_e32 v247, v249
	global_store_dwordx4 v[108:109], v[246:249], off
	v_mul_f32_e32 v102, v102, v102
	v_mul_f32_e32 v103, v103, v103
	v_cvt_pk_bf16_f32 v238, v100, v101
	v_cvt_pk_bf16_f32 v239, v102, v103
	v_mul_f32_e32 v93, v93, v93
	v_max_f32_e32 v94, 0, v94
	v_max_f32_e32 v95, 0, v95
	v_cvt_pk_bf16_f32 v240, v92, v93
	v_mul_f32_e32 v94, v94, v94
	v_mul_f32_e32 v95, v95, v95
	v_cvt_pk_bf16_f32 v241, v94, v95
	s_nop 1
	v_permlane16_swap_b32_e32 v238, v240
	v_permlane16_swap_b32_e32 v239, v241
	global_store_dwordx4 v[108:109], v[238:241], off offset:256
	v_or_b32_e32 v92, 32, v140
	v_ashrrev_i32_e32 v93, 31, v92
	v_max_f32_e32 v94, v96, v96
	v_max_f32_e32 v95, v97, v97
	v_lshlrev_b64 v[92:93], 13, v[92:93]
	v_max_f32_e32 v88, v88, v88
	v_max_f32_e32 v89, v89, v89
	v_max_f32_e32 v84, v84, v84
	v_max_f32_e32 v85, v85, v85
	v_max_f32_e32 v76, v76, v76
	v_max_f32_e32 v94, 0, v94
	v_max_f32_e32 v95, 0, v95
	v_max_f32_e32 v96, v98, v98
	v_max_f32_e32 v97, v99, v99
	v_lshl_add_u64 v[92:93], s[12:13], 0, v[92:93]
	v_max_f32_e32 v88, 0, v88
	v_max_f32_e32 v89, 0, v89
	v_max_f32_e32 v90, v90, v90
	v_max_f32_e32 v91, v91, v91
	v_max_f32_e32 v84, 0, v84
	v_max_f32_e32 v85, 0, v85
	v_max_f32_e32 v86, v86, v86
	v_max_f32_e32 v87, v87, v87
	v_max_f32_e32 v76, 0, v76
	v_max_f32_e32 v77, v77, v77
	v_mul_f32_e32 v94, v94, v94
	v_mul_f32_e32 v95, v95, v95
	v_max_f32_e32 v96, 0, v96
	v_max_f32_e32 v97, 0, v97
	v_lshl_add_u64 v[92:93], v[92:93], 0, v[126:127]
	v_mul_f32_e32 v88, v88, v88
	v_mul_f32_e32 v89, v89, v89
	v_max_f32_e32 v90, 0, v90
	v_max_f32_e32 v91, 0, v91
	v_mul_f32_e32 v84, v84, v84
	v_mul_f32_e32 v85, v85, v85
	v_max_f32_e32 v86, 0, v86
	v_max_f32_e32 v87, 0, v87
	v_mul_f32_e32 v76, v76, v76
	v_max_f32_e32 v77, 0, v77
	v_max_f32_e32 v78, v78, v78
	v_max_f32_e32 v79, v79, v79
	v_mul_f32_e32 v96, v96, v96
	v_mul_f32_e32 v97, v97, v97
	v_cvt_pk_bf16_f32 v242, v94, v95
	v_cvt_pk_bf16_f32 v243, v96, v97
	v_mul_f32_e32 v90, v90, v90
	v_mul_f32_e32 v91, v91, v91
	v_cvt_pk_bf16_f32 v244, v88, v89
	v_cvt_pk_bf16_f32 v245, v90, v91
	s_nop 1
	v_permlane16_swap_b32_e32 v242, v244
	v_permlane16_swap_b32_e32 v243, v245
	global_store_dwordx4 v[92:93], v[242:245], off
	v_mul_f32_e32 v86, v86, v86
	v_mul_f32_e32 v87, v87, v87
	v_cvt_pk_bf16_f32 v246, v84, v85
	v_cvt_pk_bf16_f32 v247, v86, v87
	v_mul_f32_e32 v77, v77, v77
	v_max_f32_e32 v78, 0, v78
	v_max_f32_e32 v79, 0, v79
	v_cvt_pk_bf16_f32 v248, v76, v77
	v_mul_f32_e32 v78, v78, v78
	v_mul_f32_e32 v79, v79, v79
	v_cvt_pk_bf16_f32 v249, v78, v79
	s_nop 1
	v_permlane16_swap_b32_e32 v246, v248
	v_permlane16_swap_b32_e32 v247, v249
	global_store_dwordx4 v[92:93], v[246:249], off offset:256
	v_or_b32_e32 v76, 48, v140
	v_ashrrev_i32_e32 v77, 31, v76
	v_max_f32_e32 v78, v80, v80
	v_max_f32_e32 v79, v81, v81
	v_lshlrev_b64 v[76:77], 13, v[76:77]
	v_max_f32_e32 v72, v72, v72
	v_max_f32_e32 v73, v73, v73
	v_max_f32_e32 v68, v68, v68
	v_max_f32_e32 v69, v69, v69
	v_max_f32_e32 v64, v64, v64
	v_max_f32_e32 v78, 0, v78
	v_max_f32_e32 v79, 0, v79
	v_max_f32_e32 v80, v82, v82
	v_max_f32_e32 v81, v83, v83
	v_lshl_add_u64 v[76:77], s[12:13], 0, v[76:77]
	v_max_f32_e32 v72, 0, v72
	v_max_f32_e32 v73, 0, v73
	v_max_f32_e32 v74, v74, v74
	v_max_f32_e32 v75, v75, v75
	v_max_f32_e32 v68, 0, v68
	v_max_f32_e32 v69, 0, v69
	v_max_f32_e32 v70, v70, v70
	v_max_f32_e32 v71, v71, v71
	v_max_f32_e32 v64, 0, v64
	v_max_f32_e32 v65, v65, v65
	v_mul_f32_e32 v78, v78, v78
	v_mul_f32_e32 v79, v79, v79
	v_max_f32_e32 v80, 0, v80
	v_max_f32_e32 v81, 0, v81
	v_lshl_add_u64 v[76:77], v[76:77], 0, v[126:127]
	v_mul_f32_e32 v72, v72, v72
	v_mul_f32_e32 v73, v73, v73
	v_max_f32_e32 v74, 0, v74
	v_max_f32_e32 v75, 0, v75
	v_mul_f32_e32 v68, v68, v68
	v_mul_f32_e32 v69, v69, v69
	v_max_f32_e32 v70, 0, v70
	v_max_f32_e32 v71, 0, v71
	v_mul_f32_e32 v64, v64, v64
	v_max_f32_e32 v65, 0, v65
	v_max_f32_e32 v66, v66, v66
	v_max_f32_e32 v67, v67, v67
	v_max_f32_e32 v60, v60, v60
	v_mul_f32_e32 v80, v80, v80
	v_mul_f32_e32 v81, v81, v81
	v_cvt_pk_bf16_f32 v238, v78, v79
	v_cvt_pk_bf16_f32 v239, v80, v81
	v_mul_f32_e32 v74, v74, v74
	v_mul_f32_e32 v75, v75, v75
	v_cvt_pk_bf16_f32 v240, v72, v73
	v_cvt_pk_bf16_f32 v241, v74, v75
	s_nop 1
	v_permlane16_swap_b32_e32 v238, v240
	v_permlane16_swap_b32_e32 v239, v241
	global_store_dwordx4 v[76:77], v[238:241], off
	v_mul_f32_e32 v70, v70, v70
	v_mul_f32_e32 v71, v71, v71
	v_cvt_pk_bf16_f32 v242, v68, v69
	v_cvt_pk_bf16_f32 v243, v70, v71
	v_mul_f32_e32 v65, v65, v65
	v_max_f32_e32 v66, 0, v66
	v_max_f32_e32 v67, 0, v67
	v_cvt_pk_bf16_f32 v244, v64, v65
	v_max_f32_e32 v60, 0, v60
	v_mul_f32_e32 v66, v66, v66
	v_mul_f32_e32 v67, v67, v67
	v_cvt_pk_bf16_f32 v245, v66, v67
	s_nop 1
	v_permlane16_swap_b32_e32 v242, v244
	v_permlane16_swap_b32_e32 v243, v245
	global_store_dwordx4 v[76:77], v[242:245], off offset:256
	v_mul_f32_e32 v64, v60, v60
	v_max_f32_e32 v60, v61, v61
	v_max_f32_e32 v60, 0, v60
	v_mul_f32_e32 v65, v60, v60
	v_max_f32_e32 v60, v62, v62
	v_max_f32_e32 v60, 0, v60
	v_mul_f32_e32 v66, v60, v60
	v_max_f32_e32 v60, v63, v63
	s_mov_b32 s11, 0x100000
	v_max_f32_e32 v56, v56, v56
	v_max_f32_e32 v57, v57, v57
	v_max_f32_e32 v52, v52, v52
	v_max_f32_e32 v53, v53, v53
	v_max_f32_e32 v44, v44, v44
	v_max_f32_e32 v60, 0, v60
	s_mov_b64 s[26:27], 0x100000
	v_cvt_pk_bf16_f32 v246, v64, v65
	v_add_co_u32_e32 v64, vcc, s11, v124
	v_max_f32_e32 v56, 0, v56
	v_max_f32_e32 v57, 0, v57
	v_max_f32_e32 v58, v58, v58
	v_max_f32_e32 v59, v59, v59
	v_max_f32_e32 v52, 0, v52
	v_max_f32_e32 v53, 0, v53
	v_max_f32_e32 v54, v54, v54
	v_max_f32_e32 v55, v55, v55
	v_max_f32_e32 v44, 0, v44
	v_max_f32_e32 v45, v45, v45
	v_mul_f32_e32 v63, v60, v60
	v_lshl_add_u64 v[60:61], v[124:125], 0, s[26:27]
	v_addc_co_u32_e32 v65, vcc, 0, v125, vcc
	v_mul_f32_e32 v56, v56, v56
	v_mul_f32_e32 v57, v57, v57
	v_max_f32_e32 v58, 0, v58
	v_max_f32_e32 v59, 0, v59
	v_mul_f32_e32 v52, v52, v52
	v_mul_f32_e32 v53, v53, v53
	v_max_f32_e32 v54, 0, v54
	v_max_f32_e32 v55, 0, v55
	v_mul_f32_e32 v44, v44, v44
	v_max_f32_e32 v45, 0, v45
	v_max_f32_e32 v46, v46, v46
	v_max_f32_e32 v47, v47, v47
	v_cvt_pk_bf16_f32 v247, v66, v63
	v_mul_f32_e32 v58, v58, v58
	v_mul_f32_e32 v59, v59, v59
	v_cvt_pk_bf16_f32 v248, v56, v57
	v_cvt_pk_bf16_f32 v249, v58, v59
	s_nop 1
	v_permlane16_swap_b32_e32 v246, v248
	v_permlane16_swap_b32_e32 v247, v249
	global_store_dwordx4 v[60:61], v[246:249], off
	v_mul_f32_e32 v54, v54, v54
	v_mul_f32_e32 v55, v55, v55
	v_cvt_pk_bf16_f32 v238, v52, v53
	v_cvt_pk_bf16_f32 v239, v54, v55
	v_mul_f32_e32 v45, v45, v45
	v_max_f32_e32 v46, 0, v46
	v_max_f32_e32 v47, 0, v47
	v_cvt_pk_bf16_f32 v240, v44, v45
	v_mul_f32_e32 v46, v46, v46
	v_mul_f32_e32 v47, v47, v47
	v_cvt_pk_bf16_f32 v241, v46, v47
	s_nop 1
	v_permlane16_swap_b32_e32 v238, v240
	v_permlane16_swap_b32_e32 v239, v241
	global_store_dwordx4 v[60:61], v[238:241], off offset:256
	v_max_f32_e32 v44, v48, v48
	v_max_f32_e32 v44, 0, v44
	v_mul_f32_e32 v46, v44, v44
	v_max_f32_e32 v44, v49, v49
	v_max_f32_e32 v44, 0, v44
	v_mul_f32_e32 v47, v44, v44
	v_max_f32_e32 v44, v50, v50
	v_max_f32_e32 v44, 0, v44
	v_mul_f32_e32 v48, v44, v44
	v_max_f32_e32 v44, v51, v51
	v_max_f32_e32 v44, 0, v44
	s_mov_b32 s11, 0x120000
	v_max_f32_e32 v40, v40, v40
	v_max_f32_e32 v41, v41, v41
	v_max_f32_e32 v36, v36, v36
	v_max_f32_e32 v37, v37, v37
	v_max_f32_e32 v28, v28, v28
	v_mul_f32_e32 v49, v44, v44
	s_mov_b64 s[26:27], 0x120000
	v_cvt_pk_bf16_f32 v242, v46, v47
	v_cvt_pk_bf16_f32 v243, v48, v49
	v_add_co_u32_e32 v48, vcc, s11, v124
	v_max_f32_e32 v40, 0, v40
	v_max_f32_e32 v41, 0, v41
	v_max_f32_e32 v42, v42, v42
	v_max_f32_e32 v43, v43, v43
	v_max_f32_e32 v36, 0, v36
	v_max_f32_e32 v37, 0, v37
	v_max_f32_e32 v38, v38, v38
	v_max_f32_e32 v39, v39, v39
	v_max_f32_e32 v28, 0, v28
	v_max_f32_e32 v29, v29, v29
	v_lshl_add_u64 v[44:45], v[124:125], 0, s[26:27]
	v_addc_co_u32_e32 v49, vcc, 0, v125, vcc
	v_mul_f32_e32 v40, v40, v40
	v_mul_f32_e32 v41, v41, v41
	v_max_f32_e32 v42, 0, v42
	v_max_f32_e32 v43, 0, v43
	v_mul_f32_e32 v36, v36, v36
	v_mul_f32_e32 v37, v37, v37
	v_max_f32_e32 v38, 0, v38
	v_max_f32_e32 v39, 0, v39
	v_mul_f32_e32 v28, v28, v28
	v_max_f32_e32 v29, 0, v29
	v_max_f32_e32 v30, v30, v30
	v_max_f32_e32 v31, v31, v31
	v_mul_f32_e32 v42, v42, v42
	v_mul_f32_e32 v43, v43, v43
	v_cvt_pk_bf16_f32 v244, v40, v41
	v_cvt_pk_bf16_f32 v245, v42, v43
	s_nop 1
	v_permlane16_swap_b32_e32 v242, v244
	v_permlane16_swap_b32_e32 v243, v245
	global_store_dwordx4 v[44:45], v[242:245], off
	v_mul_f32_e32 v38, v38, v38
	v_mul_f32_e32 v39, v39, v39
	v_cvt_pk_bf16_f32 v246, v36, v37
	v_cvt_pk_bf16_f32 v247, v38, v39
	v_mul_f32_e32 v29, v29, v29
	v_max_f32_e32 v30, 0, v30
	v_max_f32_e32 v31, 0, v31
	v_cvt_pk_bf16_f32 v248, v28, v29
	v_mul_f32_e32 v30, v30, v30
	v_mul_f32_e32 v31, v31, v31
	v_cvt_pk_bf16_f32 v249, v30, v31
	s_nop 1
	v_permlane16_swap_b32_e32 v246, v248
	v_permlane16_swap_b32_e32 v247, v249
	global_store_dwordx4 v[44:45], v[246:249], off offset:256
	v_max_f32_e32 v28, v32, v32
	v_max_f32_e32 v28, 0, v28
	v_mul_f32_e32 v30, v28, v28
	v_max_f32_e32 v28, v33, v33
	v_max_f32_e32 v28, 0, v28
	v_mul_f32_e32 v31, v28, v28
	v_max_f32_e32 v28, v34, v34
	v_max_f32_e32 v28, 0, v28
	v_mul_f32_e32 v32, v28, v28
	v_max_f32_e32 v28, v35, v35
	v_max_f32_e32 v28, 0, v28
	s_mov_b32 s11, 0x140000
	v_max_f32_e32 v24, v24, v24
	v_max_f32_e32 v25, v25, v25
	v_max_f32_e32 v20, v20, v20
	v_max_f32_e32 v21, v21, v21
	v_max_f32_e32 v12, v12, v12
	v_mul_f32_e32 v33, v28, v28
	s_mov_b64 s[26:27], 0x140000
	v_cvt_pk_bf16_f32 v238, v30, v31
	v_cvt_pk_bf16_f32 v239, v32, v33
	v_add_co_u32_e32 v32, vcc, s11, v124
	v_max_f32_e32 v24, 0, v24
	v_max_f32_e32 v25, 0, v25
	v_max_f32_e32 v26, v26, v26
	v_max_f32_e32 v27, v27, v27
	v_max_f32_e32 v20, 0, v20
	v_max_f32_e32 v21, 0, v21
	v_max_f32_e32 v22, v22, v22
	v_max_f32_e32 v23, v23, v23
	v_max_f32_e32 v12, 0, v12
	v_max_f32_e32 v13, v13, v13
	v_lshl_add_u64 v[28:29], v[124:125], 0, s[26:27]
	v_addc_co_u32_e32 v33, vcc, 0, v125, vcc
	v_mul_f32_e32 v24, v24, v24
	v_mul_f32_e32 v25, v25, v25
	v_max_f32_e32 v26, 0, v26
	v_max_f32_e32 v27, 0, v27
	v_mul_f32_e32 v20, v20, v20
	v_mul_f32_e32 v21, v21, v21
	v_max_f32_e32 v22, 0, v22
	v_max_f32_e32 v23, 0, v23
	v_mul_f32_e32 v12, v12, v12
	v_max_f32_e32 v13, 0, v13
	v_max_f32_e32 v14, v14, v14
	v_max_f32_e32 v15, v15, v15
	v_mul_f32_e32 v26, v26, v26
	v_mul_f32_e32 v27, v27, v27
	v_cvt_pk_bf16_f32 v240, v24, v25
	v_cvt_pk_bf16_f32 v241, v26, v27
	s_nop 1
	v_permlane16_swap_b32_e32 v238, v240
	v_permlane16_swap_b32_e32 v239, v241
	global_store_dwordx4 v[28:29], v[238:241], off
	v_mul_f32_e32 v22, v22, v22
	v_mul_f32_e32 v23, v23, v23
	v_cvt_pk_bf16_f32 v242, v20, v21
	v_cvt_pk_bf16_f32 v243, v22, v23
	v_mul_f32_e32 v13, v13, v13
	v_max_f32_e32 v14, 0, v14
	v_max_f32_e32 v15, 0, v15
	v_cvt_pk_bf16_f32 v244, v12, v13
	v_mul_f32_e32 v14, v14, v14
	v_mul_f32_e32 v15, v15, v15
	v_cvt_pk_bf16_f32 v245, v14, v15
	s_nop 1
	v_permlane16_swap_b32_e32 v242, v244
	v_permlane16_swap_b32_e32 v243, v245
	global_store_dwordx4 v[28:29], v[242:245], off offset:256
	v_max_f32_e32 v12, v16, v16
	v_max_f32_e32 v12, 0, v12
	v_mul_f32_e32 v14, v12, v12
	v_max_f32_e32 v12, v17, v17
	v_max_f32_e32 v12, 0, v12
	v_mul_f32_e32 v15, v12, v12
	v_max_f32_e32 v12, v18, v18
	v_max_f32_e32 v12, 0, v12
	v_mul_f32_e32 v16, v12, v12
	v_max_f32_e32 v12, v19, v19
	v_max_f32_e32 v12, 0, v12
	s_mov_b32 s11, 0x160000
	v_mul_f32_e32 v17, v12, v12
	v_cvt_pk_bf16_f32 v246, v14, v15
	v_cvt_pk_bf16_f32 v247, v16, v17
	v_add_co_u32_e32 v16, vcc, s11, v124
	v_max_f32_e32 v8, v8, v8
	v_max_f32_e32 v9, v9, v9
	v_max_f32_e32 v4, v4, v4
	v_max_f32_e32 v5, v5, v5
	v_max_f32_e32 v0, v0, v0
	v_max_f32_e32 v1, v1, v1
	s_mov_b64 s[26:27], 0x160000
	v_addc_co_u32_e32 v17, vcc, 0, v125, vcc
	v_max_f32_e32 v8, 0, v8
	v_max_f32_e32 v9, 0, v9
	v_max_f32_e32 v10, v10, v10
	v_max_f32_e32 v11, v11, v11
	v_max_f32_e32 v4, 0, v4
	v_max_f32_e32 v5, 0, v5
	v_max_f32_e32 v6, v6, v6
	v_max_f32_e32 v7, v7, v7
	v_max_f32_e32 v0, 0, v0
	v_max_f32_e32 v1, 0, v1
	v_max_f32_e32 v2, v2, v2
	v_max_f32_e32 v3, v3, v3
	v_lshl_add_u64 v[12:13], v[124:125], 0, s[26:27]
	v_mul_f32_e32 v8, v8, v8
	v_mul_f32_e32 v9, v9, v9
	v_max_f32_e32 v10, 0, v10
	v_max_f32_e32 v11, 0, v11
	v_mul_f32_e32 v4, v4, v4
	v_mul_f32_e32 v5, v5, v5
	v_max_f32_e32 v6, 0, v6
	v_max_f32_e32 v7, 0, v7
	v_mul_f32_e32 v0, v0, v0
	v_mul_f32_e32 v1, v1, v1
	v_max_f32_e32 v2, 0, v2
	v_max_f32_e32 v3, 0, v3
	s_and_b64 vcc, exec, s[8:9]
	s_mov_b32 s20, s10
	s_mov_b32 s22, s14
	s_mov_b64 s[28:29], s[18:19]
	s_mov_b64 s[26:27], s[16:17]
	v_mul_f32_e32 v10, v10, v10
	v_mul_f32_e32 v11, v11, v11
	v_cvt_pk_bf16_f32 v248, v8, v9
	v_cvt_pk_bf16_f32 v249, v10, v11
	s_nop 1
	v_permlane16_swap_b32_e32 v246, v248
	v_permlane16_swap_b32_e32 v247, v249
	global_store_dwordx4 v[12:13], v[246:249], off
	v_mul_f32_e32 v6, v6, v6
	v_mul_f32_e32 v7, v7, v7
	v_cvt_pk_bf16_f32 v238, v4, v5
	v_cvt_pk_bf16_f32 v239, v6, v7
	v_mul_f32_e32 v2, v2, v2
	v_mul_f32_e32 v3, v3, v3
	v_cvt_pk_bf16_f32 v240, v0, v1
	v_cvt_pk_bf16_f32 v241, v2, v3
	s_nop 1
	v_permlane16_swap_b32_e32 v238, v240
	v_permlane16_swap_b32_e32 v239, v241
	global_store_dwordx4 v[12:13], v[238:241], off offset:256
	s_cbranch_vccz .LBB0_2770
	s_waitcnt vmcnt(0)
	s_cmpk_gt_u32 s25, 0xff
	v_readlane_b32 s59, v255, 19
	s_cbranch_scc1 .LBB0_2777
	s_barrier
